# combo13 + slot A STAGE (P1) also issued inside MFMA block A, slot A vmcnt(6)
# baseline (speedup 1.0000x reference)
; #define PG8_STAGE(bufoff, gbase, voff) do { _Pragma("unroll") for (int _i = 0; _i < 2; ++_i) \
;     __builtin_amdgcn_global_load_lds((const unsigned*)((const char*)(gbase) + (voff)[_i]), (LAS unsigned*)(lds + (bufoff) + ldsw + _i * 8192), 16, 0, 0); } while (0)
; #define PG8_LDA(dst, b, h) do { _Pragma("unroll") for (int m = 0; m < 4; ++m) _Pragma("unroll") for (int k = 0; k < 2; ++k) dst[m][k] = *(const LAS bf16x8*)(lds + PG8_SA(b, h) + aoff + m * 2048 + k * 1024); } while (0)
; #define PG8_LDB(dst, b, h) do { _Pragma("unroll") for (int n = 0; n < 2; ++n) _Pragma("unroll") for (int k = 0; k < 2; ++k) dst[n][k] = *(const LAS bf16x8*)(lds + PG8_SB(b, h) + boff + n * 2048 + k * 1024); } while (0)
; #define PG8_MMA(ai, bj, At, Bt) do { __builtin_amdgcn_s_setprio(1); _Pragma("unroll") for (int m = 0; m < 4; ++m) _Pragma("unroll") for (int n = 0; n < 2; ++n) _Pragma("unroll") for (int k = 0; k < 2; ++k) \
;     acc[ai][bj][m][n] = __builtin_amdgcn_mfma_f32_16x16x32_bf16(Bt[n][k], At[m][k], acc[ai][bj][m][n], 0, 0, 0); __builtin_amdgcn_s_setprio(0); } while (0)
; #define PG8_BAR __builtin_amdgcn_s_barrier()
; template <class Epi, class Sched = StaticOrder>
; DI void gemm_phase(LAS unsigned char* lds, const Gemm g, const Sched& S, const Epi& E) {
;     ...
;     const bool has_next = S.next(ui + 1, nxt);
;     const char* nA = has_next ? (const char*)g.A + (size_t)nxt.pm * tstep : cA; const char* nB = has_next ? (const char*)g.Bt + (size_t)nxt.pn * tstep : cB;
;     for (int t = 0; t < nt; t += 2) {
;       const bool last = (t == nt - 2);
;       const char* a1 = cA + (size_t)(t + 1) * kstep;
;       const char* a2 = last ? nA : cA + (size_t)(t + 2) * kstep; const char* b2 = last ? nB : cB + (size_t)(t + 2) * kstep;
;       const char* a3 = a2 + kstep; const char* b3 = b2 + kstep;
;       PG8_LDB(B0, 0, 0); PG8_SCHED; PG8_LDA(At, 0, 0); PG8_STAGE(PG8_SA(1, 1), a1 + hstep, voffA);
;       PG8_WAIT_L(8); PG8_BAR; PG8_WAIT_L(0); PG8_MMA(0, 0, At, B0); PG8_BAR; PG8_SCHED;
;       PG8_LDB(B1, 0, 1); PG8_STAGE(PG8_SB(0, 0), b2, voffB);
;       PG8_BAR; PG8_WAIT_L(0); PG8_MMA(0, 1, At, B1); PG8_BAR;
;       PG8_LDA(At, 0, 1); PG8_STAGE(PG8_SA(0, 0), a2, voffA);
;       PG8_BAR; PG8_WAIT_L(0); PG8_MMA(1, 0, At, B0); PG8_BAR; PG8_SCHED;
;       PG8_STAGE(PG8_SB(0, 1), b2 + hstep, voffB);
;       PG8_WAIT_V(6); PG8_BAR; PG8_MMA(1, 1, At, B1); PG8_BAR;
.LBB0_346:
	ds_read_b128 v[128:131], v173
	ds_read_b128 v[132:135], v173 offset:1024
	ds_read_b128 v[154:157], v173 offset:2048
	ds_read_b128 v[158:161], v173 offset:3072
	s_add_u32 s8, s6, 0xfff80080
	s_addc_u32 s9, s7, -1
	s_cmp_eq_u32 s52, 28
	s_cselect_b32 s11, s31, s9
	s_cselect_b32 s10, s42, s8
	s_cselect_b32 s9, s29, s45
	s_cselect_b32 s8, s43, s44
	ds_read_b128 v[162:165], v174
	ds_read_b128 v[166:169], v174 offset:1024
	ds_read_b128 v[178:181], v174 offset:2048
	ds_read_b128 v[182:185], v174 offset:3072
	ds_read_b128 v[186:189], v174 offset:4096
	ds_read_b128 v[190:193], v174 offset:5120
	ds_read_b128 v[194:197], v174 offset:6144
	ds_read_b128 v[198:201], v174 offset:7168
	ds_read_b128 v[202:205], v175
	ds_read_b128 v[206:209], v175 offset:1024
	ds_read_b128 v[212:215], v175 offset:2048
	ds_read_b128 v[216:219], v175 offset:3072
	s_waitcnt vmcnt(6)
	s_waitcnt lgkmcnt(4)
	s_setprio 1
	s_barrier
	v_mfma_f32_16x16x32_bf16 v[124:127], v[128:131], v[162:165], v[124:127]
	s_add_i32 m0, s48, 0xc000
	v_mfma_f32_16x16x32_bf16 v[120:123], v[154:157], v[162:165], v[120:123]
	global_load_lds_dwordx4 v146, s[6:7]
	v_mfma_f32_16x16x32_bf16 v[108:111], v[128:131], v[178:181], v[108:111]
	s_add_i32 m0, s48, 0xe000
	v_mfma_f32_16x16x32_bf16 v[104:107], v[154:157], v[178:181], v[104:107]
	global_load_lds_dwordx4 v148, s[6:7]
	v_mfma_f32_16x16x32_bf16 v[100:103], v[128:131], v[186:189], v[100:103]
	v_mfma_f32_16x16x32_bf16 v[92:95], v[154:157], v[186:189], v[92:95]
	v_mfma_f32_16x16x32_bf16 v[84:87], v[128:131], v[194:197], v[84:87]
	v_mfma_f32_16x16x32_bf16 v[76:79], v[154:157], v[194:197], v[76:79]
	v_mfma_f32_16x16x32_bf16 v[124:127], v[132:135], v[166:169], v[124:127]
	v_mfma_f32_16x16x32_bf16 v[120:123], v[158:161], v[166:169], v[120:123]
	v_mfma_f32_16x16x32_bf16 v[108:111], v[132:135], v[182:185], v[108:111]
	v_mfma_f32_16x16x32_bf16 v[104:107], v[158:161], v[182:185], v[104:107]
	v_mfma_f32_16x16x32_bf16 v[100:103], v[132:135], v[190:193], v[100:103]
	v_mfma_f32_16x16x32_bf16 v[92:95], v[158:161], v[190:193], v[92:95]
	v_mfma_f32_16x16x32_bf16 v[84:87], v[132:135], v[198:201], v[84:87]
	v_mfma_f32_16x16x32_bf16 v[76:79], v[158:161], v[198:201], v[76:79]
	s_waitcnt lgkmcnt(0)
	v_mfma_f32_16x16x32_bf16 v[116:119], v[202:205], v[162:165], v[116:119]
	v_mfma_f32_16x16x32_bf16 v[112:115], v[212:215], v[162:165], v[112:115]
	v_mfma_f32_16x16x32_bf16 v[96:99], v[202:205], v[178:181], v[96:99]
	v_mfma_f32_16x16x32_bf16 v[88:91], v[212:215], v[178:181], v[88:91]
	v_mfma_f32_16x16x32_bf16 v[80:83], v[202:205], v[186:189], v[80:83]
	v_mfma_f32_16x16x32_bf16 v[72:75], v[212:215], v[186:189], v[72:75]
	v_mfma_f32_16x16x32_bf16 v[68:71], v[202:205], v[194:197], v[68:71]
	v_mfma_f32_16x16x32_bf16 v[64:67], v[212:215], v[194:197], v[64:67]
	v_mfma_f32_16x16x32_bf16 v[116:119], v[206:209], v[166:169], v[116:119]
	v_mfma_f32_16x16x32_bf16 v[112:115], v[216:219], v[166:169], v[112:115]
	v_mfma_f32_16x16x32_bf16 v[96:99], v[206:209], v[182:185], v[96:99]
	v_mfma_f32_16x16x32_bf16 v[88:91], v[216:219], v[182:185], v[88:91]
	v_mfma_f32_16x16x32_bf16 v[80:83], v[206:209], v[190:193], v[80:83]
	v_mfma_f32_16x16x32_bf16 v[72:75], v[216:219], v[190:193], v[72:75]
	v_mfma_f32_16x16x32_bf16 v[68:71], v[206:209], v[198:201], v[68:71]
	v_mfma_f32_16x16x32_bf16 v[64:67], v[216:219], v[198:201], v[64:67]
	s_barrier
	s_setprio 0
	s_add_i32 s53, s65, s41
	s_add_u32 s98, s8, 0x80
	s_addc_u32 s99, s9, 0
	s_add_u32 s100, s10, 0x80
	s_addc_u32 s101, s11, 0
	s_mov_b32 m0, s53
	s_nop 0
	global_load_lds_dwordx4 v140, s[8:9]
	s_add_i32 m0, s53, 0x2000
	s_nop 0
	global_load_lds_dwordx4 v136, s[8:9]
	s_mov_b32 m0, s48
	ds_read_b128 v[162:165], v174 offset:16384
	ds_read_b128 v[166:169], v174 offset:17408
	ds_read_b128 v[178:181], v174 offset:18432
	ds_read_b128 v[182:185], v174 offset:19456
	ds_read_b128 v[186:189], v174 offset:20480
	ds_read_b128 v[190:193], v174 offset:21504
	ds_read_b128 v[194:197], v174 offset:22528
	ds_read_b128 v[198:201], v174 offset:23552
	global_load_lds_dwordx4 v142, s[10:11]
	s_mov_b32 m0, s49
	s_nop 0
	global_load_lds_dwordx4 v138, s[10:11]
	s_add_u32 s54, s8, 0x80000
	s_addc_u32 s55, s9, 0
	s_add_i32 s53, s72, s41
	s_waitcnt vmcnt(6)
	s_waitcnt lgkmcnt(0)
	s_setprio 1
	s_barrier
	v_mfma_f32_16x16x32_bf16 v[60:63], v[128:131], v[162:165], v[60:63]
	s_mov_b32 m0, s53
	v_mfma_f32_16x16x32_bf16 v[56:59], v[154:157], v[162:165], v[56:59]
	global_load_lds_dwordx4 v140, s[54:55]
	v_mfma_f32_16x16x32_bf16 v[52:55], v[128:131], v[178:181], v[52:55]
	s_bitset1_b32 m0, 13
	v_mfma_f32_16x16x32_bf16 v[44:47], v[154:157], v[178:181], v[44:47]
	global_load_lds_dwordx4 v136, s[54:55]
	v_mfma_f32_16x16x32_bf16 v[36:39], v[128:131], v[186:189], v[36:39]
	v_mfma_f32_16x16x32_bf16 v[28:31], v[154:157], v[186:189], v[28:31]
	v_mfma_f32_16x16x32_bf16 v[20:23], v[128:131], v[194:197], v[20:23]
	v_mfma_f32_16x16x32_bf16 v[12:15], v[154:157], v[194:197], v[12:15]
	v_mfma_f32_16x16x32_bf16 v[60:63], v[132:135], v[166:169], v[60:63]
	v_mfma_f32_16x16x32_bf16 v[56:59], v[158:161], v[166:169], v[56:59]
	v_mfma_f32_16x16x32_bf16 v[52:55], v[132:135], v[182:185], v[52:55]
	v_mfma_f32_16x16x32_bf16 v[44:47], v[158:161], v[182:185], v[44:47]
	v_mfma_f32_16x16x32_bf16 v[36:39], v[132:135], v[190:193], v[36:39]
	v_mfma_f32_16x16x32_bf16 v[28:31], v[158:161], v[190:193], v[28:31]
	v_mfma_f32_16x16x32_bf16 v[20:23], v[132:135], v[198:201], v[20:23]
	v_mfma_f32_16x16x32_bf16 v[12:15], v[158:161], v[198:201], v[12:15]
	v_mfma_f32_16x16x32_bf16 v[48:51], v[202:205], v[162:165], v[48:51]
	v_mfma_f32_16x16x32_bf16 v[40:43], v[212:215], v[162:165], v[40:43]
	v_mfma_f32_16x16x32_bf16 v[32:35], v[202:205], v[178:181], v[32:35]
	v_mfma_f32_16x16x32_bf16 v[24:27], v[212:215], v[178:181], v[24:27]
	v_mfma_f32_16x16x32_bf16 v[16:19], v[202:205], v[186:189], v[16:19]
	v_mfma_f32_16x16x32_bf16 v[8:11], v[212:215], v[186:189], v[8:11]
	v_mfma_f32_16x16x32_bf16 v[4:7], v[202:205], v[194:197], v[4:7]
	v_mfma_f32_16x16x32_bf16 v[0:3], v[212:215], v[194:197], v[0:3]
	v_mfma_f32_16x16x32_bf16 v[48:51], v[206:209], v[166:169], v[48:51]
	v_mfma_f32_16x16x32_bf16 v[40:43], v[216:219], v[166:169], v[40:43]
	v_mfma_f32_16x16x32_bf16 v[32:35], v[206:209], v[182:185], v[32:35]
	v_mfma_f32_16x16x32_bf16 v[24:27], v[216:219], v[182:185], v[24:27]
	v_mfma_f32_16x16x32_bf16 v[16:19], v[206:209], v[190:193], v[16:19]
	v_mfma_f32_16x16x32_bf16 v[8:11], v[216:219], v[190:193], v[8:11]
	v_mfma_f32_16x16x32_bf16 v[4:7], v[206:209], v[198:201], v[4:7]
	v_mfma_f32_16x16x32_bf16 v[0:3], v[216:219], v[198:201], v[0:3]
	s_barrier
; #define PG8_STAGE(bufoff, gbase, voff) do { _Pragma("unroll") for (int _i = 0; _i < 2; ++_i) \
;     __builtin_amdgcn_global_load_lds((const unsigned*)((const char*)(gbase) + (voff)[_i]), (LAS unsigned*)(lds + (bufoff) + ldsw + _i * 8192), 16, 0, 0); } while (0)
; #define PG8_LDA(dst, b, h) do { _Pragma("unroll") for (int m = 0; m < 4; ++m) _Pragma("unroll") for (int k = 0; k < 2; ++k) dst[m][k] = *(const LAS bf16x8*)(lds + PG8_SA(b, h) + aoff + m * 2048 + k * 1024); } while (0)
; #define PG8_LDB(dst, b, h) do { _Pragma("unroll") for (int n = 0; n < 2; ++n) _Pragma("unroll") for (int k = 0; k < 2; ++k) dst[n][k] = *(const LAS bf16x8*)(lds + PG8_SB(b, h) + boff + n * 2048 + k * 1024); } while (0)
; #define PG8_MMA(ai, bj, At, Bt) do { __builtin_amdgcn_s_setprio(1); _Pragma("unroll") for (int m = 0; m < 4; ++m) _Pragma("unroll") for (int n = 0; n < 2; ++n) _Pragma("unroll") for (int k = 0; k < 2; ++k) \
;     acc[ai][bj][m][n] = __builtin_amdgcn_mfma_f32_16x16x32_bf16(Bt[n][k], At[m][k], acc[ai][bj][m][n], 0, 0, 0); __builtin_amdgcn_s_setprio(0); } while (0)
; #define PG8_WAIT_V(n) asm volatile("s_waitcnt vmcnt(" #n ")" ::: "memory")
; #define PG8_WAIT_L(n) asm volatile("s_waitcnt lgkmcnt(" #n ")" ::: "memory")
; #define PG8_BAR __builtin_amdgcn_s_barrier()
; #define PG8_SCHED __builtin_amdgcn_sched_barrier(0)
; template <class Epi, class Sched = StaticOrder>
; DI void gemm_phase(LAS unsigned char* lds, const Gemm g, const Sched& S, const Epi& E) {
;     ...
;       PG8_LDB(B0, 1, 0); PG8_SCHED; PG8_LDA(At, 1, 0); PG8_STAGE(PG8_SA(0, 1), a2 + hstep, voffA);
;       PG8_WAIT_L(8); PG8_BAR; PG8_WAIT_L(0); PG8_MMA(0, 0, At, B0); PG8_BAR; PG8_SCHED;
;       PG8_LDB(B1, 1, 1); PG8_STAGE(PG8_SB(1, 0), b3, voffB);
;       PG8_BAR; PG8_WAIT_L(0); PG8_MMA(0, 1, At, B1); PG8_BAR;
;       PG8_LDA(At, 1, 1); PG8_STAGE(PG8_SA(1, 0), a3, voffA);
;       PG8_BAR; PG8_WAIT_L(0); PG8_MMA(1, 0, At, B0); PG8_BAR; PG8_SCHED;
;       PG8_STAGE(PG8_SB(1, 1), b3 + hstep, voffB);
;       PG8_WAIT_V(6); PG8_BAR; PG8_MMA(1, 1, At, B1); PG8_BAR;
	s_setprio 0
	s_add_i32 s53, 0, 0x18000
	v_add_u32_e32 v158, s53, v171
	ds_read_b128 v[128:131], v158
	ds_read_b128 v[132:135], v158 offset:1024
	ds_read_b128 v[154:157], v158 offset:2048
	ds_read_b128 v[158:161], v158 offset:3072
	s_add_u32 s10, s10, 0x80000
	s_addc_u32 s11, s11, 0
	s_mov_b32 m0, s50
	ds_read_b128 v[162:165], v174 offset:32768
	ds_read_b128 v[166:169], v174 offset:33792
	ds_read_b128 v[178:181], v174 offset:34816
	ds_read_b128 v[182:185], v174 offset:35840
	ds_read_b128 v[186:189], v174 offset:36864
	ds_read_b128 v[190:193], v174 offset:37888
	ds_read_b128 v[194:197], v174 offset:38912
	ds_read_b128 v[198:201], v174 offset:39936
	global_load_lds_dwordx4 v142, s[10:11]
	s_mov_b32 m0, s51
	s_nop 0
	global_load_lds_dwordx4 v138, s[10:11]
	s_add_i32 s10, 0, 0x1c000
	v_add_u32_e32 v177, s10, v171
	ds_read_b128 v[202:205], v177
	ds_read_b128 v[206:209], v177 offset:1024
	ds_read_b128 v[212:215], v177 offset:2048
	ds_read_b128 v[216:219], v177 offset:3072
	s_waitcnt vmcnt(8)
	s_waitcnt lgkmcnt(4)
	s_setprio 1
	s_barrier
	v_mfma_f32_16x16x32_bf16 v[124:127], v[128:131], v[162:165], v[124:127]
	v_mfma_f32_16x16x32_bf16 v[120:123], v[154:157], v[162:165], v[120:123]
	v_mfma_f32_16x16x32_bf16 v[108:111], v[128:131], v[178:181], v[108:111]
	v_mfma_f32_16x16x32_bf16 v[104:107], v[154:157], v[178:181], v[104:107]
	v_mfma_f32_16x16x32_bf16 v[100:103], v[128:131], v[186:189], v[100:103]
	v_mfma_f32_16x16x32_bf16 v[92:95], v[154:157], v[186:189], v[92:95]
	v_mfma_f32_16x16x32_bf16 v[84:87], v[128:131], v[194:197], v[84:87]
	v_mfma_f32_16x16x32_bf16 v[76:79], v[154:157], v[194:197], v[76:79]
	v_mfma_f32_16x16x32_bf16 v[124:127], v[132:135], v[166:169], v[124:127]
	v_mfma_f32_16x16x32_bf16 v[120:123], v[158:161], v[166:169], v[120:123]
	v_mfma_f32_16x16x32_bf16 v[108:111], v[132:135], v[182:185], v[108:111]
	v_mfma_f32_16x16x32_bf16 v[104:107], v[158:161], v[182:185], v[104:107]
	v_mfma_f32_16x16x32_bf16 v[100:103], v[132:135], v[190:193], v[100:103]
	v_mfma_f32_16x16x32_bf16 v[92:95], v[158:161], v[190:193], v[92:95]
	v_mfma_f32_16x16x32_bf16 v[84:87], v[132:135], v[198:201], v[84:87]
	v_mfma_f32_16x16x32_bf16 v[76:79], v[158:161], v[198:201], v[76:79]
	s_waitcnt lgkmcnt(0)
	v_mfma_f32_16x16x32_bf16 v[116:119], v[202:205], v[162:165], v[116:119]
	v_mfma_f32_16x16x32_bf16 v[112:115], v[212:215], v[162:165], v[112:115]
	v_mfma_f32_16x16x32_bf16 v[96:99], v[202:205], v[178:181], v[96:99]
	v_mfma_f32_16x16x32_bf16 v[88:91], v[212:215], v[178:181], v[88:91]
	v_mfma_f32_16x16x32_bf16 v[80:83], v[202:205], v[186:189], v[80:83]
	v_mfma_f32_16x16x32_bf16 v[72:75], v[212:215], v[186:189], v[72:75]
	v_mfma_f32_16x16x32_bf16 v[68:71], v[202:205], v[194:197], v[68:71]
	v_mfma_f32_16x16x32_bf16 v[64:67], v[212:215], v[194:197], v[64:67]
	v_mfma_f32_16x16x32_bf16 v[116:119], v[206:209], v[166:169], v[116:119]
	v_mfma_f32_16x16x32_bf16 v[112:115], v[216:219], v[166:169], v[112:115]
	v_mfma_f32_16x16x32_bf16 v[96:99], v[206:209], v[182:185], v[96:99]
	v_mfma_f32_16x16x32_bf16 v[88:91], v[216:219], v[182:185], v[88:91]
	v_mfma_f32_16x16x32_bf16 v[80:83], v[206:209], v[190:193], v[80:83]
	v_mfma_f32_16x16x32_bf16 v[72:75], v[216:219], v[190:193], v[72:75]
	v_mfma_f32_16x16x32_bf16 v[68:71], v[206:209], v[198:201], v[68:71]
	v_mfma_f32_16x16x32_bf16 v[64:67], v[216:219], v[198:201], v[64:67]
	s_barrier
	s_setprio 0
	s_add_i32 s11, s53, s41
	s_mov_b32 m0, s11
	s_nop 0
	global_load_lds_dwordx4 v140, s[98:99]
	s_add_i32 m0, s11, 0x2000
	s_nop 0
	global_load_lds_dwordx4 v136, s[98:99]
	s_mov_b32 m0, s56
	ds_read_b128 v[162:165], v174 offset:49152
	ds_read_b128 v[166:169], v174 offset:50176
	ds_read_b128 v[178:181], v174 offset:51200
	ds_read_b128 v[182:185], v174 offset:52224
	ds_read_b128 v[186:189], v174 offset:53248
	ds_read_b128 v[190:193], v174 offset:54272
	ds_read_b128 v[194:197], v174 offset:55296
	ds_read_b128 v[198:201], v174 offset:56320
	global_load_lds_dwordx4 v142, s[100:101]
	s_mov_b32 m0, s57
	s_nop 0
	global_load_lds_dwordx4 v138, s[100:101]
	s_add_u32 s8, s8, 0x80080
	s_addc_u32 s9, s9, 0
	s_add_i32 s10, s10, s41
	s_add_i32 s52, s52, 2
	s_add_u32 s6, s6, 0x100
	s_addc_u32 s7, s7, 0
	s_add_u32 s44, s44, 0x100
	s_addc_u32 s45, s45, 0
	s_cmp_gt_u32 s52, 29
	s_waitcnt vmcnt(6)
	s_waitcnt lgkmcnt(0)
	s_setprio 1
	s_barrier
	v_mfma_f32_16x16x32_bf16 v[60:63], v[128:131], v[162:165], v[60:63]
	s_mov_b32 m0, s10
	v_mfma_f32_16x16x32_bf16 v[56:59], v[154:157], v[162:165], v[56:59]
	global_load_lds_dwordx4 v140, s[8:9]
	v_mfma_f32_16x16x32_bf16 v[52:55], v[128:131], v[178:181], v[52:55]
	s_bitset1_b32 m0, 13
	v_mfma_f32_16x16x32_bf16 v[44:47], v[154:157], v[178:181], v[44:47]
	global_load_lds_dwordx4 v136, s[8:9]
	v_mfma_f32_16x16x32_bf16 v[36:39], v[128:131], v[186:189], v[36:39]
	v_mfma_f32_16x16x32_bf16 v[28:31], v[154:157], v[186:189], v[28:31]
	v_mfma_f32_16x16x32_bf16 v[20:23], v[128:131], v[194:197], v[20:23]
	v_mfma_f32_16x16x32_bf16 v[12:15], v[154:157], v[194:197], v[12:15]
	v_mfma_f32_16x16x32_bf16 v[60:63], v[132:135], v[166:169], v[60:63]
	v_mfma_f32_16x16x32_bf16 v[56:59], v[158:161], v[166:169], v[56:59]
	v_mfma_f32_16x16x32_bf16 v[52:55], v[132:135], v[182:185], v[52:55]
	v_mfma_f32_16x16x32_bf16 v[44:47], v[158:161], v[182:185], v[44:47]
	v_mfma_f32_16x16x32_bf16 v[36:39], v[132:135], v[190:193], v[36:39]
	v_mfma_f32_16x16x32_bf16 v[28:31], v[158:161], v[190:193], v[28:31]
	v_mfma_f32_16x16x32_bf16 v[20:23], v[132:135], v[198:201], v[20:23]
	v_mfma_f32_16x16x32_bf16 v[12:15], v[158:161], v[198:201], v[12:15]
	v_mfma_f32_16x16x32_bf16 v[48:51], v[202:205], v[162:165], v[48:51]
	v_mfma_f32_16x16x32_bf16 v[40:43], v[212:215], v[162:165], v[40:43]
	v_mfma_f32_16x16x32_bf16 v[32:35], v[202:205], v[178:181], v[32:35]
	v_mfma_f32_16x16x32_bf16 v[24:27], v[212:215], v[178:181], v[24:27]
	v_mfma_f32_16x16x32_bf16 v[16:19], v[202:205], v[186:189], v[16:19]
	v_mfma_f32_16x16x32_bf16 v[8:11], v[212:215], v[186:189], v[8:11]
	v_mfma_f32_16x16x32_bf16 v[4:7], v[202:205], v[194:197], v[4:7]
	v_mfma_f32_16x16x32_bf16 v[0:3], v[212:215], v[194:197], v[0:3]
	v_mfma_f32_16x16x32_bf16 v[48:51], v[206:209], v[166:169], v[48:51]
	v_mfma_f32_16x16x32_bf16 v[40:43], v[216:219], v[166:169], v[40:43]
	v_mfma_f32_16x16x32_bf16 v[32:35], v[206:209], v[182:185], v[32:35]
	v_mfma_f32_16x16x32_bf16 v[24:27], v[216:219], v[182:185], v[24:27]
	v_mfma_f32_16x16x32_bf16 v[16:19], v[206:209], v[190:193], v[16:19]
	v_mfma_f32_16x16x32_bf16 v[8:11], v[216:219], v[190:193], v[8:11]
	v_mfma_f32_16x16x32_bf16 v[4:7], v[206:209], v[198:201], v[4:7]
	v_mfma_f32_16x16x32_bf16 v[0:3], v[216:219], v[198:201], v[0:3]
	s_barrier
; DI unsigned pack2(float lo, float hi) { f32x2 v = {lo, hi}; bf16v2 r = __builtin_convertvector(v, bf16v2); return __builtin_bit_cast(unsigned, r); }
; DI float row_rstd(const float* ssq, int row, int fq) {
;   const f32x4 a = *(const f32x4*)(ssq + (size_t)row * 32 + fq * 8), b = *(const f32x4*)(ssq + (size_t)row * 32 + fq * 8 + 4);
;   float sm = ((a[0] + a[1]) + (a[2] + a[3])) + ((b[0] + b[1]) + (b[2] + b[3]));
;   sm += __shfl_xor(sm, 16); sm += __shfl_xor(sm, 32);
;   return rsqrtf(sm * (1.0f / 2048.f) + 1e-6f);
;   DI void operator()(const f32x4 (&acc)[2][2][4][2], const Unit& u, int wr, int wc, int fr, int fq) const {
;     const int row0 = u.pm * BM + wr * 64 + fr, col0 = u.pn * BM + wc * 32 + 8 * fq;
;     float rsv[2][4];
; #pragma unroll
;     for (int ai = 0; ai < 2; ++ai)
; #pragma unroll
;       for (int m = 0; m < 4; ++m) rsv[ai][m] = row_rstd(ssq, row0 + ai * HALF + m * 16, fq);
; #pragma unroll
;     for (int ai = 0; ai < 2; ++ai)
; #pragma unroll
;       for (int m = 0; m < 4; ++m) {
;         const int row = row0 + ai * HALF + m * 16;
;         const float rs = rsv[ai][m];
;         bf16_t* rowp = O + (size_t)row * ldc + col0;
; #pragma unroll
;         for (int bj = 0; bj < 2; ++bj) {
;           const f32x4 v0 = acc[ai][bj][m][0] * rs, v1 = acc[ai][bj][m][1] * rs;
;           u32x4 w; w.x = pack2(v0[0], v0[1]); w.y = pack2(v0[2], v0[3]); w.z = pack2(v1[0], v1[1]); w.w = pack2(v1[2], v1[3]);
;           *(u32x4*)(rowp + bj * HALF) = w;
	s_setprio 0
	s_cbranch_scc0 .LBB0_346
	v_lshl_add_u32 v168, s4, 8, v170
	v_ashrrev_i32_e32 v169, 31, v168
	v_or_b32_e32 v154, 16, v168
	v_lshlrev_b64 v[128:129], 7, v[168:169]
	v_ashrrev_i32_e32 v155, 31, v154
	v_lshl_add_u64 v[128:129], v[144:145], 0, v[128:129]
	v_lshlrev_b64 v[156:157], 7, v[154:155]
	global_load_dwordx4 v[132:135], v[128:129], off
	s_nop 0
	global_load_dwordx4 v[128:131], v[128:129], off offset:16
	v_lshl_add_u64 v[156:157], v[144:145], 0, v[156:157]
	global_load_dwordx4 v[178:181], v[156:157], off
	global_load_dwordx4 v[182:185], v[156:157], off offset:16
	v_or_b32_e32 v160, 32, v168
	v_ashrrev_i32_e32 v161, 31, v160
	v_lshlrev_b64 v[156:157], 7, v[160:161]
	v_lshl_add_u64 v[156:157], v[144:145], 0, v[156:157]
	global_load_dwordx4 v[186:189], v[156:157], off
	global_load_dwordx4 v[190:193], v[156:157], off offset:16
	v_or_b32_e32 v156, 48, v168
	v_ashrrev_i32_e32 v157, 31, v156
	v_lshlrev_b64 v[158:159], 7, v[156:157]
	v_lshl_add_u64 v[158:159], v[144:145], 0, v[158:159]
	global_load_dwordx4 v[194:197], v[158:159], off
	global_load_dwordx4 v[198:201], v[158:159], off offset:16
	v_add_u32_e32 v164, 0x80, v168
	v_ashrrev_i32_e32 v165, 31, v164
	v_lshlrev_b64 v[158:159], 7, v[164:165]
	v_lshl_add_u64 v[158:159], v[144:145], 0, v[158:159]
	global_load_dwordx4 v[202:205], v[158:159], off
	global_load_dwordx4 v[206:209], v[158:159], off offset:16
	v_add_u32_e32 v158, 0x90, v168
	v_ashrrev_i32_e32 v159, 31, v158
	v_lshlrev_b64 v[162:163], 7, v[158:159]
	v_lshl_add_u64 v[162:163], v[144:145], 0, v[162:163]
	global_load_dwordx4 v[212:215], v[162:163], off
	global_load_dwordx4 v[216:219], v[162:163], off offset:16
	v_add_u32_e32 v166, 0xa0, v168
	v_ashrrev_i32_e32 v167, 31, v166
	v_lshlrev_b64 v[162:163], 7, v[166:167]
	v_lshl_add_u64 v[162:163], v[144:145], 0, v[162:163]
	global_load_dwordx4 v[220:223], v[162:163], off
	global_load_dwordx4 v[224:227], v[162:163], off offset:16
	v_add_u32_e32 v162, 0xb0, v168
	v_ashrrev_i32_e32 v163, 31, v162
	v_lshlrev_b64 v[228:229], 7, v[162:163]
	v_lshl_add_u64 v[232:233], v[144:145], 0, v[228:229]
	global_load_dwordx4 v[228:231], v[232:233], off
	s_nop 0
	global_load_dwordx4 v[232:235], v[232:233], off offset:16
	s_waitcnt vmcnt(0)
	v_mov_b32_e32 v236, v132
	v_mov_b32_e32 v237, v128
	v_mov_b32_e32 v128, v133
	v_mov_b32_e32 v132, v134
	v_mov_b32_e32 v133, v130
	v_mov_b32_e32 v130, v135
	v_pk_add_f32 v[130:131], v[132:133], v[130:131]
	v_mov_b32_e32 v132, v178
	v_mov_b32_e32 v133, v182
	v_mov_b32_e32 v182, v179
	v_mov_b32_e32 v134, v180
	v_mov_b32_e32 v135, v184
	v_mov_b32_e32 v184, v181
	v_pk_add_f32 v[128:129], v[236:237], v[128:129]
	v_pk_add_f32 v[132:133], v[132:133], v[182:183]
	v_pk_add_f32 v[134:135], v[134:135], v[184:185]
	v_pk_add_f32 v[128:129], v[128:129], v[130:131]
	v_pk_add_f32 v[130:131], v[132:133], v[134:135]
	v_mov_b32_e32 v133, v128
	v_mov_b32_e32 v132, v130
	v_and_b32_e32 v130, 64, v176
	v_add_u32_e32 v155, 64, v130
	v_xor_b32_e32 v130, 16, v176
	v_cmp_lt_i32_e32 vcc, v130, v155
	v_mov_b32_e32 v128, v131
	v_pk_add_f32 v[128:129], v[132:133], v[128:129]
	v_cndmask_b32_e32 v130, v176, v130, vcc
	v_lshlrev_b32_e32 v157, 2, v130
	ds_bpermute_b32 v131, v157, v129
	ds_bpermute_b32 v130, v157, v128
	v_mov_b32_e32 v178, v186
	v_mov_b32_e32 v179, v190
	v_mov_b32_e32 v190, v187
	v_mov_b32_e32 v186, v194
	s_waitcnt lgkmcnt(0)
	v_pk_add_f32 v[128:129], v[128:129], v[130:131]
	v_xor_b32_e32 v130, 32, v176
	v_cmp_lt_i32_e32 vcc, v130, v155
	v_mov_b32_e32 v187, v198
	v_mov_b32_e32 v198, v195
	v_cndmask_b32_e32 v130, v176, v130, vcc
	v_lshlrev_b32_e32 v155, 2, v130
	ds_bpermute_b32 v131, v155, v129
	ds_bpermute_b32 v130, v155, v128
	v_pk_add_f32 v[182:183], v[186:187], v[198:199]
	v_mov_b32_e32 v180, v188
	v_mov_b32_e32 v181, v192
	v_mov_b32_e32 v192, v189
	s_waitcnt lgkmcnt(0)
	v_pk_add_f32 v[128:129], v[128:129], v[130:131]
	v_mov_b64_e32 v[130:131], s[26:27]
	v_pk_fma_f32 v[128:129], v[128:129], s[24:25], v[130:131] op_sel_hi:[1,0,0]
	v_mov_b32_e32 v188, v196
	v_mul_f32_e32 v159, 0x4b800000, v129
	v_cmp_gt_f32_e32 vcc, s73, v129
	v_mov_b32_e32 v189, v200
	v_mov_b32_e32 v200, v197
	v_cndmask_b32_e32 v129, v129, v159, vcc
	v_rsq_f32_e32 v129, v129
	v_pk_add_f32 v[178:179], v[178:179], v[190:191]
	v_pk_add_f32 v[180:181], v[180:181], v[192:193]
	v_pk_add_f32 v[184:185], v[188:189], v[200:201]
	v_mul_f32_e32 v159, 0x45800000, v129
	v_cndmask_b32_e32 v198, v129, v159, vcc
	v_pk_mul_f32 v[126:127], v[126:127], v[198:199] op_sel_hi:[1,0]
	v_pk_mul_f32 v[124:125], v[124:125], v[198:199] op_sel_hi:[1,0]
	v_pk_mul_f32 v[122:123], v[122:123], v[198:199] op_sel_hi:[1,0]
	v_pk_mul_f32 v[120:121], v[120:121], v[198:199] op_sel_hi:[1,0]
	v_cvt_pk_bf16_f32 v124, v124, v125
	v_cvt_pk_bf16_f32 v125, v126, v127
	v_cvt_pk_bf16_f32 v127, v122, v123
	v_lshl_or_b32 v122, s5, 8, v172
	v_cvt_pk_bf16_f32 v126, v120, v121
	v_ashrrev_i32_e32 v123, 31, v122
	v_mov_b64_e32 v[120:121], s[2:3]
	v_mad_i64_i32 v[168:169], s[4:5], v168, s76, v[120:121]
	v_lshlrev_b64 v[122:123], 1, v[122:123]
	v_lshl_add_u64 v[168:169], v[168:169], 0, v[122:123]
	global_store_dwordx4 v[168:169], v[124:127], off
	v_mov_b32_e32 v194, v202
	v_mov_b32_e32 v195, v206
	v_pk_add_f32 v[124:125], v[178:179], v[180:181]
	v_pk_add_f32 v[126:127], v[182:183], v[184:185]
	v_mov_b32_e32 v179, v124
	v_mov_b32_e32 v178, v126
	v_mov_b32_e32 v124, v127
	v_pk_add_f32 v[124:125], v[178:179], v[124:125]
	ds_bpermute_b32 v127, v157, v125
	ds_bpermute_b32 v126, v157, v124
	v_mov_b32_e32 v206, v203
	v_mov_b32_e32 v196, v204
	v_mov_b32_e32 v197, v208
	v_mov_b32_e32 v208, v205
	v_mov_b32_e32 v202, v212
	v_mov_b32_e32 v203, v216
	v_mov_b32_e32 v216, v213
	v_mov_b32_e32 v204, v214
	v_mov_b32_e32 v205, v218
	v_mov_b32_e32 v218, v215
	v_pk_add_f32 v[186:187], v[194:195], v[206:207]
	v_pk_add_f32 v[188:189], v[196:197], v[208:209]
	v_pk_add_f32 v[190:191], v[202:203], v[216:217]
	v_pk_add_f32 v[192:193], v[204:205], v[218:219]
	v_pk_mul_f32 v[178:179], v[114:115], v[198:199] op_sel_hi:[1,0]
	s_waitcnt lgkmcnt(0)
; DI unsigned pack2(float lo, float hi) { f32x2 v = {lo, hi}; bf16v2 r = __builtin_convertvector(v, bf16v2); return __builtin_bit_cast(unsigned, r); }
; DI float row_rstd(const float* ssq, int row, int fq) {
;   const f32x4 a = *(const f32x4*)(ssq + (size_t)row * 32 + fq * 8), b = *(const f32x4*)(ssq + (size_t)row * 32 + fq * 8 + 4);
;   float sm = ((a[0] + a[1]) + (a[2] + a[3])) + ((b[0] + b[1]) + (b[2] + b[3]));
;   sm += __shfl_xor(sm, 16); sm += __shfl_xor(sm, 32);
;   return rsqrtf(sm * (1.0f / 2048.f) + 1e-6f);
;   DI void operator()(const f32x4 (&acc)[2][2][4][2], const Unit& u, int wr, int wc, int fr, int fq) const {
;     ...
;     float rsv[2][4];
; #pragma unroll
;     for (int ai = 0; ai < 2; ++ai)
; #pragma unroll
;       for (int m = 0; m < 4; ++m) rsv[ai][m] = row_rstd(ssq, row0 + ai * HALF + m * 16, fq);
; #pragma unroll
;     for (int ai = 0; ai < 2; ++ai)
; #pragma unroll
;       for (int m = 0; m < 4; ++m) {
;         const int row = row0 + ai * HALF + m * 16;
;         const float rs = rsv[ai][m];
;         bf16_t* rowp = O + (size_t)row * ldc + col0;
; #pragma unroll
;         for (int bj = 0; bj < 2; ++bj) {
;           const f32x4 v0 = acc[ai][bj][m][0] * rs, v1 = acc[ai][bj][m][1] * rs;
;           u32x4 w; w.x = pack2(v0[0], v0[1]); w.y = pack2(v0[2], v0[3]); w.z = pack2(v1[0], v1[1]); w.w = pack2(v1[2], v1[3]);
;           *(u32x4*)(rowp + bj * HALF) = w;
;         }
	v_pk_add_f32 v[114:115], v[124:125], v[126:127]
	v_pk_add_f32 v[126:127], v[186:187], v[188:189]
	v_pk_add_f32 v[180:181], v[190:191], v[192:193]
	v_mov_b32_e32 v183, v126
	v_mov_b32_e32 v182, v180
	v_mov_b32_e32 v126, v181
	v_pk_add_f32 v[126:127], v[182:183], v[126:127]
	ds_bpermute_b32 v125, v155, v115
	ds_bpermute_b32 v124, v155, v114
	ds_bpermute_b32 v181, v157, v127
	ds_bpermute_b32 v180, v157, v126
	v_mul_f32_e32 v129, 0x4b800000, v128
	v_cmp_gt_f32_e32 vcc, s73, v128
	s_waitcnt lgkmcnt(2)
	v_pk_add_f32 v[114:115], v[114:115], v[124:125]
	v_mov_b32_e32 v194, v220
	s_waitcnt lgkmcnt(0)
	v_pk_add_f32 v[124:125], v[126:127], v[180:181]
	ds_bpermute_b32 v127, v155, v125
	ds_bpermute_b32 v126, v155, v124
	v_pk_fma_f32 v[114:115], v[114:115], s[24:25], v[130:131] op_sel_hi:[1,0,0]
	v_cndmask_b32_e32 v159, v128, v129, vcc
	v_mul_f32_e32 v128, 0x4b800000, v115
	v_cmp_gt_f32_e64 s[4:5], s73, v115
	v_cmp_gt_f32_e64 s[6:7], s73, v114
	v_mov_b32_e32 v195, v224
	v_cndmask_b32_e64 v161, v115, v128, s[4:5]
	v_mul_f32_e32 v115, 0x4b800000, v114
	v_mov_b32_e32 v224, v221
	v_mov_b32_e32 v196, v222
	v_mov_b32_e32 v197, v226
	v_mov_b32_e32 v226, v223
	v_cndmask_b32_e64 v163, v114, v115, s[6:7]
	s_waitcnt lgkmcnt(0)
	v_pk_add_f32 v[114:115], v[124:125], v[126:127]
	v_pk_add_f32 v[132:133], v[194:195], v[224:225]
	v_pk_add_f32 v[134:135], v[196:197], v[226:227]
	v_mov_b32_e32 v194, v228
	v_mov_b32_e32 v195, v232
	v_mov_b32_e32 v232, v229
	v_mov_b32_e32 v196, v230
	v_mov_b32_e32 v197, v234
	v_mov_b32_e32 v234, v231
	v_pk_fma_f32 v[114:115], v[114:115], s[24:25], v[130:131] op_sel_hi:[1,0,0]
	v_pk_add_f32 v[194:195], v[194:195], v[232:233]
	v_pk_add_f32 v[196:197], v[196:197], v[234:235]
	v_mul_f32_e32 v124, 0x4b800000, v115
	v_cmp_gt_f32_e64 s[8:9], s73, v115
	v_pk_add_f32 v[126:127], v[194:195], v[196:197]
	v_cmp_gt_f32_e64 s[10:11], s73, v114
	v_cndmask_b32_e64 v165, v115, v124, s[8:9]
	v_pk_add_f32 v[124:125], v[132:133], v[134:135]
	v_mov_b32_e32 v128, v126
	v_mov_b32_e32 v129, v124
	v_mov_b32_e32 v124, v127
	v_pk_add_f32 v[124:125], v[128:129], v[124:125]
	ds_bpermute_b32 v127, v157, v125
	ds_bpermute_b32 v126, v157, v124
	v_rsq_f32_e32 v128, v159
	v_mul_f32_e32 v115, 0x4b800000, v114
	v_cndmask_b32_e64 v129, v114, v115, s[10:11]
	v_pk_mul_f32 v[116:117], v[116:117], v[198:199] op_sel_hi:[1,0]
	s_waitcnt lgkmcnt(0)
	v_pk_add_f32 v[114:115], v[124:125], v[126:127]
	ds_bpermute_b32 v125, v155, v115
	ds_bpermute_b32 v124, v155, v114
	v_mul_f32_e32 v126, 0x45800000, v128
	v_rsq_f32_e32 v127, v161
	v_cndmask_b32_e32 v126, v128, v126, vcc
	v_rsq_f32_e32 v128, v163
	s_waitcnt lgkmcnt(0)
	v_pk_add_f32 v[114:115], v[114:115], v[124:125]
	v_mul_f32_e32 v124, 0x45800000, v127
	v_cndmask_b32_e64 v124, v127, v124, s[4:5]
	v_mul_f32_e32 v127, 0x45800000, v128
	v_pk_fma_f32 v[114:115], v[114:115], s[24:25], v[130:131] op_sel_hi:[1,0,0]
	v_rsq_f32_e32 v125, v165
	v_cndmask_b32_e64 v128, v128, v127, s[6:7]
	v_rsq_f32_e32 v127, v129
	v_mul_f32_e32 v129, 0x4b800000, v115
	v_cmp_gt_f32_e32 vcc, s73, v115
	v_cmp_gt_f32_e64 s[4:5], s73, v114
	v_pk_mul_f32 v[118:119], v[118:119], v[198:199] op_sel_hi:[1,0]
	v_cndmask_b32_e32 v129, v115, v129, vcc
	v_mul_f32_e32 v115, 0x4b800000, v114
	v_cndmask_b32_e64 v131, v114, v115, s[4:5]
	v_cvt_pk_bf16_f32 v114, v116, v117
	v_rsq_f32_e32 v117, v129
	v_cvt_pk_bf16_f32 v115, v118, v119
	v_rsq_f32_e32 v119, v131
	v_mul_f32_e32 v116, 0x45800000, v125
	v_pk_mul_f32 v[112:113], v[112:113], v[198:199] op_sel_hi:[1,0]
	v_cndmask_b32_e64 v118, v125, v116, s[8:9]
	v_mul_f32_e32 v116, 0x45800000, v127
	v_cndmask_b32_e64 v130, v127, v116, s[10:11]
	v_cvt_pk_bf16_f32 v116, v112, v113
	v_mul_f32_e32 v112, 0x45800000, v117
	v_cndmask_b32_e32 v132, v117, v112, vcc
	v_mul_f32_e32 v112, 0x45800000, v119
	v_cvt_pk_bf16_f32 v117, v178, v179
	v_cndmask_b32_e64 v112, v119, v112, s[4:5]
	global_store_dwordx4 v[168:169], v[114:117], off offset:256
	v_pk_mul_f32 v[110:111], v[110:111], v[126:127] op_sel_hi:[1,0]
	v_pk_mul_f32 v[108:109], v[108:109], v[126:127] op_sel_hi:[1,0]
	v_mad_i64_i32 v[114:115], s[4:5], v154, s76, v[120:121]
	v_pk_mul_f32 v[116:117], v[106:107], v[126:127] op_sel_hi:[1,0]
	v_pk_mul_f32 v[106:107], v[104:105], v[126:127] op_sel_hi:[1,0]
	v_lshl_add_u64 v[114:115], v[114:115], 0, v[122:123]
	v_cvt_pk_bf16_f32 v104, v108, v109
	v_cvt_pk_bf16_f32 v105, v110, v111
	v_cvt_pk_bf16_f32 v106, v106, v107
	v_cvt_pk_bf16_f32 v107, v116, v117
	global_store_dwordx4 v[114:115], v[104:107], off
	v_pk_mul_f32 v[98:99], v[98:99], v[126:127] op_sel_hi:[1,0]
	v_pk_mul_f32 v[96:97], v[96:97], v[126:127] op_sel_hi:[1,0]
	v_pk_mul_f32 v[104:105], v[90:91], v[126:127] op_sel_hi:[1,0]
	v_pk_mul_f32 v[90:91], v[88:89], v[126:127] op_sel_hi:[1,0]
	v_cvt_pk_bf16_f32 v88, v96, v97
	v_cvt_pk_bf16_f32 v89, v98, v99
	v_cvt_pk_bf16_f32 v90, v90, v91
	v_cvt_pk_bf16_f32 v91, v104, v105
	global_store_dwordx4 v[114:115], v[88:91], off offset:256
	v_pk_mul_f32 v[94:95], v[94:95], v[124:125] op_sel_hi:[1,0]
	v_pk_mul_f32 v[92:93], v[92:93], v[124:125] op_sel_hi:[1,0]
	v_mad_i64_i32 v[88:89], s[4:5], v160, s76, v[120:121]
	v_lshl_add_u64 v[96:97], v[88:89], 0, v[122:123]
	v_pk_mul_f32 v[90:91], v[102:103], v[124:125] op_sel_hi:[1,0]
	v_pk_mul_f32 v[88:89], v[100:101], v[124:125] op_sel_hi:[1,0]
	v_pk_mul_f32 v[82:83], v[82:83], v[124:125] op_sel_hi:[1,0]
	v_cvt_pk_bf16_f32 v88, v88, v89
	v_cvt_pk_bf16_f32 v89, v90, v91
	v_cvt_pk_bf16_f32 v90, v92, v93
; DI unsigned pack2(float lo, float hi) { f32x2 v = {lo, hi}; bf16v2 r = __builtin_convertvector(v, bf16v2); return __builtin_bit_cast(unsigned, r); }
; #define PG8_WAIT_V(n) asm volatile("s_waitcnt vmcnt(" #n ")" ::: "memory")
; #define PG8_BAR __builtin_amdgcn_s_barrier()
;   DI void operator()(const f32x4 (&acc)[2][2][4][2], const Unit& u, int wr, int wc, int fr, int fq) const {
;     ...
;     for (int ai = 0; ai < 2; ++ai)
; #pragma unroll
;       for (int m = 0; m < 4; ++m) {
;         const int row = row0 + ai * HALF + m * 16;
;         const float rs = rsv[ai][m];
;         bf16_t* rowp = O + (size_t)row * ldc + col0;
; #pragma unroll
;         for (int bj = 0; bj < 2; ++bj) {
;           const f32x4 v0 = acc[ai][bj][m][0] * rs, v1 = acc[ai][bj][m][1] * rs;
;           u32x4 w; w.x = pack2(v0[0], v0[1]); w.y = pack2(v0[2], v0[3]); w.z = pack2(v1[0], v1[1]); w.w = pack2(v1[2], v1[3]);
;           *(u32x4*)(rowp + bj * HALF) = w;
;         }
; template <class Epi, class Sched = StaticOrder>
; DI void gemm_phase(LAS unsigned char* lds, const Gemm g, const Sched& S, const Epi& E) {
;     ...
;     if (!has_next) break;
; #pragma unroll
;     for (int a = 0; a < 2; ++a)
; #pragma unroll
;       for (int b = 0; b < 2; ++b)
; #pragma unroll
;         for (int m = 0; m < 4; ++m)
; #pragma unroll
;           for (int n = 0; n < 2; ++n) acc[a][b][m][n] = (f32x4){0.f, 0.f, 0.f, 0.f};
;     cur = nxt; cA = nA; cB = nB; ++ui;
;   }
;   PG8_WAIT_V(0);
;   if (wr == 0) PG8_BAR;
;   PG8_BAR;
	v_cvt_pk_bf16_f32 v91, v94, v95
	global_store_dwordx4 v[96:97], v[88:91], off
	v_pk_mul_f32 v[80:81], v[80:81], v[124:125] op_sel_hi:[1,0]
	v_pk_mul_f32 v[78:79], v[78:79], v[128:129] op_sel_hi:[1,0]
	v_pk_mul_f32 v[88:89], v[74:75], v[124:125] op_sel_hi:[1,0]
	v_pk_mul_f32 v[74:75], v[72:73], v[124:125] op_sel_hi:[1,0]
	v_cvt_pk_bf16_f32 v72, v80, v81
	v_cvt_pk_bf16_f32 v73, v82, v83
	v_cvt_pk_bf16_f32 v74, v74, v75
	v_cvt_pk_bf16_f32 v75, v88, v89
	global_store_dwordx4 v[96:97], v[72:75], off offset:256
	v_pk_mul_f32 v[76:77], v[76:77], v[128:129] op_sel_hi:[1,0]
	v_pk_mul_f32 v[70:71], v[70:71], v[128:129] op_sel_hi:[1,0]
	v_mad_i64_i32 v[72:73], s[4:5], v156, s76, v[120:121]
	v_lshl_add_u64 v[80:81], v[72:73], 0, v[122:123]
	v_pk_mul_f32 v[74:75], v[86:87], v[128:129] op_sel_hi:[1,0]
	v_pk_mul_f32 v[72:73], v[84:85], v[128:129] op_sel_hi:[1,0]
	v_pk_mul_f32 v[68:69], v[68:69], v[128:129] op_sel_hi:[1,0]
	v_cvt_pk_bf16_f32 v72, v72, v73
	v_cvt_pk_bf16_f32 v73, v74, v75
	v_cvt_pk_bf16_f32 v74, v76, v77
	v_cvt_pk_bf16_f32 v75, v78, v79
	global_store_dwordx4 v[80:81], v[72:75], off
	v_pk_mul_f32 v[62:63], v[62:63], v[118:119] op_sel_hi:[1,0]
	v_pk_mul_f32 v[60:61], v[60:61], v[118:119] op_sel_hi:[1,0]
	v_pk_mul_f32 v[72:73], v[66:67], v[128:129] op_sel_hi:[1,0]
	v_pk_mul_f32 v[66:67], v[64:65], v[128:129] op_sel_hi:[1,0]
	v_cvt_pk_bf16_f32 v64, v68, v69
	v_cvt_pk_bf16_f32 v65, v70, v71
	v_cvt_pk_bf16_f32 v66, v66, v67
	v_cvt_pk_bf16_f32 v67, v72, v73
	global_store_dwordx4 v[80:81], v[64:67], off offset:256
	v_pk_mul_f32 v[50:51], v[50:51], v[118:119] op_sel_hi:[1,0]
	v_pk_mul_f32 v[48:49], v[48:49], v[118:119] op_sel_hi:[1,0]
	v_mad_i64_i32 v[64:65], s[4:5], v164, s76, v[120:121]
	v_pk_mul_f32 v[66:67], v[58:59], v[118:119] op_sel_hi:[1,0]
	v_pk_mul_f32 v[58:59], v[56:57], v[118:119] op_sel_hi:[1,0]
	v_lshl_add_u64 v[64:65], v[64:65], 0, v[122:123]
	v_cvt_pk_bf16_f32 v56, v60, v61
	v_cvt_pk_bf16_f32 v57, v62, v63
	v_cvt_pk_bf16_f32 v58, v58, v59
	v_cvt_pk_bf16_f32 v59, v66, v67
	global_store_dwordx4 v[64:65], v[56:59], off
	v_pk_mul_f32 v[46:47], v[46:47], v[130:131] op_sel_hi:[1,0]
	v_pk_mul_f32 v[44:45], v[44:45], v[130:131] op_sel_hi:[1,0]
	v_pk_mul_f32 v[56:57], v[42:43], v[118:119] op_sel_hi:[1,0]
	v_pk_mul_f32 v[42:43], v[40:41], v[118:119] op_sel_hi:[1,0]
	v_cvt_pk_bf16_f32 v40, v48, v49
	v_cvt_pk_bf16_f32 v41, v50, v51
	v_cvt_pk_bf16_f32 v42, v42, v43
	v_cvt_pk_bf16_f32 v43, v56, v57
	global_store_dwordx4 v[64:65], v[40:43], off offset:256
	v_pk_mul_f32 v[34:35], v[34:35], v[130:131] op_sel_hi:[1,0]
	v_pk_mul_f32 v[32:33], v[32:33], v[130:131] op_sel_hi:[1,0]
	v_mad_i64_i32 v[40:41], s[4:5], v158, s76, v[120:121]
	v_lshl_add_u64 v[48:49], v[40:41], 0, v[122:123]
	v_pk_mul_f32 v[42:43], v[54:55], v[130:131] op_sel_hi:[1,0]
	v_pk_mul_f32 v[40:41], v[52:53], v[130:131] op_sel_hi:[1,0]
	v_pk_mul_f32 v[30:31], v[30:31], v[132:133] op_sel_hi:[1,0]
	v_cvt_pk_bf16_f32 v40, v40, v41
	v_cvt_pk_bf16_f32 v41, v42, v43
	v_cvt_pk_bf16_f32 v42, v44, v45
	v_cvt_pk_bf16_f32 v43, v46, v47
	global_store_dwordx4 v[48:49], v[40:43], off
	v_pk_mul_f32 v[28:29], v[28:29], v[132:133] op_sel_hi:[1,0]
	v_pk_mul_f32 v[18:19], v[18:19], v[132:133] op_sel_hi:[1,0]
	v_pk_mul_f32 v[40:41], v[26:27], v[130:131] op_sel_hi:[1,0]
	v_pk_mul_f32 v[26:27], v[24:25], v[130:131] op_sel_hi:[1,0]
	v_cvt_pk_bf16_f32 v24, v32, v33
	v_cvt_pk_bf16_f32 v25, v34, v35
	v_cvt_pk_bf16_f32 v26, v26, v27
	v_cvt_pk_bf16_f32 v27, v40, v41
	global_store_dwordx4 v[48:49], v[24:27], off offset:256
	v_pk_mul_f32 v[16:17], v[16:17], v[132:133] op_sel_hi:[1,0]
	v_pk_mul_f32 v[14:15], v[14:15], v[112:113] op_sel_hi:[1,0]
	v_mad_i64_i32 v[24:25], s[4:5], v166, s76, v[120:121]
	v_lshl_add_u64 v[32:33], v[24:25], 0, v[122:123]
	v_pk_mul_f32 v[26:27], v[38:39], v[132:133] op_sel_hi:[1,0]
	v_pk_mul_f32 v[24:25], v[36:37], v[132:133] op_sel_hi:[1,0]
	v_pk_mul_f32 v[12:13], v[12:13], v[112:113] op_sel_hi:[1,0]
	v_cvt_pk_bf16_f32 v24, v24, v25
	v_cvt_pk_bf16_f32 v25, v26, v27
	v_cvt_pk_bf16_f32 v26, v28, v29
	v_cvt_pk_bf16_f32 v27, v30, v31
	global_store_dwordx4 v[32:33], v[24:27], off
	v_pk_mul_f32 v[6:7], v[6:7], v[112:113] op_sel_hi:[1,0]
	v_pk_mul_f32 v[4:5], v[4:5], v[112:113] op_sel_hi:[1,0]
	v_pk_mul_f32 v[24:25], v[10:11], v[132:133] op_sel_hi:[1,0]
	v_pk_mul_f32 v[10:11], v[8:9], v[132:133] op_sel_hi:[1,0]
	v_cvt_pk_bf16_f32 v8, v16, v17
	v_cvt_pk_bf16_f32 v9, v18, v19
	v_cvt_pk_bf16_f32 v10, v10, v11
	v_cvt_pk_bf16_f32 v11, v24, v25
	global_store_dwordx4 v[32:33], v[8:11], off offset:256
	s_and_b64 vcc, exec, s[0:1]
	s_mov_b64 s[8:9], s[36:37]
	v_mad_i64_i32 v[8:9], s[4:5], v162, s76, v[120:121]
	v_lshl_add_u64 v[16:17], v[8:9], 0, v[122:123]
	v_pk_mul_f32 v[10:11], v[22:23], v[112:113] op_sel_hi:[1,0]
	v_pk_mul_f32 v[8:9], v[20:21], v[112:113] op_sel_hi:[1,0]
	s_mov_b32 s5, s28
	v_cvt_pk_bf16_f32 v8, v8, v9
	v_cvt_pk_bf16_f32 v9, v10, v11
	v_cvt_pk_bf16_f32 v10, v12, v13
	v_cvt_pk_bf16_f32 v11, v14, v15
	global_store_dwordx4 v[16:17], v[8:11], off
	s_mov_b32 s4, s30
	s_mov_b64 s[6:7], s[34:35]
	v_pk_mul_f32 v[8:9], v[2:3], v[112:113] op_sel_hi:[1,0]
	v_pk_mul_f32 v[2:3], v[0:1], v[112:113] op_sel_hi:[1,0]
	v_cvt_pk_bf16_f32 v0, v4, v5
	v_cvt_pk_bf16_f32 v1, v6, v7
	v_cvt_pk_bf16_f32 v2, v2, v3
	v_cvt_pk_bf16_f32 v3, v8, v9
	global_store_dwordx4 v[16:17], v[0:3], off offset:256
	s_cbranch_vccz .LBB0_343
	s_waitcnt vmcnt(0)
	s_cmpk_gt_u32 s27, 0xff
	s_cbranch_scc1 .LBB0_350
	s_barrier

; #define PG8_STAGE(bufoff, gbase, voff) do { _Pragma("unroll") for (int _i = 0; _i < 2; ++_i) \
;     __builtin_amdgcn_global_load_lds((const unsigned*)((const char*)(gbase) + (voff)[_i]), (LAS unsigned*)(lds + (bufoff) + ldsw + _i * 8192), 16, 0, 0); } while (0)
; #define PG8_LDA(dst, b, h) do { _Pragma("unroll") for (int m = 0; m < 4; ++m) _Pragma("unroll") for (int k = 0; k < 2; ++k) dst[m][k] = *(const LAS bf16x8*)(lds + PG8_SA(b, h) + aoff + m * 2048 + k * 1024); } while (0)
; #define PG8_LDB(dst, b, h) do { _Pragma("unroll") for (int n = 0; n < 2; ++n) _Pragma("unroll") for (int k = 0; k < 2; ++k) dst[n][k] = *(const LAS bf16x8*)(lds + PG8_SB(b, h) + boff + n * 2048 + k * 1024); } while (0)
; #define PG8_MMA(ai, bj, At, Bt) do { __builtin_amdgcn_s_setprio(1); _Pragma("unroll") for (int m = 0; m < 4; ++m) _Pragma("unroll") for (int n = 0; n < 2; ++n) _Pragma("unroll") for (int k = 0; k < 2; ++k) \
;     acc[ai][bj][m][n] = __builtin_amdgcn_mfma_f32_16x16x32_bf16(Bt[n][k], At[m][k], acc[ai][bj][m][n], 0, 0, 0); __builtin_amdgcn_s_setprio(0); } while (0)
; #define PG8_BAR __builtin_amdgcn_s_barrier()
; template <class Epi, class Sched = StaticOrder>
; DI void gemm_phase(LAS unsigned char* lds, const Gemm g, const Sched& S, const Epi& E) {
;     ...
;     const bool has_next = S.next(ui + 1, nxt);
;     const char* nA = has_next ? (const char*)g.A + (size_t)nxt.pm * tstep : cA; const char* nB = has_next ? (const char*)g.Bt + (size_t)nxt.pn * tstep : cB;
;     for (int t = 0; t < nt; t += 2) {
;       const bool last = (t == nt - 2);
;       const char* a1 = cA + (size_t)(t + 1) * kstep;
;       const char* a2 = last ? nA : cA + (size_t)(t + 2) * kstep; const char* b2 = last ? nB : cB + (size_t)(t + 2) * kstep;
;       const char* a3 = a2 + kstep; const char* b3 = b2 + kstep;
;       PG8_LDB(B0, 0, 0); PG8_SCHED; PG8_LDA(At, 0, 0); PG8_STAGE(PG8_SA(1, 1), a1 + hstep, voffA);
;       PG8_WAIT_L(8); PG8_BAR; PG8_WAIT_L(0); PG8_MMA(0, 0, At, B0); PG8_BAR; PG8_SCHED;
;       PG8_LDB(B1, 0, 1); PG8_STAGE(PG8_SB(0, 0), b2, voffB);
;       PG8_BAR; PG8_WAIT_L(0); PG8_MMA(0, 1, At, B1); PG8_BAR;
;       PG8_LDA(At, 0, 1); PG8_STAGE(PG8_SA(0, 0), a2, voffA);
;       PG8_BAR; PG8_WAIT_L(0); PG8_MMA(1, 0, At, B0); PG8_BAR; PG8_SCHED;
;       PG8_STAGE(PG8_SB(0, 1), b2 + hstep, voffB);
;       PG8_WAIT_V(6); PG8_BAR; PG8_MMA(1, 1, At, B1); PG8_BAR;
.LBB0_728:
	ds_read_b128 v[128:131], v207
	ds_read_b128 v[132:135], v207 offset:1024
	ds_read_b128 v[136:139], v207 offset:2048
	ds_read_b128 v[140:143], v207 offset:3072
	s_add_u32 s24, s22, 0xfff80080
	s_addc_u32 s25, s23, -1
	s_cmp_eq_u32 s53, 28
	s_cselect_b32 s27, s17, s25
	s_cselect_b32 s26, s43, s24
	s_cselect_b32 s25, s15, s52
	s_cselect_b32 s24, s44, s45
	ds_read_b128 v[144:147], v208
	ds_read_b128 v[148:151], v208 offset:1024
	ds_read_b128 v[152:155], v208 offset:2048
	ds_read_b128 v[156:159], v208 offset:3072
	ds_read_b128 v[160:163], v208 offset:4096
	ds_read_b128 v[164:167], v208 offset:5120
	ds_read_b128 v[168:171], v208 offset:6144
	ds_read_b128 v[172:175], v208 offset:7168
	ds_read_b128 v[192:195], v209
	ds_read_b128 v[196:199], v209 offset:1024
	ds_read_b128 v[200:203], v209 offset:2048
	ds_read_b128 v[212:215], v209 offset:3072
	s_waitcnt vmcnt(6)
	s_waitcnt lgkmcnt(4)
	s_setprio 1
	s_barrier
	v_mfma_f32_16x16x32_bf16 v[124:127], v[128:131], v[144:147], v[124:127]
	s_add_i32 m0, s37, 0xc000
	v_mfma_f32_16x16x32_bf16 v[120:123], v[136:139], v[144:147], v[120:123]
	global_load_lds_dwordx4 v184, s[22:23]
	v_mfma_f32_16x16x32_bf16 v[108:111], v[128:131], v[152:155], v[108:111]
	s_add_i32 m0, s37, 0xe000
	v_mfma_f32_16x16x32_bf16 v[104:107], v[136:139], v[152:155], v[104:107]
	global_load_lds_dwordx4 v186, s[22:23]
	v_mfma_f32_16x16x32_bf16 v[92:95], v[128:131], v[160:163], v[92:95]
	v_mfma_f32_16x16x32_bf16 v[88:91], v[136:139], v[160:163], v[88:91]
	v_mfma_f32_16x16x32_bf16 v[76:79], v[128:131], v[168:171], v[76:79]
	v_mfma_f32_16x16x32_bf16 v[72:75], v[136:139], v[168:171], v[72:75]
	v_mfma_f32_16x16x32_bf16 v[124:127], v[132:135], v[148:151], v[124:127]
	v_mfma_f32_16x16x32_bf16 v[120:123], v[140:143], v[148:151], v[120:123]
	v_mfma_f32_16x16x32_bf16 v[108:111], v[132:135], v[156:159], v[108:111]
	v_mfma_f32_16x16x32_bf16 v[104:107], v[140:143], v[156:159], v[104:107]
	v_mfma_f32_16x16x32_bf16 v[92:95], v[132:135], v[164:167], v[92:95]
	v_mfma_f32_16x16x32_bf16 v[88:91], v[140:143], v[164:167], v[88:91]
	v_mfma_f32_16x16x32_bf16 v[76:79], v[132:135], v[172:175], v[76:79]
	v_mfma_f32_16x16x32_bf16 v[72:75], v[140:143], v[172:175], v[72:75]
	s_waitcnt lgkmcnt(0)
	v_mfma_f32_16x16x32_bf16 v[116:119], v[192:195], v[144:147], v[116:119]
	v_mfma_f32_16x16x32_bf16 v[112:115], v[200:203], v[144:147], v[112:115]
	v_mfma_f32_16x16x32_bf16 v[100:103], v[192:195], v[152:155], v[100:103]
	v_mfma_f32_16x16x32_bf16 v[96:99], v[200:203], v[152:155], v[96:99]
	v_mfma_f32_16x16x32_bf16 v[84:87], v[192:195], v[160:163], v[84:87]
	v_mfma_f32_16x16x32_bf16 v[80:83], v[200:203], v[160:163], v[80:83]
	v_mfma_f32_16x16x32_bf16 v[68:71], v[192:195], v[168:171], v[68:71]
	v_mfma_f32_16x16x32_bf16 v[64:67], v[200:203], v[168:171], v[64:67]
	v_mfma_f32_16x16x32_bf16 v[116:119], v[196:199], v[148:151], v[116:119]
	v_mfma_f32_16x16x32_bf16 v[112:115], v[212:215], v[148:151], v[112:115]
	v_mfma_f32_16x16x32_bf16 v[100:103], v[196:199], v[156:159], v[100:103]
	v_mfma_f32_16x16x32_bf16 v[96:99], v[212:215], v[156:159], v[96:99]
	v_mfma_f32_16x16x32_bf16 v[84:87], v[196:199], v[164:167], v[84:87]
	v_mfma_f32_16x16x32_bf16 v[80:83], v[212:215], v[164:167], v[80:83]
	v_mfma_f32_16x16x32_bf16 v[68:71], v[196:199], v[172:175], v[68:71]
	v_mfma_f32_16x16x32_bf16 v[64:67], v[212:215], v[172:175], v[64:67]
	s_barrier
	s_setprio 0
	s_add_i32 s54, s50, s35
	s_add_u32 s98, s24, 0x80
	s_addc_u32 s99, s25, 0
	s_add_u32 s100, s26, 0x80
	s_addc_u32 s101, s27, 0
	s_mov_b32 m0, s54
	s_nop 0
	global_load_lds_dwordx4 v180, s[24:25]
	s_add_i32 m0, s54, 0x2000
	s_nop 0
	global_load_lds_dwordx4 v176, s[24:25]
	s_mov_b32 m0, s37
	ds_read_b128 v[144:147], v208 offset:16384
	ds_read_b128 v[148:151], v208 offset:17408
	ds_read_b128 v[152:155], v208 offset:18432
	ds_read_b128 v[156:159], v208 offset:19456
	ds_read_b128 v[160:163], v208 offset:20480
	ds_read_b128 v[164:167], v208 offset:21504
	ds_read_b128 v[168:171], v208 offset:22528
	ds_read_b128 v[172:175], v208 offset:23552
	global_load_lds_dwordx4 v182, s[26:27]
	s_mov_b32 m0, s38
	s_nop 0
	global_load_lds_dwordx4 v178, s[26:27]
	s_add_u32 s54, s24, 0x80000
	s_addc_u32 s55, s25, 0
	s_add_i32 s57, s51, s35
	s_waitcnt vmcnt(6)
	s_waitcnt lgkmcnt(0)
	s_setprio 1
	s_barrier
	v_mfma_f32_16x16x32_bf16 v[60:63], v[128:131], v[144:147], v[60:63]
	s_mov_b32 m0, s57
	v_mfma_f32_16x16x32_bf16 v[56:59], v[136:139], v[144:147], v[56:59]
	global_load_lds_dwordx4 v180, s[54:55]
	v_mfma_f32_16x16x32_bf16 v[44:47], v[128:131], v[152:155], v[44:47]
	s_bitset1_b32 m0, 13
	v_mfma_f32_16x16x32_bf16 v[40:43], v[136:139], v[152:155], v[40:43]
	global_load_lds_dwordx4 v176, s[54:55]
	v_mfma_f32_16x16x32_bf16 v[28:31], v[128:131], v[160:163], v[28:31]
	v_mfma_f32_16x16x32_bf16 v[24:27], v[136:139], v[160:163], v[24:27]
	v_mfma_f32_16x16x32_bf16 v[12:15], v[128:131], v[168:171], v[12:15]
	v_mfma_f32_16x16x32_bf16 v[8:11], v[136:139], v[168:171], v[8:11]
	v_mfma_f32_16x16x32_bf16 v[60:63], v[132:135], v[148:151], v[60:63]
	v_mfma_f32_16x16x32_bf16 v[56:59], v[140:143], v[148:151], v[56:59]
	v_mfma_f32_16x16x32_bf16 v[44:47], v[132:135], v[156:159], v[44:47]
	v_mfma_f32_16x16x32_bf16 v[40:43], v[140:143], v[156:159], v[40:43]
	v_mfma_f32_16x16x32_bf16 v[28:31], v[132:135], v[164:167], v[28:31]
	v_mfma_f32_16x16x32_bf16 v[24:27], v[140:143], v[164:167], v[24:27]
	v_mfma_f32_16x16x32_bf16 v[12:15], v[132:135], v[172:175], v[12:15]
	v_mfma_f32_16x16x32_bf16 v[8:11], v[140:143], v[172:175], v[8:11]
	v_mfma_f32_16x16x32_bf16 v[52:55], v[192:195], v[144:147], v[52:55]
	v_mfma_f32_16x16x32_bf16 v[48:51], v[200:203], v[144:147], v[48:51]
	v_mfma_f32_16x16x32_bf16 v[36:39], v[192:195], v[152:155], v[36:39]
	v_mfma_f32_16x16x32_bf16 v[32:35], v[200:203], v[152:155], v[32:35]
	v_mfma_f32_16x16x32_bf16 v[20:23], v[192:195], v[160:163], v[20:23]
	v_mfma_f32_16x16x32_bf16 v[16:19], v[200:203], v[160:163], v[16:19]
	v_mfma_f32_16x16x32_bf16 v[4:7], v[192:195], v[168:171], v[4:7]
	v_mfma_f32_16x16x32_bf16 v[0:3], v[200:203], v[168:171], v[0:3]
	v_mfma_f32_16x16x32_bf16 v[52:55], v[196:199], v[148:151], v[52:55]
	v_mfma_f32_16x16x32_bf16 v[48:51], v[212:215], v[148:151], v[48:51]
	v_mfma_f32_16x16x32_bf16 v[36:39], v[196:199], v[156:159], v[36:39]
	v_mfma_f32_16x16x32_bf16 v[32:35], v[212:215], v[156:159], v[32:35]
	v_mfma_f32_16x16x32_bf16 v[20:23], v[196:199], v[164:167], v[20:23]
	v_mfma_f32_16x16x32_bf16 v[16:19], v[212:215], v[164:167], v[16:19]
	v_mfma_f32_16x16x32_bf16 v[4:7], v[196:199], v[172:175], v[4:7]
	v_mfma_f32_16x16x32_bf16 v[0:3], v[212:215], v[172:175], v[0:3]
	s_barrier
; #define PG8_STAGE(bufoff, gbase, voff) do { _Pragma("unroll") for (int _i = 0; _i < 2; ++_i) \
;     __builtin_amdgcn_global_load_lds((const unsigned*)((const char*)(gbase) + (voff)[_i]), (LAS unsigned*)(lds + (bufoff) + ldsw + _i * 8192), 16, 0, 0); } while (0)
; #define PG8_LDA(dst, b, h) do { _Pragma("unroll") for (int m = 0; m < 4; ++m) _Pragma("unroll") for (int k = 0; k < 2; ++k) dst[m][k] = *(const LAS bf16x8*)(lds + PG8_SA(b, h) + aoff + m * 2048 + k * 1024); } while (0)
; #define PG8_LDB(dst, b, h) do { _Pragma("unroll") for (int n = 0; n < 2; ++n) _Pragma("unroll") for (int k = 0; k < 2; ++k) dst[n][k] = *(const LAS bf16x8*)(lds + PG8_SB(b, h) + boff + n * 2048 + k * 1024); } while (0)
; #define PG8_MMA(ai, bj, At, Bt) do { __builtin_amdgcn_s_setprio(1); _Pragma("unroll") for (int m = 0; m < 4; ++m) _Pragma("unroll") for (int n = 0; n < 2; ++n) _Pragma("unroll") for (int k = 0; k < 2; ++k) \
;     acc[ai][bj][m][n] = __builtin_amdgcn_mfma_f32_16x16x32_bf16(Bt[n][k], At[m][k], acc[ai][bj][m][n], 0, 0, 0); __builtin_amdgcn_s_setprio(0); } while (0)
; #define PG8_WAIT_V(n) asm volatile("s_waitcnt vmcnt(" #n ")" ::: "memory")
; #define PG8_WAIT_L(n) asm volatile("s_waitcnt lgkmcnt(" #n ")" ::: "memory")
; #define PG8_BAR __builtin_amdgcn_s_barrier()
; #define PG8_SCHED __builtin_amdgcn_sched_barrier(0)
; template <class Epi, class Sched = StaticOrder>
; DI void gemm_phase(LAS unsigned char* lds, const Gemm g, const Sched& S, const Epi& E) {
;     ...
;       PG8_LDB(B0, 1, 0); PG8_SCHED; PG8_LDA(At, 1, 0); PG8_STAGE(PG8_SA(0, 1), a2 + hstep, voffA);
;       PG8_WAIT_L(8); PG8_BAR; PG8_WAIT_L(0); PG8_MMA(0, 0, At, B0); PG8_BAR; PG8_SCHED;
;       PG8_LDB(B1, 1, 1); PG8_STAGE(PG8_SB(1, 0), b3, voffB);
;       PG8_BAR; PG8_WAIT_L(0); PG8_MMA(0, 1, At, B1); PG8_BAR;
;       PG8_LDA(At, 1, 1); PG8_STAGE(PG8_SA(1, 0), a3, voffA);
;       PG8_BAR; PG8_WAIT_L(0); PG8_MMA(1, 0, At, B0); PG8_BAR; PG8_SCHED;
;       PG8_STAGE(PG8_SB(1, 1), b3 + hstep, voffB);
;       PG8_WAIT_V(6); PG8_BAR; PG8_MMA(1, 1, At, B1); PG8_BAR;
	s_setprio 0
	s_add_i32 s54, 0, 0x18000
	v_add_u32_e32 v140, s54, v205
	ds_read_b128 v[128:131], v140
	ds_read_b128 v[132:135], v140 offset:1024
	ds_read_b128 v[136:139], v140 offset:2048
	ds_read_b128 v[140:143], v140 offset:3072
	s_add_u32 s26, s26, 0x80000
	s_addc_u32 s27, s27, 0
	s_mov_b32 m0, s39
	ds_read_b128 v[144:147], v208 offset:32768
	ds_read_b128 v[148:151], v208 offset:33792
	ds_read_b128 v[152:155], v208 offset:34816
	ds_read_b128 v[156:159], v208 offset:35840
	ds_read_b128 v[160:163], v208 offset:36864
	ds_read_b128 v[164:167], v208 offset:37888
	ds_read_b128 v[168:171], v208 offset:38912
	ds_read_b128 v[172:175], v208 offset:39936
	global_load_lds_dwordx4 v182, s[26:27]
	s_mov_b32 m0, s40
	s_nop 0
	global_load_lds_dwordx4 v178, s[26:27]
	s_add_i32 s26, 0, 0x1c000
	v_add_u32_e32 v212, s26, v205
	ds_read_b128 v[192:195], v212
	ds_read_b128 v[196:199], v212 offset:1024
	ds_read_b128 v[200:203], v212 offset:2048
	ds_read_b128 v[212:215], v212 offset:3072
	s_waitcnt vmcnt(8)
	s_waitcnt lgkmcnt(4)
	s_setprio 1
	s_barrier
	v_mfma_f32_16x16x32_bf16 v[124:127], v[128:131], v[144:147], v[124:127]
	v_mfma_f32_16x16x32_bf16 v[120:123], v[136:139], v[144:147], v[120:123]
	v_mfma_f32_16x16x32_bf16 v[108:111], v[128:131], v[152:155], v[108:111]
	v_mfma_f32_16x16x32_bf16 v[104:107], v[136:139], v[152:155], v[104:107]
	v_mfma_f32_16x16x32_bf16 v[92:95], v[128:131], v[160:163], v[92:95]
	v_mfma_f32_16x16x32_bf16 v[88:91], v[136:139], v[160:163], v[88:91]
	v_mfma_f32_16x16x32_bf16 v[76:79], v[128:131], v[168:171], v[76:79]
	v_mfma_f32_16x16x32_bf16 v[72:75], v[136:139], v[168:171], v[72:75]
	v_mfma_f32_16x16x32_bf16 v[124:127], v[132:135], v[148:151], v[124:127]
	v_mfma_f32_16x16x32_bf16 v[120:123], v[140:143], v[148:151], v[120:123]
	v_mfma_f32_16x16x32_bf16 v[108:111], v[132:135], v[156:159], v[108:111]
	v_mfma_f32_16x16x32_bf16 v[104:107], v[140:143], v[156:159], v[104:107]
	v_mfma_f32_16x16x32_bf16 v[92:95], v[132:135], v[164:167], v[92:95]
	v_mfma_f32_16x16x32_bf16 v[88:91], v[140:143], v[164:167], v[88:91]
	v_mfma_f32_16x16x32_bf16 v[76:79], v[132:135], v[172:175], v[76:79]
	v_mfma_f32_16x16x32_bf16 v[72:75], v[140:143], v[172:175], v[72:75]
	s_waitcnt lgkmcnt(0)
	v_mfma_f32_16x16x32_bf16 v[116:119], v[192:195], v[144:147], v[116:119]
	v_mfma_f32_16x16x32_bf16 v[112:115], v[200:203], v[144:147], v[112:115]
	v_mfma_f32_16x16x32_bf16 v[100:103], v[192:195], v[152:155], v[100:103]
	v_mfma_f32_16x16x32_bf16 v[96:99], v[200:203], v[152:155], v[96:99]
	v_mfma_f32_16x16x32_bf16 v[84:87], v[192:195], v[160:163], v[84:87]
	v_mfma_f32_16x16x32_bf16 v[80:83], v[200:203], v[160:163], v[80:83]
	v_mfma_f32_16x16x32_bf16 v[68:71], v[192:195], v[168:171], v[68:71]
	v_mfma_f32_16x16x32_bf16 v[64:67], v[200:203], v[168:171], v[64:67]
	v_mfma_f32_16x16x32_bf16 v[116:119], v[196:199], v[148:151], v[116:119]
	v_mfma_f32_16x16x32_bf16 v[112:115], v[212:215], v[148:151], v[112:115]
	v_mfma_f32_16x16x32_bf16 v[100:103], v[196:199], v[156:159], v[100:103]
	v_mfma_f32_16x16x32_bf16 v[96:99], v[212:215], v[156:159], v[96:99]
	v_mfma_f32_16x16x32_bf16 v[84:87], v[196:199], v[164:167], v[84:87]
	v_mfma_f32_16x16x32_bf16 v[80:83], v[212:215], v[164:167], v[80:83]
	v_mfma_f32_16x16x32_bf16 v[68:71], v[196:199], v[172:175], v[68:71]
	v_mfma_f32_16x16x32_bf16 v[64:67], v[212:215], v[172:175], v[64:67]
	s_barrier
	s_setprio 0
	s_add_i32 s27, s54, s35
	s_mov_b32 m0, s27
	s_nop 0
	global_load_lds_dwordx4 v180, s[98:99]
	s_add_i32 m0, s27, 0x2000
	s_nop 0
	global_load_lds_dwordx4 v176, s[98:99]
	s_mov_b32 m0, s46
	ds_read_b128 v[144:147], v208 offset:49152
	ds_read_b128 v[148:151], v208 offset:50176
	ds_read_b128 v[152:155], v208 offset:51200
	ds_read_b128 v[156:159], v208 offset:52224
	ds_read_b128 v[160:163], v208 offset:53248
	ds_read_b128 v[164:167], v208 offset:54272
	ds_read_b128 v[168:171], v208 offset:55296
	ds_read_b128 v[172:175], v208 offset:56320
	global_load_lds_dwordx4 v182, s[100:101]
	s_mov_b32 m0, s47
	s_nop 0
	global_load_lds_dwordx4 v178, s[100:101]
	s_add_u32 s24, s24, 0x80080
	s_addc_u32 s25, s25, 0
	s_add_i32 s26, s26, s35
	s_add_i32 s53, s53, 2
	s_add_u32 s22, s22, 0x100
	s_addc_u32 s23, s23, 0
	s_add_u32 s45, s45, 0x100
	s_addc_u32 s52, s52, 0
	s_cmp_gt_u32 s53, 29
	s_waitcnt vmcnt(6)
	s_waitcnt lgkmcnt(0)
	s_setprio 1
	s_barrier
	v_mfma_f32_16x16x32_bf16 v[60:63], v[128:131], v[144:147], v[60:63]
	s_mov_b32 m0, s26
	v_mfma_f32_16x16x32_bf16 v[56:59], v[136:139], v[144:147], v[56:59]
	global_load_lds_dwordx4 v180, s[24:25]
	v_mfma_f32_16x16x32_bf16 v[44:47], v[128:131], v[152:155], v[44:47]
	s_bitset1_b32 m0, 13
	v_mfma_f32_16x16x32_bf16 v[40:43], v[136:139], v[152:155], v[40:43]
	global_load_lds_dwordx4 v176, s[24:25]
	v_mfma_f32_16x16x32_bf16 v[28:31], v[128:131], v[160:163], v[28:31]
	v_mfma_f32_16x16x32_bf16 v[24:27], v[136:139], v[160:163], v[24:27]
	v_mfma_f32_16x16x32_bf16 v[12:15], v[128:131], v[168:171], v[12:15]
	v_mfma_f32_16x16x32_bf16 v[8:11], v[136:139], v[168:171], v[8:11]
	v_mfma_f32_16x16x32_bf16 v[60:63], v[132:135], v[148:151], v[60:63]
	v_mfma_f32_16x16x32_bf16 v[56:59], v[140:143], v[148:151], v[56:59]
	v_mfma_f32_16x16x32_bf16 v[44:47], v[132:135], v[156:159], v[44:47]
	v_mfma_f32_16x16x32_bf16 v[40:43], v[140:143], v[156:159], v[40:43]
	v_mfma_f32_16x16x32_bf16 v[28:31], v[132:135], v[164:167], v[28:31]
	v_mfma_f32_16x16x32_bf16 v[24:27], v[140:143], v[164:167], v[24:27]
	v_mfma_f32_16x16x32_bf16 v[12:15], v[132:135], v[172:175], v[12:15]
	v_mfma_f32_16x16x32_bf16 v[8:11], v[140:143], v[172:175], v[8:11]
	v_mfma_f32_16x16x32_bf16 v[52:55], v[192:195], v[144:147], v[52:55]
	v_mfma_f32_16x16x32_bf16 v[48:51], v[200:203], v[144:147], v[48:51]
	v_mfma_f32_16x16x32_bf16 v[36:39], v[192:195], v[152:155], v[36:39]
	v_mfma_f32_16x16x32_bf16 v[32:35], v[200:203], v[152:155], v[32:35]
	v_mfma_f32_16x16x32_bf16 v[20:23], v[192:195], v[160:163], v[20:23]
	v_mfma_f32_16x16x32_bf16 v[16:19], v[200:203], v[160:163], v[16:19]
	v_mfma_f32_16x16x32_bf16 v[4:7], v[192:195], v[168:171], v[4:7]
	v_mfma_f32_16x16x32_bf16 v[0:3], v[200:203], v[168:171], v[0:3]
	v_mfma_f32_16x16x32_bf16 v[52:55], v[196:199], v[148:151], v[52:55]
	v_mfma_f32_16x16x32_bf16 v[48:51], v[212:215], v[148:151], v[48:51]
	v_mfma_f32_16x16x32_bf16 v[36:39], v[196:199], v[156:159], v[36:39]
	v_mfma_f32_16x16x32_bf16 v[32:35], v[212:215], v[156:159], v[32:35]
	v_mfma_f32_16x16x32_bf16 v[20:23], v[196:199], v[164:167], v[20:23]
	v_mfma_f32_16x16x32_bf16 v[16:19], v[212:215], v[164:167], v[16:19]
	v_mfma_f32_16x16x32_bf16 v[4:7], v[196:199], v[172:175], v[4:7]
	v_mfma_f32_16x16x32_bf16 v[0:3], v[212:215], v[172:175], v[0:3]
	s_barrier
; DI unsigned pack2(float lo, float hi) { f32x2 v = {lo, hi}; bf16v2 r = __builtin_convertvector(v, bf16v2); return __builtin_bit_cast(unsigned, r); }
;   DI void operator()(const f32x4 (&acc)[2][2][4][2], const Unit& u, int wr, int wc, int fr, int fq) const {
;     const int row0 = u.pm * BM + wr * 64 + fr, col0 = u.pn * BM + wc * 32 + 8 * fq;
; #pragma unroll
;     for (int ai = 0; ai < 2; ++ai) {
;       f32x4 bv[4][2][2];
; #pragma unroll
;       for (int m = 0; m < 4; ++m)
; #pragma unroll
;         for (int bj = 0; bj < 2; ++bj) {
;           const float* bp = base + (size_t)(row0 + ai * HALF + m * 16) * 2048 + col0 + bj * HALF;
;           bv[m][bj][0] = *(const f32x4*)bp; bv[m][bj][1] = *(const f32x4*)(bp + 4);
;         }
; #pragma unroll
;       for (int m = 0; m < 4; ++m) {
;         const int row = row0 + ai * HALF + m * 16;
;         const size_t off = (size_t)row * 2048 + col0;
;         float ss = 0.f;
; #pragma unroll
;         for (int bj = 0; bj < 2; ++bj) {
;           const f32x4 v0 = acc[ai][bj][m][0] + bv[m][bj][0], v1 = acc[ai][bj][m][1] + bv[m][bj][1];
;           *(f32x4*)(C + off + bj * HALF) = v0; *(f32x4*)(C + off + bj * HALF + 4) = v1;
;           if (xb) {
;             u32x4 w; w.x = pack2(v0[0], v0[1]); w.y = pack2(v0[2], v0[3]); w.z = pack2(v1[0], v1[1]); w.w = pack2(v1[2], v1[3]);
;             *(u32x4*)(xb + off + bj * HALF) = w;
;             ss += v0[0] * v0[0] + v0[1] * v0[1] + v0[2] * v0[2] + v0[3] * v0[3] + v1[0] * v1[0] + v1[1] * v1[1] + v1[2] * v1[2] + v1[3] * v1[3];
;           }
;         }
;         if (xb) {
;           ss += __shfl_xor(ss, 16); ss += __shfl_xor(ss, 32);
;           if (fq == 0) ssq[(size_t)row * 32 + u.pn * 4 + wc] = ss;
	s_setprio 0
	s_cbranch_scc0 .LBB0_728
	v_lshl_add_u32 v196, s12, 8, v204
	v_lshl_or_b32 v192, s42, 8, v206
	v_ashrrev_i32_e32 v193, 31, v192
	v_ashrrev_i32_e32 v197, 31, v196
	v_lshl_add_u64 v[194:195], v[192:193], 2, s[60:61]
	v_lshlrev_b64 v[128:129], 13, v[196:197]
	v_lshl_add_u64 v[128:129], v[194:195], 0, v[128:129]
	global_load_dwordx4 v[214:217], v[128:129], off
	global_load_dwordx4 v[218:221], v[128:129], off offset:16
	global_load_dwordx4 v[222:225], v[128:129], off offset:512
	global_load_dwordx4 v[226:229], v[128:129], off offset:528
	v_or_b32_e32 v202, 16, v196
	v_or_b32_e32 v200, 32, v196
	v_or_b32_e32 v198, 48, v196
	v_ashrrev_i32_e32 v203, 31, v202
	v_ashrrev_i32_e32 v201, 31, v200
	v_ashrrev_i32_e32 v199, 31, v198
	v_lshlrev_b64 v[128:129], 13, v[202:203]
	v_lshlrev_b64 v[130:131], 13, v[200:201]
	v_lshlrev_b64 v[132:133], 13, v[198:199]
	v_lshl_add_u64 v[128:129], v[194:195], 0, v[128:129]
	v_lshl_add_u64 v[130:131], v[194:195], 0, v[130:131]
	v_lshl_add_u64 v[132:133], v[194:195], 0, v[132:133]
	global_load_dwordx4 v[168:171], v[128:129], off offset:16
	global_load_dwordx4 v[172:175], v[128:129], off
	global_load_dwordx4 v[160:163], v[128:129], off offset:528
	global_load_dwordx4 v[164:167], v[128:129], off offset:512
	global_load_dwordx4 v[152:155], v[130:131], off offset:16
	global_load_dwordx4 v[156:159], v[130:131], off
	global_load_dwordx4 v[144:147], v[130:131], off offset:528
	global_load_dwordx4 v[148:151], v[130:131], off offset:512
	global_load_dwordx4 v[136:139], v[132:133], off offset:16
	global_load_dwordx4 v[140:143], v[132:133], off
	s_nop 0
	global_load_dwordx4 v[128:131], v[132:133], off offset:528
	s_nop 0
	global_load_dwordx4 v[132:135], v[132:133], off offset:512
	v_and_b32_e32 v212, 64, v211
	v_xor_b32_e32 v230, 16, v211
	v_add_u32_e32 v232, 64, v212
	v_xor_b32_e32 v231, 32, v211
	v_cmp_lt_i32_e32 vcc, v230, v232
	v_lshlrev_b64 v[212:213], 11, v[196:197]
	v_readlane_b32 s64, v243, 3
	v_cndmask_b32_e32 v233, v211, v230, vcc
	v_cmp_lt_i32_e32 vcc, v231, v232
	v_readlane_b32 s78, v243, 17
	v_readlane_b32 s79, v243, 18
	v_cndmask_b32_e32 v234, v211, v231, vcc
	v_lshl_add_u64 v[230:231], v[212:213], 0, v[192:193]
	v_lshlrev_b32_e32 v212, 2, v233
	v_lshl_add_u64 v[232:233], v[230:231], 2, s[78:79]
	v_lshl_add_u64 v[230:231], v[230:231], 1, s[2:3]
	s_lshl_b32 s22, s42, 2
	s_ashr_i32 s23, s22, 31
	v_readlane_b32 s65, v243, 4
	v_readlane_b32 s66, v243, 5
	v_readlane_b32 s67, v243, 6
	v_readlane_b32 s68, v243, 7
	v_readlane_b32 s69, v243, 8
	v_readlane_b32 s70, v243, 9
	v_readlane_b32 s71, v243, 10
	v_readlane_b32 s72, v243, 11
	v_readlane_b32 s73, v243, 12
	v_readlane_b32 s74, v243, 13
	v_readlane_b32 s75, v243, 14
	v_readlane_b32 s76, v243, 15
	v_readlane_b32 s77, v243, 16
	s_waitcnt vmcnt(0)
	v_pk_add_f32 v[126:127], v[126:127], v[216:217]
	v_pk_add_f32 v[124:125], v[124:125], v[214:215]
	v_pk_add_f32 v[116:117], v[116:117], v[222:223]
	v_pk_add_f32 v[122:123], v[122:123], v[220:221]
	v_pk_add_f32 v[120:121], v[120:121], v[218:219]
	v_pk_add_f32 v[214:215], v[112:113], v[226:227]
	global_store_dwordx4 v[232:233], v[124:127], off
	global_store_dwordx4 v[232:233], v[120:123], off offset:16
	v_cvt_pk_bf16_f32 v112, v124, v125
	v_mul_f32_e32 v125, v125, v125
	v_mul_f32_e32 v213, v117, v117
	v_pk_add_f32 v[118:119], v[118:119], v[224:225]
	v_fmac_f32_e32 v125, v124, v124
	v_fmac_f32_e32 v213, v116, v116
	v_fmac_f32_e32 v125, v126, v126
	v_fmac_f32_e32 v213, v118, v118
	v_fmac_f32_e32 v125, v127, v127
	v_fmac_f32_e32 v213, v119, v119
	v_fmac_f32_e32 v125, v120, v120
	v_fmac_f32_e32 v213, v214, v214
	v_pk_add_f32 v[216:217], v[114:115], v[228:229]
	v_fmac_f32_e32 v125, v121, v121
	v_fmac_f32_e32 v213, v215, v215
	v_fmac_f32_e32 v125, v122, v122
	v_fmac_f32_e32 v213, v216, v216
	v_fmac_f32_e32 v125, v123, v123
	v_fmac_f32_e32 v213, v217, v217
	v_cvt_pk_bf16_f32 v114, v120, v121
	v_add_f32_e32 v120, v125, v213
	ds_bpermute_b32 v121, v212, v120
	v_cvt_pk_bf16_f32 v113, v126, v127
	v_cvt_pk_bf16_f32 v115, v122, v123
	global_store_dwordx4 v[230:231], v[112:115], off
	global_store_dwordx4 v[232:233], v[116:119], off offset:512
	global_store_dwordx4 v[232:233], v[214:217], off offset:528
	v_cvt_pk_bf16_f32 v122, v116, v117
	s_waitcnt lgkmcnt(0)
	v_add_f32_e32 v112, v120, v121
	v_lshlrev_b32_e32 v120, 2, v234
	ds_bpermute_b32 v113, v120, v112
	v_cvt_pk_bf16_f32 v123, v118, v119
	v_cvt_pk_bf16_f32 v124, v214, v215
	v_cvt_pk_bf16_f32 v125, v216, v217
	global_store_dwordx4 v[230:231], v[122:125], off offset:256
	s_and_saveexec_b64 s[24:25], s[0:1]
	s_cbranch_execz .LBB0_731
	s_waitcnt lgkmcnt(0)
	v_add_f32_e32 v114, v112, v113
	v_lshlrev_b64 v[112:113], 7, v[196:197]
	v_lshl_add_u64 v[112:113], s[8:9], 0, v[112:113]
	v_lshl_add_u64 v[112:113], s[22:23], 2, v[112:113]
	s_lshl_b32 s12, s41, 2
	v_lshl_add_u64 v[112:113], v[112:113], 0, s[12:13]
	global_store_dword v[112:113], v114, off

; #define PG8_STAGE(bufoff, gbase, voff) do { _Pragma("unroll") for (int _i = 0; _i < 2; ++_i) \
;     __builtin_amdgcn_global_load_lds((const unsigned*)((const char*)(gbase) + (voff)[_i]), (LAS unsigned*)(lds + (bufoff) + ldsw + _i * 8192), 16, 0, 0); } while (0)
; #define PG8_LDA(dst, b, h) do { _Pragma("unroll") for (int m = 0; m < 4; ++m) _Pragma("unroll") for (int k = 0; k < 2; ++k) dst[m][k] = *(const LAS bf16x8*)(lds + PG8_SA(b, h) + aoff + m * 2048 + k * 1024); } while (0)
; #define PG8_LDB(dst, b, h) do { _Pragma("unroll") for (int n = 0; n < 2; ++n) _Pragma("unroll") for (int k = 0; k < 2; ++k) dst[n][k] = *(const LAS bf16x8*)(lds + PG8_SB(b, h) + boff + n * 2048 + k * 1024); } while (0)
; #define PG8_MMA(ai, bj, At, Bt) do { __builtin_amdgcn_s_setprio(1); _Pragma("unroll") for (int m = 0; m < 4; ++m) _Pragma("unroll") for (int n = 0; n < 2; ++n) _Pragma("unroll") for (int k = 0; k < 2; ++k) \
;     acc[ai][bj][m][n] = __builtin_amdgcn_mfma_f32_16x16x32_bf16(Bt[n][k], At[m][k], acc[ai][bj][m][n], 0, 0, 0); __builtin_amdgcn_s_setprio(0); } while (0)
; #define PG8_BAR __builtin_amdgcn_s_barrier()
; template <class Epi, class Sched = StaticOrder>
; DI void gemm_phase(LAS unsigned char* lds, const Gemm g, const Sched& S, const Epi& E) {
;     ...
;     const bool has_next = S.next(ui + 1, nxt);
;     const char* nA = has_next ? (const char*)g.A + (size_t)nxt.pm * tstep : cA; const char* nB = has_next ? (const char*)g.Bt + (size_t)nxt.pn * tstep : cB;
;     for (int t = 0; t < nt; t += 2) {
;       const bool last = (t == nt - 2);
;       const char* a1 = cA + (size_t)(t + 1) * kstep;
;       const char* a2 = last ? nA : cA + (size_t)(t + 2) * kstep; const char* b2 = last ? nB : cB + (size_t)(t + 2) * kstep;
;       const char* a3 = a2 + kstep; const char* b3 = b2 + kstep;
;       PG8_LDB(B0, 0, 0); PG8_SCHED; PG8_LDA(At, 0, 0); PG8_STAGE(PG8_SA(1, 1), a1 + hstep, voffA);
;       PG8_WAIT_L(8); PG8_BAR; PG8_WAIT_L(0); PG8_MMA(0, 0, At, B0); PG8_BAR; PG8_SCHED;
;       PG8_LDB(B1, 0, 1); PG8_STAGE(PG8_SB(0, 0), b2, voffB);
;       PG8_BAR; PG8_WAIT_L(0); PG8_MMA(0, 1, At, B1); PG8_BAR;
;       PG8_LDA(At, 0, 1); PG8_STAGE(PG8_SA(0, 0), a2, voffA);
;       PG8_BAR; PG8_WAIT_L(0); PG8_MMA(1, 0, At, B0); PG8_BAR; PG8_SCHED;
;       PG8_STAGE(PG8_SB(0, 1), b2 + hstep, voffB);
;       PG8_WAIT_V(6); PG8_BAR; PG8_MMA(1, 1, At, B1); PG8_BAR;
.LBB0_811:
	ds_read_b128 v[64:67], v201
	ds_read_b128 v[68:71], v201 offset:1024
	ds_read_b128 v[72:75], v201 offset:2048
	ds_read_b128 v[76:79], v201 offset:3072
	s_add_u32 s46, s14, 0xfff80080
	s_addc_u32 s47, s15, -1
	s_cmp_eq_u32 s52, 28
	s_cselect_b32 s49, s37, s47
	s_cselect_b32 s48, s42, s46
	s_cselect_b32 s47, s35, s45
	s_cselect_b32 s46, s43, s44
	ds_read_b128 v[80:83], v202
	ds_read_b128 v[84:87], v202 offset:1024
	ds_read_b128 v[92:95], v202 offset:2048
	ds_read_b128 v[96:99], v202 offset:3072
	ds_read_b128 v[180:183], v202 offset:4096
	ds_read_b128 v[184:187], v202 offset:5120
	ds_read_b128 v[188:191], v202 offset:6144
	ds_read_b128 v[192:195], v202 offset:7168
	ds_read_b128 v[206:209], v203
	ds_read_b128 v[212:215], v203 offset:1024
	ds_read_b128 v[216:219], v203 offset:2048
	ds_read_b128 v[220:223], v203 offset:3072
	s_waitcnt vmcnt(6)
	s_waitcnt lgkmcnt(4)
	s_setprio 1
	s_barrier
	v_mfma_f32_16x16x32_bf16 v[156:159], v[64:67], v[80:83], v[156:159]
	s_add_i32 m0, s62, 0xc000
	v_mfma_f32_16x16x32_bf16 v[144:147], v[72:75], v[80:83], v[144:147]
	global_load_lds_dwordx4 v170, s[14:15]
	v_mfma_f32_16x16x32_bf16 v[140:143], v[64:67], v[92:95], v[140:143]
	s_add_i32 m0, s62, 0xe000
	v_mfma_f32_16x16x32_bf16 v[132:135], v[72:75], v[92:95], v[132:135]
	global_load_lds_dwordx4 v172, s[14:15]
	v_mfma_f32_16x16x32_bf16 v[124:127], v[64:67], v[180:183], v[124:127]
	v_mfma_f32_16x16x32_bf16 v[116:119], v[72:75], v[180:183], v[116:119]
	v_mfma_f32_16x16x32_bf16 v[112:115], v[64:67], v[188:191], v[112:115]
	v_mfma_f32_16x16x32_bf16 v[108:111], v[72:75], v[188:191], v[108:111]
	v_mfma_f32_16x16x32_bf16 v[156:159], v[68:71], v[84:87], v[156:159]
	v_mfma_f32_16x16x32_bf16 v[144:147], v[76:79], v[84:87], v[144:147]
	v_mfma_f32_16x16x32_bf16 v[140:143], v[68:71], v[96:99], v[140:143]
	v_mfma_f32_16x16x32_bf16 v[132:135], v[76:79], v[96:99], v[132:135]
	v_mfma_f32_16x16x32_bf16 v[124:127], v[68:71], v[184:187], v[124:127]
	v_mfma_f32_16x16x32_bf16 v[116:119], v[76:79], v[184:187], v[116:119]
	v_mfma_f32_16x16x32_bf16 v[112:115], v[68:71], v[192:195], v[112:115]
	v_mfma_f32_16x16x32_bf16 v[108:111], v[76:79], v[192:195], v[108:111]
	s_waitcnt lgkmcnt(0)
	v_mfma_f32_16x16x32_bf16 v[152:155], v[206:209], v[80:83], v[152:155]
	v_mfma_f32_16x16x32_bf16 v[80:83], v[216:219], v[80:83], v[148:151]
	v_mfma_f32_16x16x32_bf16 v[152:155], v[212:215], v[84:87], v[152:155]
	v_mfma_f32_16x16x32_bf16 v[80:83], v[220:223], v[84:87], v[80:83]
	v_mfma_f32_16x16x32_bf16 v[84:87], v[206:209], v[92:95], v[136:139]
	v_mfma_f32_16x16x32_bf16 v[92:95], v[216:219], v[92:95], v[128:131]
	v_mfma_f32_16x16x32_bf16 v[104:107], v[216:219], v[180:183], v[104:107]
	v_mfma_f32_16x16x32_bf16 v[100:103], v[206:209], v[188:191], v[100:103]
	v_mfma_f32_16x16x32_bf16 v[88:91], v[216:219], v[188:191], v[88:91]
	v_mfma_f32_16x16x32_bf16 v[84:87], v[212:215], v[96:99], v[84:87]
	v_mfma_f32_16x16x32_bf16 v[92:95], v[220:223], v[96:99], v[92:95]
	v_mfma_f32_16x16x32_bf16 v[96:99], v[206:209], v[180:183], v[120:123]
	v_mfma_f32_16x16x32_bf16 v[104:107], v[220:223], v[184:187], v[104:107]
	v_mfma_f32_16x16x32_bf16 v[100:103], v[212:215], v[192:195], v[100:103]
	v_mfma_f32_16x16x32_bf16 v[88:91], v[220:223], v[192:195], v[88:91]
	v_mfma_f32_16x16x32_bf16 v[96:99], v[212:215], v[184:187], v[96:99]
	s_barrier
	s_setprio 0
	s_add_i32 s53, s72, s60
	s_add_u32 s98, s46, 0x80
	s_addc_u32 s99, s47, 0
	s_add_u32 s100, s48, 0x80
	s_addc_u32 s101, s49, 0
	s_mov_b32 m0, s53
	s_nop 0
	global_load_lds_dwordx4 v164, s[46:47]
	s_add_i32 m0, s53, 0x2000
	s_nop 0
	global_load_lds_dwordx4 v160, s[46:47]
	s_mov_b32 m0, s62
	ds_read_b128 v[120:123], v202 offset:16384
	ds_read_b128 v[128:131], v202 offset:17408
	ds_read_b128 v[136:139], v202 offset:18432
	ds_read_b128 v[148:151], v202 offset:19456
	ds_read_b128 v[180:183], v202 offset:20480
	ds_read_b128 v[184:187], v202 offset:21504
	ds_read_b128 v[188:191], v202 offset:22528
	ds_read_b128 v[192:195], v202 offset:23552
	global_load_lds_dwordx4 v166, s[48:49]
	s_mov_b32 m0, s63
	s_nop 0
	global_load_lds_dwordx4 v162, s[48:49]
	s_add_u32 s54, s46, 0x80000
	s_addc_u32 s55, s47, 0
	s_add_i32 s53, s73, s60
	s_waitcnt vmcnt(6)
	s_waitcnt lgkmcnt(0)
	s_setprio 1
	s_barrier
	v_mfma_f32_16x16x32_bf16 v[60:63], v[64:67], v[120:123], v[60:63]
	s_mov_b32 m0, s53
	v_mfma_f32_16x16x32_bf16 v[48:51], v[72:75], v[120:123], v[48:51]
	global_load_lds_dwordx4 v164, s[54:55]
	v_mfma_f32_16x16x32_bf16 v[44:47], v[64:67], v[136:139], v[44:47]
	s_bitset1_b32 m0, 13
	v_mfma_f32_16x16x32_bf16 v[36:39], v[72:75], v[136:139], v[36:39]
	global_load_lds_dwordx4 v160, s[54:55]
	v_mfma_f32_16x16x32_bf16 v[28:31], v[64:67], v[180:183], v[28:31]
	v_mfma_f32_16x16x32_bf16 v[20:23], v[72:75], v[180:183], v[20:23]
	v_mfma_f32_16x16x32_bf16 v[16:19], v[64:67], v[188:191], v[16:19]
	v_mfma_f32_16x16x32_bf16 v[12:15], v[72:75], v[188:191], v[12:15]
	v_mfma_f32_16x16x32_bf16 v[60:63], v[68:71], v[128:131], v[60:63]
	v_mfma_f32_16x16x32_bf16 v[48:51], v[76:79], v[128:131], v[48:51]
	v_mfma_f32_16x16x32_bf16 v[44:47], v[68:71], v[148:151], v[44:47]
	v_mfma_f32_16x16x32_bf16 v[36:39], v[76:79], v[148:151], v[36:39]
	v_mfma_f32_16x16x32_bf16 v[28:31], v[68:71], v[184:187], v[28:31]
	v_mfma_f32_16x16x32_bf16 v[20:23], v[76:79], v[184:187], v[20:23]
	v_mfma_f32_16x16x32_bf16 v[16:19], v[68:71], v[192:195], v[16:19]
	v_mfma_f32_16x16x32_bf16 v[12:15], v[76:79], v[192:195], v[12:15]
	v_mfma_f32_16x16x32_bf16 v[56:59], v[206:209], v[120:123], v[56:59]
	v_mfma_f32_16x16x32_bf16 v[52:55], v[216:219], v[120:123], v[52:55]
	v_mfma_f32_16x16x32_bf16 v[40:43], v[206:209], v[136:139], v[40:43]
	v_mfma_f32_16x16x32_bf16 v[32:35], v[216:219], v[136:139], v[32:35]
	v_mfma_f32_16x16x32_bf16 v[24:27], v[206:209], v[180:183], v[24:27]
	v_mfma_f32_16x16x32_bf16 v[8:11], v[216:219], v[180:183], v[8:11]
	v_mfma_f32_16x16x32_bf16 v[4:7], v[206:209], v[188:191], v[4:7]
	v_mfma_f32_16x16x32_bf16 v[0:3], v[216:219], v[188:191], v[0:3]
	v_mfma_f32_16x16x32_bf16 v[56:59], v[212:215], v[128:131], v[56:59]
	v_mfma_f32_16x16x32_bf16 v[52:55], v[220:223], v[128:131], v[52:55]
	v_mfma_f32_16x16x32_bf16 v[40:43], v[212:215], v[148:151], v[40:43]
	v_mfma_f32_16x16x32_bf16 v[32:35], v[220:223], v[148:151], v[32:35]
	v_mfma_f32_16x16x32_bf16 v[24:27], v[212:215], v[184:187], v[24:27]
	v_mfma_f32_16x16x32_bf16 v[8:11], v[220:223], v[184:187], v[8:11]
	v_mfma_f32_16x16x32_bf16 v[4:7], v[212:215], v[192:195], v[4:7]
	v_mfma_f32_16x16x32_bf16 v[0:3], v[220:223], v[192:195], v[0:3]
	s_barrier
; #define PG8_STAGE(bufoff, gbase, voff) do { _Pragma("unroll") for (int _i = 0; _i < 2; ++_i) \
;     __builtin_amdgcn_global_load_lds((const unsigned*)((const char*)(gbase) + (voff)[_i]), (LAS unsigned*)(lds + (bufoff) + ldsw + _i * 8192), 16, 0, 0); } while (0)
; #define PG8_LDA(dst, b, h) do { _Pragma("unroll") for (int m = 0; m < 4; ++m) _Pragma("unroll") for (int k = 0; k < 2; ++k) dst[m][k] = *(const LAS bf16x8*)(lds + PG8_SA(b, h) + aoff + m * 2048 + k * 1024); } while (0)
; #define PG8_LDB(dst, b, h) do { _Pragma("unroll") for (int n = 0; n < 2; ++n) _Pragma("unroll") for (int k = 0; k < 2; ++k) dst[n][k] = *(const LAS bf16x8*)(lds + PG8_SB(b, h) + boff + n * 2048 + k * 1024); } while (0)
; #define PG8_MMA(ai, bj, At, Bt) do { __builtin_amdgcn_s_setprio(1); _Pragma("unroll") for (int m = 0; m < 4; ++m) _Pragma("unroll") for (int n = 0; n < 2; ++n) _Pragma("unroll") for (int k = 0; k < 2; ++k) \
;     acc[ai][bj][m][n] = __builtin_amdgcn_mfma_f32_16x16x32_bf16(Bt[n][k], At[m][k], acc[ai][bj][m][n], 0, 0, 0); __builtin_amdgcn_s_setprio(0); } while (0)
; #define PG8_WAIT_V(n) asm volatile("s_waitcnt vmcnt(" #n ")" ::: "memory")
; #define PG8_WAIT_L(n) asm volatile("s_waitcnt lgkmcnt(" #n ")" ::: "memory")
; #define PG8_BAR __builtin_amdgcn_s_barrier()
; #define PG8_SCHED __builtin_amdgcn_sched_barrier(0)
; template <class Epi, class Sched = StaticOrder>
; DI void gemm_phase(LAS unsigned char* lds, const Gemm g, const Sched& S, const Epi& E) {
;     ...
;       PG8_LDB(B0, 1, 0); PG8_SCHED; PG8_LDA(At, 1, 0); PG8_STAGE(PG8_SA(0, 1), a2 + hstep, voffA);
;       PG8_WAIT_L(8); PG8_BAR; PG8_WAIT_L(0); PG8_MMA(0, 0, At, B0); PG8_BAR; PG8_SCHED;
;       PG8_LDB(B1, 1, 1); PG8_STAGE(PG8_SB(1, 0), b3, voffB);
;       PG8_BAR; PG8_WAIT_L(0); PG8_MMA(0, 1, At, B1); PG8_BAR;
;       PG8_LDA(At, 1, 1); PG8_STAGE(PG8_SA(1, 0), a3, voffA);
;       PG8_BAR; PG8_WAIT_L(0); PG8_MMA(1, 0, At, B0); PG8_BAR; PG8_SCHED;
;       PG8_STAGE(PG8_SB(1, 1), b3 + hstep, voffB);
;       PG8_WAIT_V(6); PG8_BAR; PG8_MMA(1, 1, At, B1); PG8_BAR;
	s_setprio 0
	s_add_i32 s53, 0, 0x18000
	v_add_u32_e32 v76, s53, v198
	ds_read_b128 v[64:67], v76
	ds_read_b128 v[68:71], v76 offset:1024
	ds_read_b128 v[72:75], v76 offset:2048
	ds_read_b128 v[76:79], v76 offset:3072
	s_add_u32 s48, s48, 0x80000
	s_addc_u32 s49, s49, 0
	s_mov_b32 m0, s64
	ds_read_b128 v[120:123], v202 offset:32768
	ds_read_b128 v[128:131], v202 offset:33792
	ds_read_b128 v[180:183], v202 offset:34816
	ds_read_b128 v[184:187], v202 offset:35840
	ds_read_b128 v[188:191], v202 offset:36864
	ds_read_b128 v[192:195], v202 offset:37888
	ds_read_b128 v[206:209], v202 offset:38912
	ds_read_b128 v[212:215], v202 offset:39936
	global_load_lds_dwordx4 v166, s[48:49]
	s_mov_b32 m0, s65
	s_nop 0
	global_load_lds_dwordx4 v162, s[48:49]
	s_add_i32 s48, 0, 0x1c000
	v_add_u32_e32 v244, s48, v198
	ds_read_b128 v[216:219], v244
	ds_read_b128 v[220:223], v244 offset:1024
	ds_read_b128 v[224:227], v244 offset:2048
	ds_read_b128 v[228:231], v244 offset:3072
	s_waitcnt vmcnt(8)
	s_waitcnt lgkmcnt(4)
	s_setprio 1
	s_barrier
	v_mfma_f32_16x16x32_bf16 v[136:139], v[64:67], v[120:123], v[156:159]
	v_mfma_f32_16x16x32_bf16 v[156:159], v[68:71], v[128:131], v[136:139]
	v_mfma_f32_16x16x32_bf16 v[136:139], v[72:75], v[120:123], v[144:147]
	v_mfma_f32_16x16x32_bf16 v[144:147], v[76:79], v[128:131], v[136:139]
	v_mfma_f32_16x16x32_bf16 v[136:139], v[64:67], v[180:183], v[140:143]
	v_mfma_f32_16x16x32_bf16 v[132:135], v[72:75], v[180:183], v[132:135]
	v_mfma_f32_16x16x32_bf16 v[124:127], v[64:67], v[188:191], v[124:127]
	v_mfma_f32_16x16x32_bf16 v[116:119], v[72:75], v[188:191], v[116:119]
	v_mfma_f32_16x16x32_bf16 v[112:115], v[64:67], v[206:209], v[112:115]
	v_mfma_f32_16x16x32_bf16 v[108:111], v[72:75], v[206:209], v[108:111]
	v_mfma_f32_16x16x32_bf16 v[140:143], v[68:71], v[184:187], v[136:139]
	v_mfma_f32_16x16x32_bf16 v[132:135], v[76:79], v[184:187], v[132:135]
	v_mfma_f32_16x16x32_bf16 v[124:127], v[68:71], v[192:195], v[124:127]
	v_mfma_f32_16x16x32_bf16 v[116:119], v[76:79], v[192:195], v[116:119]
	v_mfma_f32_16x16x32_bf16 v[112:115], v[68:71], v[212:215], v[112:115]
	v_mfma_f32_16x16x32_bf16 v[108:111], v[76:79], v[212:215], v[108:111]
	s_waitcnt lgkmcnt(0)
	v_mfma_f32_16x16x32_bf16 v[80:83], v[224:227], v[120:123], v[80:83]
	v_mfma_f32_16x16x32_bf16 v[136:139], v[216:219], v[120:123], v[152:155]
	v_mfma_f32_16x16x32_bf16 v[148:151], v[228:231], v[128:131], v[80:83]
	v_mfma_f32_16x16x32_bf16 v[80:83], v[216:219], v[180:183], v[84:87]
	v_mfma_f32_16x16x32_bf16 v[152:155], v[220:223], v[128:131], v[136:139]
	v_mfma_f32_16x16x32_bf16 v[136:139], v[220:223], v[184:187], v[80:83]
	v_mfma_f32_16x16x32_bf16 v[80:83], v[224:227], v[180:183], v[92:95]
	v_mfma_f32_16x16x32_bf16 v[128:131], v[228:231], v[184:187], v[80:83]
	v_mfma_f32_16x16x32_bf16 v[80:83], v[216:219], v[188:191], v[96:99]
	v_mfma_f32_16x16x32_bf16 v[120:123], v[220:223], v[192:195], v[80:83]
	v_mfma_f32_16x16x32_bf16 v[80:83], v[224:227], v[188:191], v[104:107]
	v_mfma_f32_16x16x32_bf16 v[104:107], v[228:231], v[192:195], v[80:83]
	v_mfma_f32_16x16x32_bf16 v[80:83], v[216:219], v[206:209], v[100:103]
	v_mfma_f32_16x16x32_bf16 v[100:103], v[220:223], v[212:215], v[80:83]
	v_mfma_f32_16x16x32_bf16 v[80:83], v[224:227], v[206:209], v[88:91]
	v_mfma_f32_16x16x32_bf16 v[88:91], v[228:231], v[212:215], v[80:83]
	s_barrier
	s_setprio 0
	s_add_i32 s49, s53, s60
	s_mov_b32 m0, s49
	s_nop 0
	global_load_lds_dwordx4 v164, s[98:99]
	s_add_i32 m0, s49, 0x2000
	s_nop 0
	global_load_lds_dwordx4 v160, s[98:99]
	s_mov_b32 m0, s67
	s_nop 2
	ds_read_b128 v[80:83], v202 offset:49152
	ds_read_b128 v[84:87], v202 offset:50176
	ds_read_b128 v[92:95], v202 offset:51200
	ds_read_b128 v[96:99], v202 offset:52224
	ds_read_b128 v[180:183], v202 offset:53248
	ds_read_b128 v[184:187], v202 offset:54272
	ds_read_b128 v[188:191], v202 offset:55296
	ds_read_b128 v[192:195], v202 offset:56320
	global_load_lds_dwordx4 v166, s[100:101]
	s_mov_b32 m0, s68
	s_nop 0
	global_load_lds_dwordx4 v162, s[100:101]
	s_add_u32 s46, s46, 0x80080
	s_addc_u32 s47, s47, 0
	s_add_i32 s48, s48, s60
	s_add_i32 s52, s52, 2
	s_add_u32 s14, s14, 0x100
	s_addc_u32 s15, s15, 0
	s_add_u32 s44, s44, 0x100
	s_addc_u32 s45, s45, 0
	s_cmp_gt_u32 s52, 29
	s_waitcnt vmcnt(6)
	s_waitcnt lgkmcnt(0)
	s_setprio 1
	s_barrier
	v_mfma_f32_16x16x32_bf16 v[60:63], v[64:67], v[80:83], v[60:63]
	s_mov_b32 m0, s48
	v_mfma_f32_16x16x32_bf16 v[48:51], v[72:75], v[80:83], v[48:51]
	global_load_lds_dwordx4 v164, s[46:47]
	v_mfma_f32_16x16x32_bf16 v[44:47], v[64:67], v[92:95], v[44:47]
	s_bitset1_b32 m0, 13
	v_mfma_f32_16x16x32_bf16 v[36:39], v[72:75], v[92:95], v[36:39]
	global_load_lds_dwordx4 v160, s[46:47]
	v_mfma_f32_16x16x32_bf16 v[28:31], v[64:67], v[180:183], v[28:31]
	v_mfma_f32_16x16x32_bf16 v[20:23], v[72:75], v[180:183], v[20:23]
	v_mfma_f32_16x16x32_bf16 v[16:19], v[64:67], v[188:191], v[16:19]
	v_mfma_f32_16x16x32_bf16 v[12:15], v[72:75], v[188:191], v[12:15]
	v_mfma_f32_16x16x32_bf16 v[60:63], v[68:71], v[84:87], v[60:63]
	v_mfma_f32_16x16x32_bf16 v[48:51], v[76:79], v[84:87], v[48:51]
	v_mfma_f32_16x16x32_bf16 v[44:47], v[68:71], v[96:99], v[44:47]
	v_mfma_f32_16x16x32_bf16 v[36:39], v[76:79], v[96:99], v[36:39]
	v_mfma_f32_16x16x32_bf16 v[28:31], v[68:71], v[184:187], v[28:31]
	v_mfma_f32_16x16x32_bf16 v[20:23], v[76:79], v[184:187], v[20:23]
	v_mfma_f32_16x16x32_bf16 v[16:19], v[68:71], v[192:195], v[16:19]
	v_mfma_f32_16x16x32_bf16 v[12:15], v[76:79], v[192:195], v[12:15]
	v_mfma_f32_16x16x32_bf16 v[56:59], v[216:219], v[80:83], v[56:59]
	v_mfma_f32_16x16x32_bf16 v[52:55], v[224:227], v[80:83], v[52:55]
	v_mfma_f32_16x16x32_bf16 v[40:43], v[216:219], v[92:95], v[40:43]
	v_mfma_f32_16x16x32_bf16 v[32:35], v[224:227], v[92:95], v[32:35]
	v_mfma_f32_16x16x32_bf16 v[24:27], v[216:219], v[180:183], v[24:27]
	v_mfma_f32_16x16x32_bf16 v[8:11], v[224:227], v[180:183], v[8:11]
	v_mfma_f32_16x16x32_bf16 v[4:7], v[216:219], v[188:191], v[4:7]
	v_mfma_f32_16x16x32_bf16 v[0:3], v[224:227], v[188:191], v[0:3]
	v_mfma_f32_16x16x32_bf16 v[56:59], v[220:223], v[84:87], v[56:59]
	v_mfma_f32_16x16x32_bf16 v[52:55], v[228:231], v[84:87], v[52:55]
	v_mfma_f32_16x16x32_bf16 v[40:43], v[220:223], v[96:99], v[40:43]
	v_mfma_f32_16x16x32_bf16 v[32:35], v[228:231], v[96:99], v[32:35]
	v_mfma_f32_16x16x32_bf16 v[24:27], v[220:223], v[184:187], v[24:27]
	v_mfma_f32_16x16x32_bf16 v[8:11], v[228:231], v[184:187], v[8:11]
	v_mfma_f32_16x16x32_bf16 v[4:7], v[220:223], v[192:195], v[4:7]
	v_mfma_f32_16x16x32_bf16 v[0:3], v[228:231], v[192:195], v[0:3]
	s_barrier
; DI float dpp_ror1(float v) { return __int_as_float(__builtin_amdgcn_update_dpp(0, __float_as_int(v), 0x121, 0xf, 0xf, false)); }
; DI float dpp_ror2(float v) { return __int_as_float(__builtin_amdgcn_update_dpp(0, __float_as_int(v), 0x122, 0xf, 0xf, false)); }
; DI float row_rstd(const float* ssq, int row, int fq) {
;   const f32x4 a = *(const f32x4*)(ssq + (size_t)row * 32 + fq * 8), b = *(const f32x4*)(ssq + (size_t)row * 32 + fq * 8 + 4);
;   float sm = ((a[0] + a[1]) + (a[2] + a[3])) + ((b[0] + b[1]) + (b[2] + b[3]));
;   sm += __shfl_xor(sm, 16); sm += __shfl_xor(sm, 32);
;   return rsqrtf(sm * (1.0f / 2048.f) + 1e-6f);
;   DI void operator()(const f32x4 (&acc)[2][2][4][2], const Unit& u, int wr, int wc, int fr, int fq) const {
;     const int col = u.pn * 128 + wc * 32 + 8 * fq;
;     float w0[8], w1[8], w2[8], bb[8];
; #pragma unroll
;     for (int e = 0; e < 8; ++e) { w0[e] = cw[col + e]; w1[e] = cw[5632 + col + e]; w2[e] = cw[2 * 5632 + col + e]; bb[e] = cb[col + e]; }
; #pragma unroll
;     for (int ai = 0; ai < 2; ++ai) {
;       const int row0 = u.pm * BM + ai * HALF + wr * 64, span = row0 >> 6;
;       float rsv[4];
; #pragma unroll
;       for (int m = 0; m < 4; ++m) rsv[m] = row_rstd(ssq, row0 + 16 * m + fr, fq);
;       float p1[8], p2[8];
; #pragma unroll
;       for (int e = 0; e < 8; ++e) { p1[e] = 0.f; p2[e] = 0.f; }
; #pragma unroll
;       for (int m = 0; m < 4; ++m) {
;         float g[8], uu[8], a[8];
;         const float rs = rsv[m];
; #pragma unroll
;         for (int e = 0; e < 4; ++e) { g[e] = acc[ai][0][m][0][e] * rs; g[4 + e] = acc[ai][0][m][1][e] * rs; uu[e] = acc[ai][1][m][0][e] * rs; uu[4 + e] = acc[ai][1][m][1][e] * rs; }
; #pragma unroll
;         for (int e = 0; e < 8; ++e) {
;           const float x1 = dpp_ror1(g[e]), x2 = dpp_ror2(g[e]);
	s_setprio 0
	s_cbranch_scc0 .LBB0_811
	s_lshl_b32 s35, s12, 8
	s_add_i32 s35, s35, s66
	v_or_b32_e32 v190, s35, v179
	v_ashrrev_i32_e32 v191, 31, v190
	v_lshlrev_b64 v[64:65], 7, v[190:191]
	v_or_b32_e32 v188, 16, v190
	v_lshl_add_u64 v[64:65], v[168:169], 0, v[64:65]
	v_ashrrev_i32_e32 v189, 31, v188
	global_load_dwordx4 v[192:195], v[64:65], off
	global_load_dwordx4 v[206:209], v[64:65], off offset:16
	v_lshlrev_b64 v[64:65], 7, v[188:189]
	v_lshl_add_u64 v[64:65], v[168:169], 0, v[64:65]
	global_load_dwordx4 v[212:215], v[64:65], off
	global_load_dwordx4 v[216:219], v[64:65], off offset:16
	v_or_b32_e32 v186, 32, v190
	v_ashrrev_i32_e32 v187, 31, v186
	v_lshlrev_b64 v[64:65], 7, v[186:187]
	v_or_b32_e32 v184, 48, v190
	v_lshl_add_u64 v[64:65], v[168:169], 0, v[64:65]
	v_ashrrev_i32_e32 v185, 31, v184
	global_load_dwordx4 v[220:223], v[64:65], off
	global_load_dwordx4 v[224:227], v[64:65], off offset:16
	v_lshlrev_b64 v[64:65], 7, v[184:185]
	v_lshl_add_u64 v[64:65], v[168:169], 0, v[64:65]
	global_load_dwordx4 v[228:231], v[64:65], off
	global_load_dwordx4 v[232:235], v[64:65], off offset:16
	v_lshl_or_b32 v180, s13, 7, v200
	v_and_b32_e32 v65, 64, v204
	v_xor_b32_e32 v64, 16, v204
	v_ashrrev_i32_e32 v181, 31, v180
	v_add_u32_e32 v65, 64, v65
	v_readlane_b32 s44, v243, 3
	v_xor_b32_e32 v66, 32, v204
	v_lshlrev_b64 v[182:183], 2, v[180:181]
	v_cmp_lt_i32_e32 vcc, v64, v65
	v_readlane_b32 s52, v243, 11
	v_readlane_b32 s53, v243, 12
	v_cndmask_b32_e32 v64, v204, v64, vcc
	v_cmp_lt_i32_e32 vcc, v66, v65
	v_lshl_add_u64 v[92:93], s[52:53], 0, v[182:183]
	v_readlane_b32 s54, v243, 13
	v_cndmask_b32_e32 v65, v204, v66, vcc
	v_add_co_u32_e32 v94, vcc, 0x5000, v92
	v_readlane_b32 s55, v243, 14
	s_nop 0
	v_addc_co_u32_e32 v95, vcc, 0, v93, vcc
	v_add_co_u32_e32 v96, vcc, 0xb000, v92
	v_lshl_add_u64 v[72:73], s[54:55], 0, v[182:183]
	v_lshl_add_u64 v[74:75], v[92:93], 0, s[26:27]
	v_lshl_add_u64 v[76:77], v[92:93], 0, s[28:29]
	v_addc_co_u32_e32 v97, vcc, 0, v93, vcc
	v_lshlrev_b32_e32 v187, 2, v64
	v_lshlrev_b32_e32 v185, 2, v65
	global_load_dwordx4 v[64:67], v[92:93], off offset:16
	global_load_dwordx4 v[80:83], v[92:93], off
	global_load_dwordx4 v[68:71], v[72:73], off offset:16
	global_load_dwordx4 v[84:87], v[72:73], off
	s_nop 0
	global_load_dwordx4 v[72:75], v[74:75], off offset:16
	s_nop 0
	global_load_dwordx4 v[76:79], v[76:77], off offset:16
	s_nop 0
	global_load_dwordx4 v[92:95], v[94:95], off offset:2048
	s_nop 0
	global_load_dwordx4 v[96:99], v[96:97], off
	v_mov_b32_e32 v211, 0
	v_mov_b32_e32 v205, 0
	v_readlane_b32 s45, v243, 4
	v_readlane_b32 s46, v243, 5
	v_readlane_b32 s47, v243, 6
	v_readlane_b32 s48, v243, 7
	v_readlane_b32 s49, v243, 8
	v_readlane_b32 s50, v243, 9
	v_readlane_b32 s51, v243, 10
	v_readlane_b32 s56, v243, 15
	v_readlane_b32 s57, v243, 16
	v_readlane_b32 s58, v243, 17
	v_readlane_b32 s59, v243, 18
	s_waitcnt vmcnt(0)
	v_mov_b32_e32 v196, v192
	v_mov_b32_e32 v197, v206
	v_mov_b32_e32 v206, v193
	v_mov_b32_e32 v192, v194
	v_mov_b32_e32 v193, v208
	v_mov_b32_e32 v208, v195
	v_pk_add_f32 v[194:195], v[196:197], v[206:207]
	v_pk_add_f32 v[192:193], v[192:193], v[208:209]
	v_mov_b32_e32 v196, v212
	v_mov_b32_e32 v197, v216
	v_mov_b32_e32 v216, v213
	v_mov_b32_e32 v206, v214
	v_mov_b32_e32 v207, v218
	v_mov_b32_e32 v218, v215
	v_pk_add_f32 v[192:193], v[194:195], v[192:193]
	v_pk_add_f32 v[194:195], v[196:197], v[216:217]
	v_pk_add_f32 v[196:197], v[206:207], v[218:219]
	v_mov_b32_e32 v208, v220
	v_pk_add_f32 v[194:195], v[194:195], v[196:197]
	v_mov_b32_e32 v197, v192
	v_mov_b32_e32 v196, v194
	v_mov_b32_e32 v192, v195
	v_pk_add_f32 v[192:193], v[196:197], v[192:193]
	ds_bpermute_b32 v195, v187, v193
	ds_bpermute_b32 v194, v187, v192
	v_mov_b32_e32 v209, v224
	v_mov_b32_e32 v224, v221
	v_mov_b32_e32 v212, v222
	v_mov_b32_e32 v213, v226
	s_waitcnt lgkmcnt(0)
	v_pk_add_f32 v[192:193], v[192:193], v[194:195]
	ds_bpermute_b32 v195, v185, v193
	ds_bpermute_b32 v194, v185, v192
	v_mov_b32_e32 v226, v223
	v_mov_b32_e32 v196, v228
	v_mov_b32_e32 v197, v232
	v_mov_b32_e32 v232, v229
	s_waitcnt lgkmcnt(0)
; DI unsigned pack2(float lo, float hi) { f32x2 v = {lo, hi}; bf16v2 r = __builtin_convertvector(v, bf16v2); return __builtin_bit_cast(unsigned, r); }
; DI float silu_f(float x) { return x * sigmoid_f(x); }
; DI float dpp_ror1(float v) { return __int_as_float(__builtin_amdgcn_update_dpp(0, __float_as_int(v), 0x121, 0xf, 0xf, false)); }
; DI float dpp_ror2(float v) { return __int_as_float(__builtin_amdgcn_update_dpp(0, __float_as_int(v), 0x122, 0xf, 0xf, false)); }
;   DI void operator()(const f32x4 (&acc)[2][2][4][2], const Unit& u, int wr, int wc, int fr, int fq) const {
;     ...
;       for (int m = 0; m < 4; ++m) {
;         float g[8], uu[8], a[8];
;         const float rs = rsv[m];
; #pragma unroll
;         for (int e = 0; e < 4; ++e) { g[e] = acc[ai][0][m][0][e] * rs; g[4 + e] = acc[ai][0][m][1][e] * rs; uu[e] = acc[ai][1][m][0][e] * rs; uu[4 + e] = acc[ai][1][m][1][e] * rs; }
; #pragma unroll
;         for (int e = 0; e < 8; ++e) {
;           const float x1 = dpp_ror1(g[e]), x2 = dpp_ror2(g[e]);
;           const float pr1 = (fr == 0) ? p1[e] : x1, pr2 = (fr < 2) ? p2[e] : x2;
;           a[e] = w2[e] * g[e] + w1[e] * pr1 + w0[e] * pr2 + bb[e];
;           p1[e] = x1; p2[e] = x2;
;         }
;         if (m == 0 && fr < 2) {
;           float* ha = headA + (size_t)(span * 2 + fr) * 5632 + col; float* hu = headU + (size_t)(span * 2 + fr) * 5632 + col;
;           *(f32x4*)ha = (f32x4){a[0], a[1], a[2], a[3]}; *(f32x4*)(ha + 4) = (f32x4){a[4], a[5], a[6], a[7]};
;           *(f32x4*)hu = (f32x4){uu[0], uu[1], uu[2], uu[3]}; *(f32x4*)(hu + 4) = (f32x4){uu[4], uu[5], uu[6], uu[7]};
;         } else {
;           u32x4 w;
;           w.x = pack2(silu_f(a[0]) * uu[0], silu_f(a[1]) * uu[1]);
;           w.y = pack2(silu_f(a[2]) * uu[2], silu_f(a[3]) * uu[3]);
;           w.z = pack2(silu_f(a[4]) * uu[4], silu_f(a[5]) * uu[5]);
;           w.w = pack2(silu_f(a[6]) * uu[6], silu_f(a[7]) * uu[7]);
;           *(u32x4*)(H + (size_t)(row0 + 16 * m + fr) * 5632 + col) = w;
;         }
	v_pk_add_f32 v[192:193], v[192:193], v[194:195]
	v_mov_b32_e32 v206, v230
	v_pk_fma_f32 v[192:193], v[192:193], s[30:31], v[178:179] op_sel_hi:[1,0,0]
	v_mov_b32_e32 v207, v234
	v_mul_f32_e32 v189, 0x4b800000, v193
	v_cmp_gt_f32_e64 s[12:13], s74, v193
	v_mov_b32_e32 v234, v231
	v_pk_add_f32 v[208:209], v[208:209], v[224:225]
	v_cndmask_b32_e64 v189, v193, v189, s[12:13]
	v_rsq_f32_e32 v189, v189
	v_pk_add_f32 v[212:213], v[212:213], v[226:227]
	v_pk_add_f32 v[196:197], v[196:197], v[232:233]
	v_pk_add_f32 v[194:195], v[206:207], v[234:235]
	v_mul_f32_e32 v191, 0x45800000, v189
	v_cndmask_b32_e64 v220, v189, v191, s[12:13]
	v_pk_add_f32 v[208:209], v[208:209], v[212:213]
	v_pk_add_f32 v[194:195], v[196:197], v[194:195]
	v_pk_mul_f32 v[156:157], v[156:157], v[220:221] op_sel_hi:[1,0]
	v_mov_b32_e32 v216, 0
	v_mov_b32_e32 v218, 0
	v_mov_b32_e32 v196, v194
	v_mov_b32_e32 v197, v208
	v_mov_b32_e32 v208, v195
	v_mov_b32_dpp v216, v156 row_ror:1 row_mask:0xf bank_mask:0xf
	v_mov_b32_dpp v218, v157 row_ror:1 row_mask:0xf bank_mask:0xf
	v_pk_add_f32 v[194:195], v[196:197], v[208:209]
	v_cndmask_b32_e64 v207, v218, 0, s[0:1]
	v_cndmask_b32_e64 v206, v216, 0, s[0:1]
	v_pk_mul_f32 v[158:159], v[158:159], v[220:221] op_sel_hi:[1,0]
	v_mov_b32_e32 v212, 0
	v_mov_b32_e32 v214, 0
	ds_bpermute_b32 v197, v187, v195
	ds_bpermute_b32 v196, v187, v194
	v_mov_b32_e32 v215, 0
	v_mov_b32_e32 v217, 0
	v_pk_mul_f32 v[206:207], v[92:93], v[206:207]
	v_mov_b32_dpp v212, v158 row_ror:1 row_mask:0xf bank_mask:0xf
	v_mov_b32_dpp v214, v159 row_ror:1 row_mask:0xf bank_mask:0xf
	v_mov_b32_dpp v215, v156 row_ror:2 row_mask:0xf bank_mask:0xf
	v_mov_b32_dpp v217, v157 row_ror:2 row_mask:0xf bank_mask:0xf
	v_pk_fma_f32 v[156:157], v[96:97], v[156:157], v[206:207]
	v_mov_b32_e32 v213, 0
	v_cndmask_b32_e64 v207, v214, 0, s[0:1]
	v_cndmask_b32_e64 v206, v212, 0, s[0:1]
	v_cndmask_b32_e64 v209, v217, 0, s[4:5]
	v_cndmask_b32_e64 v208, v215, 0, s[4:5]
	v_mov_b32_dpp v211, v158 row_ror:2 row_mask:0xf bank_mask:0xf
	v_mov_b32_dpp v213, v159 row_ror:2 row_mask:0xf bank_mask:0xf
	v_pk_mul_f32 v[206:207], v[94:95], v[206:207]
	v_pk_fma_f32 v[156:157], v[80:81], v[208:209], v[156:157]
	v_cndmask_b32_e64 v209, v213, 0, s[4:5]
	v_cndmask_b32_e64 v208, v211, 0, s[4:5]
	v_pk_fma_f32 v[158:159], v[98:99], v[158:159], v[206:207]
	v_pk_mul_f32 v[144:145], v[144:145], v[220:221] op_sel_hi:[1,0]
	v_pk_fma_f32 v[158:159], v[82:83], v[208:209], v[158:159]
	v_mov_b32_e32 v207, 0
	v_mov_b32_e32 v209, 0
	v_pk_mul_f32 v[146:147], v[146:147], v[220:221] op_sel_hi:[1,0]
	v_mov_b32_e32 v191, 0
	s_waitcnt lgkmcnt(0)
	v_pk_add_f32 v[194:195], v[194:195], v[196:197]
	v_mov_b32_dpp v207, v144 row_ror:1 row_mask:0xf bank_mask:0xf
	v_mov_b32_dpp v209, v145 row_ror:1 row_mask:0xf bank_mask:0xf
	v_mov_b32_dpp v191, v146 row_ror:1 row_mask:0xf bank_mask:0xf
	v_mov_b32_dpp v205, v147 row_ror:1 row_mask:0xf bank_mask:0xf
	ds_bpermute_b32 v197, v185, v195
	ds_bpermute_b32 v196, v185, v194
	v_pk_mul_f32 v[152:153], v[152:153], v[220:221] op_sel_hi:[1,0]
	v_pk_mul_f32 v[148:149], v[148:149], v[220:221] op_sel_hi:[1,0]
	v_pk_mul_f32 v[154:155], v[154:155], v[220:221] op_sel_hi:[1,0]
	v_pk_mul_f32 v[150:151], v[150:151], v[220:221] op_sel_hi:[1,0]
	v_mov_b32_e32 v206, 0
	v_mov_b32_e32 v208, 0
	v_cndmask_b32_e64 v223, v209, 0, s[0:1]
	v_cndmask_b32_e64 v222, v207, 0, s[0:1]
	v_mov_b32_e32 v189, 0
	v_mov_b32_e32 v193, 0
	v_cndmask_b32_e64 v221, v205, 0, s[0:1]
	v_cndmask_b32_e64 v220, v191, 0, s[0:1]
	v_mov_b32_dpp v206, v144 row_ror:2 row_mask:0xf bank_mask:0xf
	v_mov_b32_dpp v208, v145 row_ror:2 row_mask:0xf bank_mask:0xf
	v_pk_mul_f32 v[222:223], v[72:73], v[222:223]
	v_mov_b32_dpp v189, v146 row_ror:2 row_mask:0xf bank_mask:0xf
	v_mov_b32_dpp v193, v147 row_ror:2 row_mask:0xf bank_mask:0xf
	v_pk_mul_f32 v[220:221], v[74:75], v[220:221]
	v_cndmask_b32_e64 v225, v208, 0, s[4:5]
	v_cndmask_b32_e64 v224, v206, 0, s[4:5]
	v_pk_fma_f32 v[144:145], v[76:77], v[144:145], v[222:223]
	v_cndmask_b32_e64 v223, v193, 0, s[4:5]
	v_cndmask_b32_e64 v222, v189, 0, s[4:5]
	v_pk_fma_f32 v[146:147], v[78:79], v[146:147], v[220:221]
	v_pk_fma_f32 v[144:145], v[64:65], v[224:225], v[144:145]
	v_pk_fma_f32 v[146:147], v[66:67], v[222:223], v[146:147]
	v_cmp_gt_f32_e32 vcc, s74, v192
	v_pk_add_f32 v[156:157], v[84:85], v[156:157]
	v_pk_add_f32 v[158:159], v[86:87], v[158:159]
	v_pk_add_f32 v[144:145], v[68:69], v[144:145]
	v_pk_add_f32 v[146:147], v[70:71], v[146:147]
	s_and_saveexec_b64 s[12:13], s[10:11]
	s_xor_b64 s[12:13], exec, s[12:13]
	s_cbranch_execz .LBB0_814
	v_mul_f32_e32 v219, 0xbfb8aa3b, v156
	v_exp_f32_e32 v219, v219
	v_mul_f32_e32 v220, 0xbfb8aa3b, v157
	v_exp_f32_e32 v220, v220
	v_mul_f32_e32 v222, 0xbfb8aa3b, v159
	v_add_f32_e32 v219, 1.0, v219
	v_exp_f32_e32 v223, v222
	v_add_f32_e32 v221, 1.0, v220
	v_rcp_f32_e32 v220, v219
	v_mul_f32_e32 v219, 0xbfb8aa3b, v158
	v_exp_f32_e32 v219, v219
	v_rcp_f32_e32 v221, v221
	v_add_f32_e32 v219, 1.0, v219
	v_rcp_f32_e32 v222, v219
	v_add_f32_e32 v219, 1.0, v223
	v_rcp_f32_e32 v223, v219
	v_pk_mul_f32 v[156:157], v[156:157], v[220:221]
	s_nop 0
	v_pk_mul_f32 v[152:153], v[152:153], v[156:157]
	v_pk_mul_f32 v[156:157], v[158:159], v[222:223]
	v_cvt_pk_bf16_f32 v152, v152, v153
	v_mul_f32_e32 v153, 0xbfb8aa3b, v144
	v_pk_mul_f32 v[154:155], v[154:155], v[156:157]
	v_exp_f32_e32 v156, v153
	v_mul_f32_e32 v153, 0xbfb8aa3b, v145
	v_exp_f32_e32 v157, v153
	v_cvt_pk_bf16_f32 v153, v154, v155
	v_add_f32_e32 v154, 1.0, v156
	v_mul_f32_e32 v156, 0xbfb8aa3b, v146
	v_add_f32_e32 v155, 1.0, v157
	v_mul_f32_e32 v157, 0xbfb8aa3b, v147
	v_exp_f32_e32 v156, v156
	v_exp_f32_e32 v157, v157
	v_rcp_f32_e32 v154, v154
	v_rcp_f32_e32 v155, v155
	v_add_f32_e32 v156, 1.0, v156
	v_add_f32_e32 v157, 1.0, v157
	v_rcp_f32_e32 v156, v156
	v_rcp_f32_e32 v157, v157
	v_pk_mul_f32 v[144:145], v[144:145], v[154:155]
	s_nop 0
	v_pk_mul_f32 v[144:145], v[148:149], v[144:145]
	s_nop 0
	v_cvt_pk_bf16_f32 v154, v144, v145
	v_pk_mul_f32 v[144:145], v[146:147], v[156:157]
	s_nop 0
	v_pk_mul_f32 v[144:145], v[150:151], v[144:145]
	s_nop 0
	v_cvt_pk_bf16_f32 v155, v144, v145
	v_mov_b64_e32 v[144:145], s[16:17]
	v_mad_i64_i32 v[144:145], s[14:15], v190, s75, v[144:145]
	v_lshl_add_u64 v[144:145], v[180:181], 1, v[144:145]
	global_store_dwordx4 v[144:145], v[152:155], off

; #define PG8_STAGE(bufoff, gbase, voff) do { _Pragma("unroll") for (int _i = 0; _i < 2; ++_i) \
;     __builtin_amdgcn_global_load_lds((const unsigned*)((const char*)(gbase) + (voff)[_i]), (LAS unsigned*)(lds + (bufoff) + ldsw + _i * 8192), 16, 0, 0); } while (0)
; #define PG8_LDA(dst, b, h) do { _Pragma("unroll") for (int m = 0; m < 4; ++m) _Pragma("unroll") for (int k = 0; k < 2; ++k) dst[m][k] = *(const LAS bf16x8*)(lds + PG8_SA(b, h) + aoff + m * 2048 + k * 1024); } while (0)
; #define PG8_LDB(dst, b, h) do { _Pragma("unroll") for (int n = 0; n < 2; ++n) _Pragma("unroll") for (int k = 0; k < 2; ++k) dst[n][k] = *(const LAS bf16x8*)(lds + PG8_SB(b, h) + boff + n * 2048 + k * 1024); } while (0)
; #define PG8_MMA(ai, bj, At, Bt) do { __builtin_amdgcn_s_setprio(1); _Pragma("unroll") for (int m = 0; m < 4; ++m) _Pragma("unroll") for (int n = 0; n < 2; ++n) _Pragma("unroll") for (int k = 0; k < 2; ++k) \
;     acc[ai][bj][m][n] = __builtin_amdgcn_mfma_f32_16x16x32_bf16(Bt[n][k], At[m][k], acc[ai][bj][m][n], 0, 0, 0); __builtin_amdgcn_s_setprio(0); } while (0)
; #define PG8_WAIT_V(n) asm volatile("s_waitcnt vmcnt(" #n ")" ::: "memory")
; #define PG8_WAIT_L(n) asm volatile("s_waitcnt lgkmcnt(" #n ")" ::: "memory")
; #define PG8_BAR __builtin_amdgcn_s_barrier()
; #define PG8_SCHED __builtin_amdgcn_sched_barrier(0)
; template <class Epi, class Sched = StaticOrder>
; DI void gemm_phase(LAS unsigned char* lds, const Gemm g, const Sched& S, const Epi& E) {
;     ...
;     for (int t = 0; t < nt; t += 2) {
;       const bool last = (t == nt - 2);
;       const char* a1 = cA + (size_t)(t + 1) * kstep;
;       const char* a2 = last ? nA : cA + (size_t)(t + 2) * kstep; const char* b2 = last ? nB : cB + (size_t)(t + 2) * kstep;
;       const char* a3 = a2 + kstep; const char* b3 = b2 + kstep;
;       PG8_LDB(B0, 0, 0); PG8_SCHED; PG8_LDA(At, 0, 0); PG8_STAGE(PG8_SA(1, 1), a1 + hstep, voffA);
;       PG8_WAIT_L(8); PG8_BAR; PG8_WAIT_L(0); PG8_MMA(0, 0, At, B0); PG8_BAR; PG8_SCHED;
;       PG8_LDB(B1, 0, 1); PG8_STAGE(PG8_SB(0, 0), b2, voffB);
;       PG8_BAR; PG8_WAIT_L(0); PG8_MMA(0, 1, At, B1); PG8_BAR;
;       PG8_LDA(At, 0, 1); PG8_STAGE(PG8_SA(0, 0), a2, voffA);
;       PG8_BAR; PG8_WAIT_L(0); PG8_MMA(1, 0, At, B0); PG8_BAR; PG8_SCHED;
;       PG8_STAGE(PG8_SB(0, 1), b2 + hstep, voffB);
;       PG8_WAIT_V(6); PG8_BAR; PG8_MMA(1, 1, At, B1); PG8_BAR;
.LBB0_961:
	ds_read_b128 v[128:131], v214
	ds_read_b128 v[132:135], v214 offset:1024
	ds_read_b128 v[136:139], v214 offset:2048
	ds_read_b128 v[140:143], v214 offset:3072
	s_add_u32 s20, s18, 0xffea0080
	s_addc_u32 s21, s19, -1
	s_cmpk_eq_i32 s44, 0x54
	s_cselect_b32 s23, s5, s21
	s_cselect_b32 s22, s4, s20
	s_cselect_b32 s21, s7, s43
	s_cselect_b32 s20, s6, s42
	ds_read_b128 v[144:147], v215
	ds_read_b128 v[148:151], v215 offset:1024
	ds_read_b128 v[152:155], v215 offset:2048
	ds_read_b128 v[156:159], v215 offset:3072
	ds_read_b128 v[160:163], v215 offset:4096
	ds_read_b128 v[164:167], v215 offset:5120
	ds_read_b128 v[168:171], v215 offset:6144
	ds_read_b128 v[172:175], v215 offset:7168
	ds_read_b128 v[192:195], v216
	ds_read_b128 v[196:199], v216 offset:1024
	ds_read_b128 v[200:203], v216 offset:2048
	ds_read_b128 v[204:207], v216 offset:3072
	s_waitcnt vmcnt(6)
	s_waitcnt lgkmcnt(4)
	s_setprio 1
	s_barrier
	v_mfma_f32_16x16x32_bf16 v[124:127], v[128:131], v[144:147], v[124:127]
	s_add_i32 m0, s31, 0xc000
	v_mfma_f32_16x16x32_bf16 v[120:123], v[136:139], v[144:147], v[120:123]
	global_load_lds_dwordx4 v184, s[18:19]
	v_mfma_f32_16x16x32_bf16 v[108:111], v[128:131], v[152:155], v[108:111]
	s_add_i32 m0, s31, 0xe000
	v_mfma_f32_16x16x32_bf16 v[104:107], v[136:139], v[152:155], v[104:107]
	global_load_lds_dwordx4 v186, s[18:19]
	v_mfma_f32_16x16x32_bf16 v[92:95], v[128:131], v[160:163], v[92:95]
	v_mfma_f32_16x16x32_bf16 v[88:91], v[136:139], v[160:163], v[88:91]
	v_mfma_f32_16x16x32_bf16 v[76:79], v[128:131], v[168:171], v[76:79]
	v_mfma_f32_16x16x32_bf16 v[72:75], v[136:139], v[168:171], v[72:75]
	v_mfma_f32_16x16x32_bf16 v[124:127], v[132:135], v[148:151], v[124:127]
	v_mfma_f32_16x16x32_bf16 v[120:123], v[140:143], v[148:151], v[120:123]
	v_mfma_f32_16x16x32_bf16 v[108:111], v[132:135], v[156:159], v[108:111]
	v_mfma_f32_16x16x32_bf16 v[104:107], v[140:143], v[156:159], v[104:107]
	v_mfma_f32_16x16x32_bf16 v[92:95], v[132:135], v[164:167], v[92:95]
	v_mfma_f32_16x16x32_bf16 v[88:91], v[140:143], v[164:167], v[88:91]
	v_mfma_f32_16x16x32_bf16 v[76:79], v[132:135], v[172:175], v[76:79]
	v_mfma_f32_16x16x32_bf16 v[72:75], v[140:143], v[172:175], v[72:75]
	s_waitcnt lgkmcnt(0)
	v_mfma_f32_16x16x32_bf16 v[116:119], v[192:195], v[144:147], v[116:119]
	v_mfma_f32_16x16x32_bf16 v[112:115], v[200:203], v[144:147], v[112:115]
	v_mfma_f32_16x16x32_bf16 v[100:103], v[192:195], v[152:155], v[100:103]
	v_mfma_f32_16x16x32_bf16 v[96:99], v[200:203], v[152:155], v[96:99]
	v_mfma_f32_16x16x32_bf16 v[84:87], v[192:195], v[160:163], v[84:87]
	v_mfma_f32_16x16x32_bf16 v[80:83], v[200:203], v[160:163], v[80:83]
	v_mfma_f32_16x16x32_bf16 v[68:71], v[192:195], v[168:171], v[68:71]
	v_mfma_f32_16x16x32_bf16 v[64:67], v[200:203], v[168:171], v[64:67]
	v_mfma_f32_16x16x32_bf16 v[116:119], v[196:199], v[148:151], v[116:119]
	v_mfma_f32_16x16x32_bf16 v[112:115], v[204:207], v[148:151], v[112:115]
	v_mfma_f32_16x16x32_bf16 v[100:103], v[196:199], v[156:159], v[100:103]
	v_mfma_f32_16x16x32_bf16 v[96:99], v[204:207], v[156:159], v[96:99]
	v_mfma_f32_16x16x32_bf16 v[84:87], v[196:199], v[164:167], v[84:87]
	v_mfma_f32_16x16x32_bf16 v[80:83], v[204:207], v[164:167], v[80:83]
	v_mfma_f32_16x16x32_bf16 v[68:71], v[196:199], v[172:175], v[68:71]
	v_mfma_f32_16x16x32_bf16 v[64:67], v[204:207], v[172:175], v[64:67]
	s_barrier
	s_setprio 0
	s_add_i32 s45, s46, s30
	s_add_u32 s98, s20, 0x80
	s_addc_u32 s99, s21, 0
	s_add_u32 s100, s22, 0x80
	s_addc_u32 s101, s23, 0
	s_mov_b32 m0, s45
	s_nop 0
	global_load_lds_dwordx4 v178, s[20:21]
	s_add_i32 m0, s45, 0x2000
	s_nop 0
	global_load_lds_dwordx4 v182, s[20:21]
	s_mov_b32 m0, s31
	ds_read_b128 v[144:147], v215 offset:16384
	ds_read_b128 v[148:151], v215 offset:17408
	ds_read_b128 v[152:155], v215 offset:18432
	ds_read_b128 v[156:159], v215 offset:19456
	ds_read_b128 v[160:163], v215 offset:20480
	ds_read_b128 v[164:167], v215 offset:21504
	ds_read_b128 v[168:171], v215 offset:22528
	ds_read_b128 v[172:175], v215 offset:23552
	global_load_lds_dwordx4 v176, s[22:23]
	s_mov_b32 m0, s33
	s_nop 0
	global_load_lds_dwordx4 v180, s[22:23]
	s_add_u32 s52, s20, 0x160000
	s_addc_u32 s53, s21, 0
	s_add_i32 s45, s47, s30
	s_waitcnt vmcnt(6)
	s_waitcnt lgkmcnt(0)
	s_setprio 1
	s_barrier
	v_mfma_f32_16x16x32_bf16 v[60:63], v[128:131], v[144:147], v[60:63]
	s_mov_b32 m0, s45
	v_mfma_f32_16x16x32_bf16 v[56:59], v[136:139], v[144:147], v[56:59]
	global_load_lds_dwordx4 v178, s[52:53]
	v_mfma_f32_16x16x32_bf16 v[44:47], v[128:131], v[152:155], v[44:47]
	s_bitset1_b32 m0, 13
	v_mfma_f32_16x16x32_bf16 v[40:43], v[136:139], v[152:155], v[40:43]
	global_load_lds_dwordx4 v182, s[52:53]
	v_mfma_f32_16x16x32_bf16 v[28:31], v[128:131], v[160:163], v[28:31]
	v_mfma_f32_16x16x32_bf16 v[24:27], v[136:139], v[160:163], v[24:27]
	v_mfma_f32_16x16x32_bf16 v[12:15], v[128:131], v[168:171], v[12:15]
	v_mfma_f32_16x16x32_bf16 v[8:11], v[136:139], v[168:171], v[8:11]
	v_mfma_f32_16x16x32_bf16 v[60:63], v[132:135], v[148:151], v[60:63]
	v_mfma_f32_16x16x32_bf16 v[56:59], v[140:143], v[148:151], v[56:59]
	v_mfma_f32_16x16x32_bf16 v[44:47], v[132:135], v[156:159], v[44:47]
	v_mfma_f32_16x16x32_bf16 v[40:43], v[140:143], v[156:159], v[40:43]
	v_mfma_f32_16x16x32_bf16 v[28:31], v[132:135], v[164:167], v[28:31]
	v_mfma_f32_16x16x32_bf16 v[24:27], v[140:143], v[164:167], v[24:27]
	v_mfma_f32_16x16x32_bf16 v[12:15], v[132:135], v[172:175], v[12:15]
	v_mfma_f32_16x16x32_bf16 v[8:11], v[140:143], v[172:175], v[8:11]
	v_mfma_f32_16x16x32_bf16 v[52:55], v[192:195], v[144:147], v[52:55]
	v_mfma_f32_16x16x32_bf16 v[48:51], v[200:203], v[144:147], v[48:51]
	v_mfma_f32_16x16x32_bf16 v[36:39], v[192:195], v[152:155], v[36:39]
	v_mfma_f32_16x16x32_bf16 v[32:35], v[200:203], v[152:155], v[32:35]
	v_mfma_f32_16x16x32_bf16 v[20:23], v[192:195], v[160:163], v[20:23]
	v_mfma_f32_16x16x32_bf16 v[16:19], v[200:203], v[160:163], v[16:19]
	v_mfma_f32_16x16x32_bf16 v[4:7], v[192:195], v[168:171], v[4:7]
	v_mfma_f32_16x16x32_bf16 v[0:3], v[200:203], v[168:171], v[0:3]
	v_mfma_f32_16x16x32_bf16 v[52:55], v[196:199], v[148:151], v[52:55]
	v_mfma_f32_16x16x32_bf16 v[48:51], v[204:207], v[148:151], v[48:51]
	v_mfma_f32_16x16x32_bf16 v[36:39], v[196:199], v[156:159], v[36:39]
	v_mfma_f32_16x16x32_bf16 v[32:35], v[204:207], v[156:159], v[32:35]
	v_mfma_f32_16x16x32_bf16 v[20:23], v[196:199], v[164:167], v[20:23]
	v_mfma_f32_16x16x32_bf16 v[16:19], v[204:207], v[164:167], v[16:19]
	v_mfma_f32_16x16x32_bf16 v[4:7], v[196:199], v[172:175], v[4:7]
	v_mfma_f32_16x16x32_bf16 v[0:3], v[204:207], v[172:175], v[0:3]
	s_barrier
; #define PG8_STAGE(bufoff, gbase, voff) do { _Pragma("unroll") for (int _i = 0; _i < 2; ++_i) \
;     __builtin_amdgcn_global_load_lds((const unsigned*)((const char*)(gbase) + (voff)[_i]), (LAS unsigned*)(lds + (bufoff) + ldsw + _i * 8192), 16, 0, 0); } while (0)
; #define PG8_LDA(dst, b, h) do { _Pragma("unroll") for (int m = 0; m < 4; ++m) _Pragma("unroll") for (int k = 0; k < 2; ++k) dst[m][k] = *(const LAS bf16x8*)(lds + PG8_SA(b, h) + aoff + m * 2048 + k * 1024); } while (0)
; #define PG8_LDB(dst, b, h) do { _Pragma("unroll") for (int n = 0; n < 2; ++n) _Pragma("unroll") for (int k = 0; k < 2; ++k) dst[n][k] = *(const LAS bf16x8*)(lds + PG8_SB(b, h) + boff + n * 2048 + k * 1024); } while (0)
; #define PG8_MMA(ai, bj, At, Bt) do { __builtin_amdgcn_s_setprio(1); _Pragma("unroll") for (int m = 0; m < 4; ++m) _Pragma("unroll") for (int n = 0; n < 2; ++n) _Pragma("unroll") for (int k = 0; k < 2; ++k) \
;     acc[ai][bj][m][n] = __builtin_amdgcn_mfma_f32_16x16x32_bf16(Bt[n][k], At[m][k], acc[ai][bj][m][n], 0, 0, 0); __builtin_amdgcn_s_setprio(0); } while (0)
; #define PG8_WAIT_V(n) asm volatile("s_waitcnt vmcnt(" #n ")" ::: "memory")
; #define PG8_WAIT_L(n) asm volatile("s_waitcnt lgkmcnt(" #n ")" ::: "memory")
; #define PG8_BAR __builtin_amdgcn_s_barrier()
; #define PG8_SCHED __builtin_amdgcn_sched_barrier(0)
; template <class Epi, class Sched = StaticOrder>
; DI void gemm_phase(LAS unsigned char* lds, const Gemm g, const Sched& S, const Epi& E) {
;     ...
;       PG8_LDB(B0, 1, 0); PG8_SCHED; PG8_LDA(At, 1, 0); PG8_STAGE(PG8_SA(0, 1), a2 + hstep, voffA);
;       PG8_WAIT_L(8); PG8_BAR; PG8_WAIT_L(0); PG8_MMA(0, 0, At, B0); PG8_BAR; PG8_SCHED;
;       PG8_LDB(B1, 1, 1); PG8_STAGE(PG8_SB(1, 0), b3, voffB);
;       PG8_BAR; PG8_WAIT_L(0); PG8_MMA(0, 1, At, B1); PG8_BAR;
;       PG8_LDA(At, 1, 1); PG8_STAGE(PG8_SA(1, 0), a3, voffA);
;       PG8_BAR; PG8_WAIT_L(0); PG8_MMA(1, 0, At, B0); PG8_BAR; PG8_SCHED;
;       PG8_STAGE(PG8_SB(1, 1), b3 + hstep, voffB);
;       PG8_WAIT_V(6); PG8_BAR; PG8_MMA(1, 1, At, B1); PG8_BAR;
;     }
	s_setprio 0
	s_add_i32 s45, 0, 0x18000
	v_add_u32_e32 v140, s45, v212
	ds_read_b128 v[128:131], v140
	ds_read_b128 v[132:135], v140 offset:1024
	ds_read_b128 v[136:139], v140 offset:2048
	ds_read_b128 v[140:143], v140 offset:3072
	s_add_u32 s22, s22, 0x160000
	s_addc_u32 s23, s23, 0
	s_mov_b32 m0, s34
	ds_read_b128 v[144:147], v215 offset:32768
	ds_read_b128 v[148:151], v215 offset:33792
	ds_read_b128 v[152:155], v215 offset:34816
	ds_read_b128 v[156:159], v215 offset:35840
	ds_read_b128 v[160:163], v215 offset:36864
	ds_read_b128 v[164:167], v215 offset:37888
	ds_read_b128 v[168:171], v215 offset:38912
	ds_read_b128 v[172:175], v215 offset:39936
	global_load_lds_dwordx4 v176, s[22:23]
	s_mov_b32 m0, s35
	s_nop 0
	global_load_lds_dwordx4 v180, s[22:23]
	s_add_i32 s22, 0, 0x1c000
	v_add_u32_e32 v204, s22, v212
	ds_read_b128 v[192:195], v204
	ds_read_b128 v[196:199], v204 offset:1024
	ds_read_b128 v[200:203], v204 offset:2048
	ds_read_b128 v[204:207], v204 offset:3072
	s_waitcnt vmcnt(8)
	s_waitcnt lgkmcnt(4)
	s_setprio 1
	s_barrier
	v_mfma_f32_16x16x32_bf16 v[124:127], v[128:131], v[144:147], v[124:127]
	v_mfma_f32_16x16x32_bf16 v[120:123], v[136:139], v[144:147], v[120:123]
	v_mfma_f32_16x16x32_bf16 v[108:111], v[128:131], v[152:155], v[108:111]
	v_mfma_f32_16x16x32_bf16 v[104:107], v[136:139], v[152:155], v[104:107]
	v_mfma_f32_16x16x32_bf16 v[92:95], v[128:131], v[160:163], v[92:95]
	v_mfma_f32_16x16x32_bf16 v[88:91], v[136:139], v[160:163], v[88:91]
	v_mfma_f32_16x16x32_bf16 v[76:79], v[128:131], v[168:171], v[76:79]
	v_mfma_f32_16x16x32_bf16 v[72:75], v[136:139], v[168:171], v[72:75]
	v_mfma_f32_16x16x32_bf16 v[124:127], v[132:135], v[148:151], v[124:127]
	v_mfma_f32_16x16x32_bf16 v[120:123], v[140:143], v[148:151], v[120:123]
	v_mfma_f32_16x16x32_bf16 v[108:111], v[132:135], v[156:159], v[108:111]
	v_mfma_f32_16x16x32_bf16 v[104:107], v[140:143], v[156:159], v[104:107]
	v_mfma_f32_16x16x32_bf16 v[92:95], v[132:135], v[164:167], v[92:95]
	v_mfma_f32_16x16x32_bf16 v[88:91], v[140:143], v[164:167], v[88:91]
	v_mfma_f32_16x16x32_bf16 v[76:79], v[132:135], v[172:175], v[76:79]
	v_mfma_f32_16x16x32_bf16 v[72:75], v[140:143], v[172:175], v[72:75]
	s_waitcnt lgkmcnt(0)
	v_mfma_f32_16x16x32_bf16 v[116:119], v[192:195], v[144:147], v[116:119]
	v_mfma_f32_16x16x32_bf16 v[112:115], v[200:203], v[144:147], v[112:115]
	v_mfma_f32_16x16x32_bf16 v[100:103], v[192:195], v[152:155], v[100:103]
	v_mfma_f32_16x16x32_bf16 v[96:99], v[200:203], v[152:155], v[96:99]
	v_mfma_f32_16x16x32_bf16 v[84:87], v[192:195], v[160:163], v[84:87]
	v_mfma_f32_16x16x32_bf16 v[80:83], v[200:203], v[160:163], v[80:83]
	v_mfma_f32_16x16x32_bf16 v[68:71], v[192:195], v[168:171], v[68:71]
	v_mfma_f32_16x16x32_bf16 v[64:67], v[200:203], v[168:171], v[64:67]
	v_mfma_f32_16x16x32_bf16 v[116:119], v[196:199], v[148:151], v[116:119]
	v_mfma_f32_16x16x32_bf16 v[112:115], v[204:207], v[148:151], v[112:115]
	v_mfma_f32_16x16x32_bf16 v[100:103], v[196:199], v[156:159], v[100:103]
	v_mfma_f32_16x16x32_bf16 v[96:99], v[204:207], v[156:159], v[96:99]
	v_mfma_f32_16x16x32_bf16 v[84:87], v[196:199], v[164:167], v[84:87]
	v_mfma_f32_16x16x32_bf16 v[80:83], v[204:207], v[164:167], v[80:83]
	v_mfma_f32_16x16x32_bf16 v[68:71], v[196:199], v[172:175], v[68:71]
	v_mfma_f32_16x16x32_bf16 v[64:67], v[204:207], v[172:175], v[64:67]
	s_barrier
	s_setprio 0
	s_add_i32 s23, s45, s30
	s_mov_b32 m0, s23
	s_nop 0
	global_load_lds_dwordx4 v178, s[98:99]
	s_add_i32 m0, s23, 0x2000
	s_nop 0
	global_load_lds_dwordx4 v182, s[98:99]
	s_mov_b32 m0, s37
	ds_read_b128 v[144:147], v215 offset:49152
	ds_read_b128 v[148:151], v215 offset:50176
	ds_read_b128 v[152:155], v215 offset:51200
	ds_read_b128 v[156:159], v215 offset:52224
	ds_read_b128 v[160:163], v215 offset:53248
	ds_read_b128 v[164:167], v215 offset:54272
	ds_read_b128 v[168:171], v215 offset:55296
	ds_read_b128 v[172:175], v215 offset:56320
	global_load_lds_dwordx4 v176, s[100:101]
	s_mov_b32 m0, s38
	s_nop 0
	global_load_lds_dwordx4 v180, s[100:101]
	s_add_u32 s20, s20, 0x160080
	s_addc_u32 s21, s21, 0
	s_add_i32 s22, s22, s30
	s_add_i32 s44, s44, 2
	s_add_u32 s18, s18, 0x100
	s_addc_u32 s19, s19, 0
	s_add_u32 s42, s42, 0x100
	s_addc_u32 s43, s43, 0
	s_cmpk_gt_u32 s44, 0x55
	s_waitcnt vmcnt(6)
	s_waitcnt lgkmcnt(0)
	s_setprio 1
	s_barrier
	v_mfma_f32_16x16x32_bf16 v[60:63], v[128:131], v[144:147], v[60:63]
	s_mov_b32 m0, s22
	v_mfma_f32_16x16x32_bf16 v[56:59], v[136:139], v[144:147], v[56:59]
	global_load_lds_dwordx4 v178, s[20:21]
	v_mfma_f32_16x16x32_bf16 v[44:47], v[128:131], v[152:155], v[44:47]
	s_bitset1_b32 m0, 13
	v_mfma_f32_16x16x32_bf16 v[40:43], v[136:139], v[152:155], v[40:43]
	global_load_lds_dwordx4 v182, s[20:21]
	v_mfma_f32_16x16x32_bf16 v[28:31], v[128:131], v[160:163], v[28:31]
	v_mfma_f32_16x16x32_bf16 v[24:27], v[136:139], v[160:163], v[24:27]
	v_mfma_f32_16x16x32_bf16 v[12:15], v[128:131], v[168:171], v[12:15]
	v_mfma_f32_16x16x32_bf16 v[8:11], v[136:139], v[168:171], v[8:11]
	v_mfma_f32_16x16x32_bf16 v[60:63], v[132:135], v[148:151], v[60:63]
	v_mfma_f32_16x16x32_bf16 v[56:59], v[140:143], v[148:151], v[56:59]
	v_mfma_f32_16x16x32_bf16 v[44:47], v[132:135], v[156:159], v[44:47]
	v_mfma_f32_16x16x32_bf16 v[40:43], v[140:143], v[156:159], v[40:43]
	v_mfma_f32_16x16x32_bf16 v[28:31], v[132:135], v[164:167], v[28:31]
	v_mfma_f32_16x16x32_bf16 v[24:27], v[140:143], v[164:167], v[24:27]
	v_mfma_f32_16x16x32_bf16 v[12:15], v[132:135], v[172:175], v[12:15]
	v_mfma_f32_16x16x32_bf16 v[8:11], v[140:143], v[172:175], v[8:11]
	v_mfma_f32_16x16x32_bf16 v[52:55], v[192:195], v[144:147], v[52:55]
	v_mfma_f32_16x16x32_bf16 v[48:51], v[200:203], v[144:147], v[48:51]
	v_mfma_f32_16x16x32_bf16 v[36:39], v[192:195], v[152:155], v[36:39]
	v_mfma_f32_16x16x32_bf16 v[32:35], v[200:203], v[152:155], v[32:35]
	v_mfma_f32_16x16x32_bf16 v[20:23], v[192:195], v[160:163], v[20:23]
	v_mfma_f32_16x16x32_bf16 v[16:19], v[200:203], v[160:163], v[16:19]
	v_mfma_f32_16x16x32_bf16 v[4:7], v[192:195], v[168:171], v[4:7]
	v_mfma_f32_16x16x32_bf16 v[0:3], v[200:203], v[168:171], v[0:3]
	v_mfma_f32_16x16x32_bf16 v[52:55], v[196:199], v[148:151], v[52:55]
	v_mfma_f32_16x16x32_bf16 v[48:51], v[204:207], v[148:151], v[48:51]
	v_mfma_f32_16x16x32_bf16 v[36:39], v[196:199], v[156:159], v[36:39]
	v_mfma_f32_16x16x32_bf16 v[32:35], v[204:207], v[156:159], v[32:35]
	v_mfma_f32_16x16x32_bf16 v[20:23], v[196:199], v[164:167], v[20:23]
	v_mfma_f32_16x16x32_bf16 v[16:19], v[204:207], v[164:167], v[16:19]
	v_mfma_f32_16x16x32_bf16 v[4:7], v[196:199], v[172:175], v[4:7]
	v_mfma_f32_16x16x32_bf16 v[0:3], v[204:207], v[172:175], v[0:3]
	s_barrier
; DI unsigned pack2(float lo, float hi) { f32x2 v = {lo, hi}; bf16v2 r = __builtin_convertvector(v, bf16v2); return __builtin_bit_cast(unsigned, r); }
;   DI void operator()(const f32x4 (&acc)[2][2][4][2], const Unit& u, int wr, int wc, int fr, int fq) const {
;     const int row0 = u.pm * BM + wr * 64 + fr, col0 = u.pn * BM + wc * 32 + 8 * fq;
; #pragma unroll
;     for (int ai = 0; ai < 2; ++ai) {
;       f32x4 bv[4][2][2];
; #pragma unroll
;       for (int m = 0; m < 4; ++m)
; #pragma unroll
;         for (int bj = 0; bj < 2; ++bj) {
;           const float* bp = base + (size_t)(row0 + ai * HALF + m * 16) * 2048 + col0 + bj * HALF;
;           bv[m][bj][0] = *(const f32x4*)bp; bv[m][bj][1] = *(const f32x4*)(bp + 4);
;         }
; #pragma unroll
;       for (int m = 0; m < 4; ++m) {
;         const int row = row0 + ai * HALF + m * 16;
;         const size_t off = (size_t)row * 2048 + col0;
;         float ss = 0.f;
; #pragma unroll
;         for (int bj = 0; bj < 2; ++bj) {
;           const f32x4 v0 = acc[ai][bj][m][0] + bv[m][bj][0], v1 = acc[ai][bj][m][1] + bv[m][bj][1];
;           *(f32x4*)(C + off + bj * HALF) = v0; *(f32x4*)(C + off + bj * HALF + 4) = v1;
;           if (xb) {
;             u32x4 w; w.x = pack2(v0[0], v0[1]); w.y = pack2(v0[2], v0[3]); w.z = pack2(v1[0], v1[1]); w.w = pack2(v1[2], v1[3]);
;             *(u32x4*)(xb + off + bj * HALF) = w;
;             ss += v0[0] * v0[0] + v0[1] * v0[1] + v0[2] * v0[2] + v0[3] * v0[3] + v1[0] * v1[0] + v1[1] * v1[1] + v1[2] * v1[2] + v1[3] * v1[3];
;           }
;         }
;         if (xb) {
;           ss += __shfl_xor(ss, 16); ss += __shfl_xor(ss, 32);
;           if (fq == 0) ssq[(size_t)row * 32 + u.pn * 4 + wc] = ss;
;         }
	s_setprio 0
	s_cbranch_scc0 .LBB0_961
	v_lshl_add_u32 v194, s51, 8, v211
	v_lshl_or_b32 v192, s2, 8, v213
	v_readlane_b32 s52, v243, 3
	v_ashrrev_i32_e32 v193, 31, v192
	v_readlane_b32 s66, v243, 17
	v_readlane_b32 s67, v243, 18
	v_ashrrev_i32_e32 v195, 31, v194
	v_lshlrev_b64 v[128:129], 13, v[194:195]
	v_lshl_add_u64 v[196:197], v[192:193], 2, s[66:67]
	v_lshl_add_u64 v[236:237], v[196:197], 0, v[128:129]
	global_load_dwordx4 v[220:223], v[236:237], off
	global_load_dwordx4 v[224:227], v[236:237], off offset:16
	global_load_dwordx4 v[228:231], v[236:237], off offset:512
	global_load_dwordx4 v[232:235], v[236:237], off offset:528
	v_or_b32_e32 v206, 16, v194
	v_or_b32_e32 v202, 32, v194
	v_or_b32_e32 v198, 48, v194
	v_ashrrev_i32_e32 v207, 31, v206
	v_ashrrev_i32_e32 v203, 31, v202
	v_ashrrev_i32_e32 v199, 31, v198
	v_lshlrev_b64 v[128:129], 13, v[206:207]
	v_lshlrev_b64 v[130:131], 13, v[202:203]
	v_lshlrev_b64 v[132:133], 13, v[198:199]
	v_lshl_add_u64 v[208:209], v[196:197], 0, v[128:129]
	v_lshl_add_u64 v[204:205], v[196:197], 0, v[130:131]
	v_lshl_add_u64 v[200:201], v[196:197], 0, v[132:133]
	global_load_dwordx4 v[168:171], v[208:209], off offset:16
	global_load_dwordx4 v[172:175], v[208:209], off
	global_load_dwordx4 v[160:163], v[208:209], off offset:528
	global_load_dwordx4 v[164:167], v[208:209], off offset:512
	global_load_dwordx4 v[152:155], v[204:205], off offset:16
	global_load_dwordx4 v[156:159], v[204:205], off
	global_load_dwordx4 v[144:147], v[204:205], off offset:528
	global_load_dwordx4 v[148:151], v[204:205], off offset:512
	global_load_dwordx4 v[136:139], v[200:201], off offset:16
	global_load_dwordx4 v[140:143], v[200:201], off
	global_load_dwordx4 v[128:131], v[200:201], off offset:528
	global_load_dwordx4 v[132:135], v[200:201], off offset:512
	v_and_b32_e32 v218, 64, v217
	v_xor_b32_e32 v238, 16, v217
	v_add_u32_e32 v240, 64, v218
	v_xor_b32_e32 v239, 32, v217
	v_cmp_lt_i32_e32 vcc, v238, v240
	v_lshlrev_b64 v[218:219], 11, v[194:195]
	s_lshl_b32 s18, s2, 2
	v_cndmask_b32_e32 v241, v217, v238, vcc
	v_cmp_lt_i32_e32 vcc, v239, v240
	s_ashr_i32 s19, s18, 31
	v_readlane_b32 s53, v243, 4
	v_cndmask_b32_e32 v240, v217, v239, vcc
	v_lshl_add_u64 v[238:239], v[218:219], 0, v[192:193]
	v_lshlrev_b32_e32 v218, 2, v241
	v_lshl_add_u64 v[238:239], v[238:239], 1, s[12:13]
	v_readlane_b32 s54, v243, 5
	v_readlane_b32 s55, v243, 6
	v_readlane_b32 s56, v243, 7
	v_readlane_b32 s57, v243, 8
	v_readlane_b32 s58, v243, 9
	v_readlane_b32 s59, v243, 10
	v_readlane_b32 s60, v243, 11
	v_readlane_b32 s61, v243, 12
	v_readlane_b32 s62, v243, 13
	v_readlane_b32 s63, v243, 14
	v_readlane_b32 s64, v243, 15
	v_readlane_b32 s65, v243, 16
	s_waitcnt vmcnt(0)
	v_pk_add_f32 v[126:127], v[126:127], v[222:223]
	v_pk_add_f32 v[124:125], v[124:125], v[220:221]
	v_pk_add_f32 v[116:117], v[116:117], v[228:229]
	v_pk_add_f32 v[122:123], v[122:123], v[226:227]
	v_pk_add_f32 v[120:121], v[120:121], v[224:225]
	v_pk_add_f32 v[220:221], v[112:113], v[232:233]
	global_store_dwordx4 v[236:237], v[124:127], off
	global_store_dwordx4 v[236:237], v[120:123], off offset:16
	v_cvt_pk_bf16_f32 v112, v124, v125
	v_mul_f32_e32 v125, v125, v125
	v_mul_f32_e32 v219, v117, v117
	v_pk_add_f32 v[118:119], v[118:119], v[230:231]
	v_fmac_f32_e32 v125, v124, v124
	v_fmac_f32_e32 v219, v116, v116
	v_fmac_f32_e32 v125, v126, v126
	v_fmac_f32_e32 v219, v118, v118
	v_fmac_f32_e32 v125, v127, v127
	v_fmac_f32_e32 v219, v119, v119
	v_fmac_f32_e32 v125, v120, v120
	v_fmac_f32_e32 v219, v220, v220
	v_pk_add_f32 v[222:223], v[114:115], v[234:235]
	v_fmac_f32_e32 v125, v121, v121
	v_fmac_f32_e32 v219, v221, v221
	v_fmac_f32_e32 v125, v122, v122
	v_fmac_f32_e32 v219, v222, v222
	v_fmac_f32_e32 v125, v123, v123
	v_fmac_f32_e32 v219, v223, v223
	v_cvt_pk_bf16_f32 v114, v120, v121
	v_add_f32_e32 v121, v125, v219
	v_cvt_pk_bf16_f32 v115, v122, v123
	ds_bpermute_b32 v122, v218, v121
	v_cvt_pk_bf16_f32 v113, v126, v127
	global_store_dwordx4 v[238:239], v[112:115], off
	global_store_dwordx4 v[236:237], v[116:119], off offset:512
	global_store_dwordx4 v[236:237], v[220:223], off offset:528
	v_lshlrev_b32_e32 v126, 2, v240
	v_cvt_pk_bf16_f32 v120, v116, v117
	s_waitcnt lgkmcnt(0)
	v_add_f32_e32 v112, v121, v122
	ds_bpermute_b32 v113, v126, v112
	v_cvt_pk_bf16_f32 v121, v118, v119
	v_cvt_pk_bf16_f32 v122, v220, v221
	v_cvt_pk_bf16_f32 v123, v222, v223
	global_store_dwordx4 v[238:239], v[120:123], off offset:256
	s_and_saveexec_b64 s[20:21], s[0:1]
	s_cbranch_execz .LBB0_964
	s_waitcnt lgkmcnt(0)
	v_add_f32_e32 v114, v112, v113
	v_lshlrev_b64 v[112:113], 7, v[194:195]
	v_lshl_add_u64 v[112:113], s[14:15], 0, v[112:113]
	v_lshl_add_u64 v[112:113], s[18:19], 2, v[112:113]
	s_lshl_b32 s2, s36, 2
	v_lshl_add_u64 v[112:113], v[112:113], 0, s[2:3]
	global_store_dword v[112:113], v114, off

; #define PG8_STAGE(bufoff, gbase, voff) do { _Pragma("unroll") for (int _i = 0; _i < 2; ++_i) \
;     __builtin_amdgcn_global_load_lds((const unsigned*)((const char*)(gbase) + (voff)[_i]), (LAS unsigned*)(lds + (bufoff) + ldsw + _i * 8192), 16, 0, 0); } while (0)
; #define PG8_LDA(dst, b, h) do { _Pragma("unroll") for (int m = 0; m < 4; ++m) _Pragma("unroll") for (int k = 0; k < 2; ++k) dst[m][k] = *(const LAS bf16x8*)(lds + PG8_SA(b, h) + aoff + m * 2048 + k * 1024); } while (0)
; #define PG8_LDB(dst, b, h) do { _Pragma("unroll") for (int n = 0; n < 2; ++n) _Pragma("unroll") for (int k = 0; k < 2; ++k) dst[n][k] = *(const LAS bf16x8*)(lds + PG8_SB(b, h) + boff + n * 2048 + k * 1024); } while (0)
; #define PG8_MMA(ai, bj, At, Bt) do { __builtin_amdgcn_s_setprio(1); _Pragma("unroll") for (int m = 0; m < 4; ++m) _Pragma("unroll") for (int n = 0; n < 2; ++n) _Pragma("unroll") for (int k = 0; k < 2; ++k) \
;     acc[ai][bj][m][n] = __builtin_amdgcn_mfma_f32_16x16x32_bf16(Bt[n][k], At[m][k], acc[ai][bj][m][n], 0, 0, 0); __builtin_amdgcn_s_setprio(0); } while (0)
; #define PG8_WAIT_V(n) asm volatile("s_waitcnt vmcnt(" #n ")" ::: "memory")
; #define PG8_WAIT_L(n) asm volatile("s_waitcnt lgkmcnt(" #n ")" ::: "memory")
; #define PG8_BAR __builtin_amdgcn_s_barrier()
; #define PG8_SCHED __builtin_amdgcn_sched_barrier(0)
; template <class Epi, class Sched = StaticOrder>
; DI void gemm_phase(LAS unsigned char* lds, const Gemm g, const Sched& S, const Epi& E) {
;     ...
;     for (int t = 0; t < nt; t += 2) {
;       const bool last = (t == nt - 2);
;       const char* a1 = cA + (size_t)(t + 1) * kstep;
;       const char* a2 = last ? nA : cA + (size_t)(t + 2) * kstep; const char* b2 = last ? nB : cB + (size_t)(t + 2) * kstep;
;       const char* a3 = a2 + kstep; const char* b3 = b2 + kstep;
;       PG8_LDB(B0, 0, 0); PG8_SCHED; PG8_LDA(At, 0, 0); PG8_STAGE(PG8_SA(1, 1), a1 + hstep, voffA);
;       PG8_WAIT_L(8); PG8_BAR; PG8_WAIT_L(0); PG8_MMA(0, 0, At, B0); PG8_BAR; PG8_SCHED;
;       PG8_LDB(B1, 0, 1); PG8_STAGE(PG8_SB(0, 0), b2, voffB);
;       PG8_BAR; PG8_WAIT_L(0); PG8_MMA(0, 1, At, B1); PG8_BAR;
;       PG8_LDA(At, 0, 1); PG8_STAGE(PG8_SA(0, 0), a2, voffA);
;       PG8_BAR; PG8_WAIT_L(0); PG8_MMA(1, 0, At, B0); PG8_BAR; PG8_SCHED;
;       PG8_STAGE(PG8_SB(0, 1), b2 + hstep, voffB);
;       PG8_WAIT_V(6); PG8_BAR; PG8_MMA(1, 1, At, B1); PG8_BAR;
.LBB0_1052:
	ds_read_b128 v[128:131], v203
	ds_read_b128 v[132:135], v203 offset:1024
	ds_read_b128 v[136:139], v203 offset:2048
	ds_read_b128 v[140:143], v203 offset:3072
	s_add_u32 s12, s10, 0xfff80080
	s_addc_u32 s13, s11, -1
	s_cmp_eq_u32 s52, 28
	s_cselect_b32 s65, s41, s13
	s_cselect_b32 s64, s42, s12
	s_cselect_b32 s13, s43, s49
	s_cselect_b32 s12, s44, s45
	ds_read_b128 v[144:147], v204
	ds_read_b128 v[148:151], v204 offset:1024
	ds_read_b128 v[152:155], v204 offset:2048
	ds_read_b128 v[156:159], v204 offset:3072
	ds_read_b128 v[178:181], v204 offset:4096
	ds_read_b128 v[182:185], v204 offset:5120
	ds_read_b128 v[186:189], v204 offset:6144
	ds_read_b128 v[190:193], v204 offset:7168
	ds_read_b128 v[194:197], v205
	ds_read_b128 v[212:215], v205 offset:1024
	ds_read_b128 v[216:219], v205 offset:2048
	ds_read_b128 v[220:223], v205 offset:3072
	s_waitcnt vmcnt(6)
	s_waitcnt lgkmcnt(4)
	s_setprio 1
	s_barrier
	v_mfma_f32_16x16x32_bf16 v[124:127], v[128:131], v[144:147], v[124:127]
	s_add_i32 m0, s61, 0xc000
	v_mfma_f32_16x16x32_bf16 v[120:123], v[136:139], v[144:147], v[120:123]
	global_load_lds_dwordx4 v172, s[10:11]
	v_mfma_f32_16x16x32_bf16 v[116:119], v[128:131], v[152:155], v[116:119]
	s_add_i32 m0, s61, 0xe000
	v_mfma_f32_16x16x32_bf16 v[104:107], v[136:139], v[152:155], v[104:107]
	global_load_lds_dwordx4 v174, s[10:11]
	v_mfma_f32_16x16x32_bf16 v[92:95], v[128:131], v[178:181], v[92:95]
	v_mfma_f32_16x16x32_bf16 v[88:91], v[136:139], v[178:181], v[88:91]
	v_mfma_f32_16x16x32_bf16 v[84:87], v[128:131], v[186:189], v[84:87]
	v_mfma_f32_16x16x32_bf16 v[72:75], v[136:139], v[186:189], v[72:75]
	v_mfma_f32_16x16x32_bf16 v[124:127], v[132:135], v[148:151], v[124:127]
	v_mfma_f32_16x16x32_bf16 v[120:123], v[140:143], v[148:151], v[120:123]
	v_mfma_f32_16x16x32_bf16 v[116:119], v[132:135], v[156:159], v[116:119]
	v_mfma_f32_16x16x32_bf16 v[104:107], v[140:143], v[156:159], v[104:107]
	v_mfma_f32_16x16x32_bf16 v[92:95], v[132:135], v[182:185], v[92:95]
	v_mfma_f32_16x16x32_bf16 v[88:91], v[140:143], v[182:185], v[88:91]
	v_mfma_f32_16x16x32_bf16 v[84:87], v[132:135], v[190:193], v[84:87]
	v_mfma_f32_16x16x32_bf16 v[72:75], v[140:143], v[190:193], v[72:75]
	s_waitcnt lgkmcnt(0)
	v_mfma_f32_16x16x32_bf16 v[112:115], v[194:197], v[144:147], v[112:115]
	v_mfma_f32_16x16x32_bf16 v[108:111], v[216:219], v[144:147], v[108:111]
	v_mfma_f32_16x16x32_bf16 v[100:103], v[194:197], v[152:155], v[100:103]
	v_mfma_f32_16x16x32_bf16 v[96:99], v[216:219], v[152:155], v[96:99]
	v_mfma_f32_16x16x32_bf16 v[80:83], v[194:197], v[178:181], v[80:83]
	v_mfma_f32_16x16x32_bf16 v[76:79], v[216:219], v[178:181], v[76:79]
	v_mfma_f32_16x16x32_bf16 v[68:71], v[194:197], v[186:189], v[68:71]
	v_mfma_f32_16x16x32_bf16 v[64:67], v[216:219], v[186:189], v[64:67]
	v_mfma_f32_16x16x32_bf16 v[112:115], v[212:215], v[148:151], v[112:115]
	v_mfma_f32_16x16x32_bf16 v[108:111], v[220:223], v[148:151], v[108:111]
	v_mfma_f32_16x16x32_bf16 v[100:103], v[212:215], v[156:159], v[100:103]
	v_mfma_f32_16x16x32_bf16 v[96:99], v[220:223], v[156:159], v[96:99]
	v_mfma_f32_16x16x32_bf16 v[80:83], v[212:215], v[182:185], v[80:83]
	v_mfma_f32_16x16x32_bf16 v[76:79], v[220:223], v[182:185], v[76:79]
	v_mfma_f32_16x16x32_bf16 v[68:71], v[212:215], v[190:193], v[68:71]
	v_mfma_f32_16x16x32_bf16 v[64:67], v[220:223], v[190:193], v[64:67]
	s_barrier
	s_setprio 0
	s_add_i32 s53, s80, s70
	s_add_u32 s98, s12, 0x80
	s_addc_u32 s99, s13, 0
	s_add_u32 s100, s64, 0x80
	s_addc_u32 s101, s65, 0
	s_mov_b32 m0, s53
	s_nop 0
	global_load_lds_dwordx4 v162, s[12:13]
	s_add_i32 m0, s53, 0x2000
	s_nop 0
	global_load_lds_dwordx4 v166, s[12:13]
	s_mov_b32 m0, s61
	ds_read_b128 v[144:147], v204 offset:16384
	ds_read_b128 v[148:151], v204 offset:17408
	ds_read_b128 v[152:155], v204 offset:18432
	ds_read_b128 v[156:159], v204 offset:19456
	ds_read_b128 v[178:181], v204 offset:20480
	ds_read_b128 v[182:185], v204 offset:21504
	ds_read_b128 v[186:189], v204 offset:22528
	ds_read_b128 v[190:193], v204 offset:23552
	global_load_lds_dwordx4 v160, s[64:65]
	s_mov_b32 m0, s63
	s_nop 0
	global_load_lds_dwordx4 v164, s[64:65]
	s_add_u32 s54, s12, 0x80000
	s_addc_u32 s55, s13, 0
	s_add_i32 s53, s81, s70
	s_waitcnt vmcnt(6)
	s_waitcnt lgkmcnt(0)
	s_setprio 1
	s_barrier
	v_mfma_f32_16x16x32_bf16 v[60:63], v[128:131], v[144:147], v[60:63]
	s_mov_b32 m0, s53
	v_mfma_f32_16x16x32_bf16 v[56:59], v[136:139], v[144:147], v[56:59]
	global_load_lds_dwordx4 v162, s[54:55]
	v_mfma_f32_16x16x32_bf16 v[48:51], v[128:131], v[152:155], v[48:51]
	s_bitset1_b32 m0, 13
	v_mfma_f32_16x16x32_bf16 v[40:43], v[136:139], v[152:155], v[40:43]
	global_load_lds_dwordx4 v166, s[54:55]
	v_mfma_f32_16x16x32_bf16 v[28:31], v[128:131], v[178:181], v[28:31]
	v_mfma_f32_16x16x32_bf16 v[24:27], v[136:139], v[178:181], v[24:27]
	v_mfma_f32_16x16x32_bf16 v[12:15], v[128:131], v[186:189], v[12:15]
	v_mfma_f32_16x16x32_bf16 v[8:11], v[136:139], v[186:189], v[8:11]
	v_mfma_f32_16x16x32_bf16 v[60:63], v[132:135], v[148:151], v[60:63]
	v_mfma_f32_16x16x32_bf16 v[56:59], v[140:143], v[148:151], v[56:59]
	v_mfma_f32_16x16x32_bf16 v[48:51], v[132:135], v[156:159], v[48:51]
	v_mfma_f32_16x16x32_bf16 v[40:43], v[140:143], v[156:159], v[40:43]
	v_mfma_f32_16x16x32_bf16 v[28:31], v[132:135], v[182:185], v[28:31]
	v_mfma_f32_16x16x32_bf16 v[24:27], v[140:143], v[182:185], v[24:27]
	v_mfma_f32_16x16x32_bf16 v[12:15], v[132:135], v[190:193], v[12:15]
	v_mfma_f32_16x16x32_bf16 v[8:11], v[140:143], v[190:193], v[8:11]
	v_mfma_f32_16x16x32_bf16 v[52:55], v[194:197], v[144:147], v[52:55]
	v_mfma_f32_16x16x32_bf16 v[44:47], v[216:219], v[144:147], v[44:47]
	v_mfma_f32_16x16x32_bf16 v[36:39], v[194:197], v[152:155], v[36:39]
	v_mfma_f32_16x16x32_bf16 v[32:35], v[216:219], v[152:155], v[32:35]
	v_mfma_f32_16x16x32_bf16 v[20:23], v[194:197], v[178:181], v[20:23]
	v_mfma_f32_16x16x32_bf16 v[16:19], v[216:219], v[178:181], v[16:19]
	v_mfma_f32_16x16x32_bf16 v[4:7], v[194:197], v[186:189], v[4:7]
	v_mfma_f32_16x16x32_bf16 v[0:3], v[216:219], v[186:189], v[0:3]
	v_mfma_f32_16x16x32_bf16 v[52:55], v[212:215], v[148:151], v[52:55]
	v_mfma_f32_16x16x32_bf16 v[44:47], v[220:223], v[148:151], v[44:47]
	v_mfma_f32_16x16x32_bf16 v[36:39], v[212:215], v[156:159], v[36:39]
	v_mfma_f32_16x16x32_bf16 v[32:35], v[220:223], v[156:159], v[32:35]
	v_mfma_f32_16x16x32_bf16 v[20:23], v[212:215], v[182:185], v[20:23]
	v_mfma_f32_16x16x32_bf16 v[16:19], v[220:223], v[182:185], v[16:19]
	v_mfma_f32_16x16x32_bf16 v[4:7], v[212:215], v[190:193], v[4:7]
	v_mfma_f32_16x16x32_bf16 v[0:3], v[220:223], v[190:193], v[0:3]
	s_barrier
; #define PG8_STAGE(bufoff, gbase, voff) do { _Pragma("unroll") for (int _i = 0; _i < 2; ++_i) \
;     __builtin_amdgcn_global_load_lds((const unsigned*)((const char*)(gbase) + (voff)[_i]), (LAS unsigned*)(lds + (bufoff) + ldsw + _i * 8192), 16, 0, 0); } while (0)
; #define PG8_LDA(dst, b, h) do { _Pragma("unroll") for (int m = 0; m < 4; ++m) _Pragma("unroll") for (int k = 0; k < 2; ++k) dst[m][k] = *(const LAS bf16x8*)(lds + PG8_SA(b, h) + aoff + m * 2048 + k * 1024); } while (0)
; #define PG8_LDB(dst, b, h) do { _Pragma("unroll") for (int n = 0; n < 2; ++n) _Pragma("unroll") for (int k = 0; k < 2; ++k) dst[n][k] = *(const LAS bf16x8*)(lds + PG8_SB(b, h) + boff + n * 2048 + k * 1024); } while (0)
; #define PG8_MMA(ai, bj, At, Bt) do { __builtin_amdgcn_s_setprio(1); _Pragma("unroll") for (int m = 0; m < 4; ++m) _Pragma("unroll") for (int n = 0; n < 2; ++n) _Pragma("unroll") for (int k = 0; k < 2; ++k) \
;     acc[ai][bj][m][n] = __builtin_amdgcn_mfma_f32_16x16x32_bf16(Bt[n][k], At[m][k], acc[ai][bj][m][n], 0, 0, 0); __builtin_amdgcn_s_setprio(0); } while (0)
; #define PG8_WAIT_V(n) asm volatile("s_waitcnt vmcnt(" #n ")" ::: "memory")
; #define PG8_WAIT_L(n) asm volatile("s_waitcnt lgkmcnt(" #n ")" ::: "memory")
; #define PG8_BAR __builtin_amdgcn_s_barrier()
; #define PG8_SCHED __builtin_amdgcn_sched_barrier(0)
; template <class Epi, class Sched = StaticOrder>
; DI void gemm_phase(LAS unsigned char* lds, const Gemm g, const Sched& S, const Epi& E) {
;     ...
;       PG8_LDB(B0, 1, 0); PG8_SCHED; PG8_LDA(At, 1, 0); PG8_STAGE(PG8_SA(0, 1), a2 + hstep, voffA);
;       PG8_WAIT_L(8); PG8_BAR; PG8_WAIT_L(0); PG8_MMA(0, 0, At, B0); PG8_BAR; PG8_SCHED;
;       PG8_LDB(B1, 1, 1); PG8_STAGE(PG8_SB(1, 0), b3, voffB);
;       PG8_BAR; PG8_WAIT_L(0); PG8_MMA(0, 1, At, B1); PG8_BAR;
;       PG8_LDA(At, 1, 1); PG8_STAGE(PG8_SA(1, 0), a3, voffA);
;       PG8_BAR; PG8_WAIT_L(0); PG8_MMA(1, 0, At, B0); PG8_BAR; PG8_SCHED;
;       PG8_STAGE(PG8_SB(1, 1), b3 + hstep, voffB);
;       PG8_WAIT_V(6); PG8_BAR; PG8_MMA(1, 1, At, B1); PG8_BAR;
;     }
	s_setprio 0
	s_add_i32 s53, 0, 0x18000
	v_add_u32_e32 v140, s53, v199
	ds_read_b128 v[128:131], v140
	ds_read_b128 v[132:135], v140 offset:1024
	ds_read_b128 v[136:139], v140 offset:2048
	ds_read_b128 v[140:143], v140 offset:3072
	s_add_u32 s54, s64, 0x80000
	s_addc_u32 s55, s65, 0
	s_mov_b32 m0, s71
	ds_read_b128 v[144:147], v204 offset:32768
	ds_read_b128 v[148:151], v204 offset:33792
	ds_read_b128 v[152:155], v204 offset:34816
	ds_read_b128 v[156:159], v204 offset:35840
	ds_read_b128 v[178:181], v204 offset:36864
	ds_read_b128 v[182:185], v204 offset:37888
	ds_read_b128 v[186:189], v204 offset:38912
	ds_read_b128 v[190:193], v204 offset:39936
	global_load_lds_dwordx4 v160, s[54:55]
	s_mov_b32 m0, s72
	s_nop 0
	global_load_lds_dwordx4 v164, s[54:55]
	s_add_i32 s54, 0, 0x1c000
	v_add_u32_e32 v168, s54, v199
	ds_read_b128 v[194:197], v168
	ds_read_b128 v[212:215], v168 offset:1024
	ds_read_b128 v[216:219], v168 offset:2048
	ds_read_b128 v[220:223], v168 offset:3072
	s_waitcnt vmcnt(8)
	s_waitcnt lgkmcnt(4)
	s_setprio 1
	s_barrier
	v_mfma_f32_16x16x32_bf16 v[124:127], v[128:131], v[144:147], v[124:127]
	v_mfma_f32_16x16x32_bf16 v[120:123], v[136:139], v[144:147], v[120:123]
	v_mfma_f32_16x16x32_bf16 v[116:119], v[128:131], v[152:155], v[116:119]
	v_mfma_f32_16x16x32_bf16 v[104:107], v[136:139], v[152:155], v[104:107]
	v_mfma_f32_16x16x32_bf16 v[92:95], v[128:131], v[178:181], v[92:95]
	v_mfma_f32_16x16x32_bf16 v[88:91], v[136:139], v[178:181], v[88:91]
	v_mfma_f32_16x16x32_bf16 v[84:87], v[128:131], v[186:189], v[84:87]
	v_mfma_f32_16x16x32_bf16 v[72:75], v[136:139], v[186:189], v[72:75]
	v_mfma_f32_16x16x32_bf16 v[124:127], v[132:135], v[148:151], v[124:127]
	v_mfma_f32_16x16x32_bf16 v[120:123], v[140:143], v[148:151], v[120:123]
	v_mfma_f32_16x16x32_bf16 v[116:119], v[132:135], v[156:159], v[116:119]
	v_mfma_f32_16x16x32_bf16 v[104:107], v[140:143], v[156:159], v[104:107]
	v_mfma_f32_16x16x32_bf16 v[92:95], v[132:135], v[182:185], v[92:95]
	v_mfma_f32_16x16x32_bf16 v[88:91], v[140:143], v[182:185], v[88:91]
	v_mfma_f32_16x16x32_bf16 v[84:87], v[132:135], v[190:193], v[84:87]
	v_mfma_f32_16x16x32_bf16 v[72:75], v[140:143], v[190:193], v[72:75]
	s_waitcnt lgkmcnt(0)
	v_mfma_f32_16x16x32_bf16 v[112:115], v[194:197], v[144:147], v[112:115]
	v_mfma_f32_16x16x32_bf16 v[108:111], v[216:219], v[144:147], v[108:111]
	v_mfma_f32_16x16x32_bf16 v[100:103], v[194:197], v[152:155], v[100:103]
	v_mfma_f32_16x16x32_bf16 v[96:99], v[216:219], v[152:155], v[96:99]
	v_mfma_f32_16x16x32_bf16 v[80:83], v[194:197], v[178:181], v[80:83]
	v_mfma_f32_16x16x32_bf16 v[76:79], v[216:219], v[178:181], v[76:79]
	v_mfma_f32_16x16x32_bf16 v[68:71], v[194:197], v[186:189], v[68:71]
	v_mfma_f32_16x16x32_bf16 v[64:67], v[216:219], v[186:189], v[64:67]
	v_mfma_f32_16x16x32_bf16 v[112:115], v[212:215], v[148:151], v[112:115]
	v_mfma_f32_16x16x32_bf16 v[108:111], v[220:223], v[148:151], v[108:111]
	v_mfma_f32_16x16x32_bf16 v[100:103], v[212:215], v[156:159], v[100:103]
	v_mfma_f32_16x16x32_bf16 v[96:99], v[220:223], v[156:159], v[96:99]
	v_mfma_f32_16x16x32_bf16 v[80:83], v[212:215], v[182:185], v[80:83]
	v_mfma_f32_16x16x32_bf16 v[76:79], v[220:223], v[182:185], v[76:79]
	v_mfma_f32_16x16x32_bf16 v[68:71], v[212:215], v[190:193], v[68:71]
	v_mfma_f32_16x16x32_bf16 v[64:67], v[220:223], v[190:193], v[64:67]
	s_barrier
	s_setprio 0
	s_add_i32 s53, s53, s70
	s_mov_b32 m0, s53
	s_nop 0
	global_load_lds_dwordx4 v162, s[98:99]
	s_add_i32 m0, s53, 0x2000
	s_nop 0
	global_load_lds_dwordx4 v166, s[98:99]
	s_mov_b32 m0, s76
	ds_read_b128 v[144:147], v204 offset:49152
	ds_read_b128 v[148:151], v204 offset:50176
	ds_read_b128 v[152:155], v204 offset:51200
	ds_read_b128 v[156:159], v204 offset:52224
	ds_read_b128 v[178:181], v204 offset:53248
	ds_read_b128 v[182:185], v204 offset:54272
	ds_read_b128 v[186:189], v204 offset:55296
	ds_read_b128 v[190:193], v204 offset:56320
	global_load_lds_dwordx4 v160, s[100:101]
	s_mov_b32 m0, s77
	s_nop 0
	global_load_lds_dwordx4 v164, s[100:101]
	s_add_u32 s12, s12, 0x80080
	s_addc_u32 s13, s13, 0
	s_add_i32 s53, s54, s70
	s_add_i32 s52, s52, 2
	s_add_u32 s10, s10, 0x100
	s_addc_u32 s11, s11, 0
	s_add_u32 s45, s45, 0x100
	s_addc_u32 s49, s49, 0
	s_cmp_gt_u32 s52, 29
	s_waitcnt vmcnt(6)
	s_waitcnt lgkmcnt(0)
	s_setprio 1
	s_barrier
	v_mfma_f32_16x16x32_bf16 v[60:63], v[128:131], v[144:147], v[60:63]
	s_mov_b32 m0, s53
	v_mfma_f32_16x16x32_bf16 v[56:59], v[136:139], v[144:147], v[56:59]
	global_load_lds_dwordx4 v162, s[12:13]
	v_mfma_f32_16x16x32_bf16 v[48:51], v[128:131], v[152:155], v[48:51]
	s_bitset1_b32 m0, 13
	v_mfma_f32_16x16x32_bf16 v[40:43], v[136:139], v[152:155], v[40:43]
	global_load_lds_dwordx4 v166, s[12:13]
	v_mfma_f32_16x16x32_bf16 v[28:31], v[128:131], v[178:181], v[28:31]
	v_mfma_f32_16x16x32_bf16 v[24:27], v[136:139], v[178:181], v[24:27]
	v_mfma_f32_16x16x32_bf16 v[12:15], v[128:131], v[186:189], v[12:15]
	v_mfma_f32_16x16x32_bf16 v[8:11], v[136:139], v[186:189], v[8:11]
	v_mfma_f32_16x16x32_bf16 v[60:63], v[132:135], v[148:151], v[60:63]
	v_mfma_f32_16x16x32_bf16 v[56:59], v[140:143], v[148:151], v[56:59]
	v_mfma_f32_16x16x32_bf16 v[48:51], v[132:135], v[156:159], v[48:51]
	v_mfma_f32_16x16x32_bf16 v[40:43], v[140:143], v[156:159], v[40:43]
	v_mfma_f32_16x16x32_bf16 v[28:31], v[132:135], v[182:185], v[28:31]
	v_mfma_f32_16x16x32_bf16 v[24:27], v[140:143], v[182:185], v[24:27]
	v_mfma_f32_16x16x32_bf16 v[12:15], v[132:135], v[190:193], v[12:15]
	v_mfma_f32_16x16x32_bf16 v[8:11], v[140:143], v[190:193], v[8:11]
	v_mfma_f32_16x16x32_bf16 v[52:55], v[194:197], v[144:147], v[52:55]
	v_mfma_f32_16x16x32_bf16 v[44:47], v[216:219], v[144:147], v[44:47]
	v_mfma_f32_16x16x32_bf16 v[36:39], v[194:197], v[152:155], v[36:39]
	v_mfma_f32_16x16x32_bf16 v[32:35], v[216:219], v[152:155], v[32:35]
	v_mfma_f32_16x16x32_bf16 v[20:23], v[194:197], v[178:181], v[20:23]
	v_mfma_f32_16x16x32_bf16 v[16:19], v[216:219], v[178:181], v[16:19]
	v_mfma_f32_16x16x32_bf16 v[4:7], v[194:197], v[186:189], v[4:7]
	v_mfma_f32_16x16x32_bf16 v[0:3], v[216:219], v[186:189], v[0:3]
	v_mfma_f32_16x16x32_bf16 v[52:55], v[212:215], v[148:151], v[52:55]
	v_mfma_f32_16x16x32_bf16 v[44:47], v[220:223], v[148:151], v[44:47]
	v_mfma_f32_16x16x32_bf16 v[36:39], v[212:215], v[156:159], v[36:39]
	v_mfma_f32_16x16x32_bf16 v[32:35], v[220:223], v[156:159], v[32:35]
	v_mfma_f32_16x16x32_bf16 v[20:23], v[212:215], v[182:185], v[20:23]
	v_mfma_f32_16x16x32_bf16 v[16:19], v[220:223], v[182:185], v[16:19]
	v_mfma_f32_16x16x32_bf16 v[4:7], v[212:215], v[190:193], v[4:7]
	v_mfma_f32_16x16x32_bf16 v[0:3], v[220:223], v[190:193], v[0:3]
	s_barrier
; DI float row_rstd(const float* ssq, int row, int fq) {
;   const f32x4 a = *(const f32x4*)(ssq + (size_t)row * 32 + fq * 8), b = *(const f32x4*)(ssq + (size_t)row * 32 + fq * 8 + 4);
;   float sm = ((a[0] + a[1]) + (a[2] + a[3])) + ((b[0] + b[1]) + (b[2] + b[3]));
;   sm += __shfl_xor(sm, 16); sm += __shfl_xor(sm, 32);
;   return rsqrtf(sm * (1.0f / 2048.f) + 1e-6f);
; }
;   DI void operator()(const f32x4 (&acc)[2][2][4][2], const Unit& u, int wr, int wc, int fr, int fq) const {
;     ...
;     const int col = u.pn * 128 + wc * 32 + 8 * fq;
;     float w0[8], w1[8], w2[8];
; #pragma unroll
;     for (int e = 0; e < 8; ++e) { w0[e] = cw[col + e]; w1[e] = cw[2048 + col + e]; w2[e] = cw[4096 + col + e]; }
; #pragma unroll
;     for (int ai = 0; ai < 2; ++ai) {
;       const int row0 = u.pm * BM + ai * HALF + wr * 64, span = row0 >> 6;
;       float rsv[4];
; #pragma unroll
;       for (int m = 0; m < 4; ++m) rsv[m] = row_rstd(ssq, row0 + 16 * m + fr, fq);
	s_setprio 0
	s_cbranch_scc0 .LBB0_1052
	s_cmp_lt_i32 s62, 16
	s_mov_b64 s[10:11], -1
	s_cbranch_scc0 .LBB0_1067
	s_lshl_b32 s41, s60, 8
	s_add_i32 s41, s41, s75
	v_or_b32_e32 v186, s41, v177
	v_ashrrev_i32_e32 v187, 31, v186
	v_lshlrev_b64 v[128:129], 7, v[186:187]
	v_or_b32_e32 v180, 16, v186
	v_lshl_add_u64 v[128:129], v[170:171], 0, v[128:129]
	v_ashrrev_i32_e32 v181, 31, v180
	global_load_dwordx4 v[152:155], v[128:129], off
	global_load_dwordx4 v[156:159], v[128:129], off offset:16
	v_lshlrev_b64 v[128:129], 7, v[180:181]
	v_lshl_add_u64 v[128:129], v[170:171], 0, v[128:129]
	global_load_dwordx4 v[188:191], v[128:129], off
	global_load_dwordx4 v[192:195], v[128:129], off offset:16
	v_or_b32_e32 v184, 32, v186
	v_ashrrev_i32_e32 v185, 31, v184
	v_lshlrev_b64 v[128:129], 7, v[184:185]
	v_or_b32_e32 v182, 48, v186
	v_lshl_add_u64 v[128:129], v[170:171], 0, v[128:129]
	v_ashrrev_i32_e32 v183, 31, v182
	global_load_dwordx4 v[212:215], v[128:129], off
	global_load_dwordx4 v[216:219], v[128:129], off offset:16
	v_lshlrev_b64 v[128:129], 7, v[182:183]
	v_lshl_add_u64 v[128:129], v[170:171], 0, v[128:129]
	global_load_dwordx4 v[220:223], v[128:129], off
	global_load_dwordx4 v[224:227], v[128:129], off offset:16
	v_and_b32_e32 v129, 64, v206
	v_lshl_or_b32 v178, s62, 7, v200
	v_xor_b32_e32 v128, 16, v206
	v_add_u32_e32 v129, 64, v129
	v_readlane_b32 s44, v243, 3
	v_xor_b32_e32 v130, 32, v206
	v_ashrrev_i32_e32 v179, 31, v178
	v_readlane_b32 s45, v243, 4
	v_cmp_lt_i32_e32 vcc, v128, v129
	s_movk_i32 s10, 0x2000
	v_lshl_add_u64 v[144:145], v[178:179], 2, s[44:45]
	v_cndmask_b32_e32 v134, v206, v128, vcc
	v_cmp_lt_i32_e32 vcc, v130, v129
	v_lshl_add_u64 v[132:133], v[144:145], 0, s[26:27]
	v_lshl_add_u64 v[136:137], v[144:145], 0, s[28:29]
	v_cndmask_b32_e32 v135, v206, v130, vcc
	v_add_co_u32_e32 v146, vcc, s10, v144
	global_load_dwordx4 v[128:131], v[144:145], off offset:16
	global_load_dwordx4 v[140:143], v[144:145], off
	v_addc_co_u32_e32 v147, vcc, 0, v145, vcc
	v_add_co_u32_e32 v148, vcc, s74, v144
	v_lshlrev_b32_e32 v196, 2, v134
	s_nop 0
	v_addc_co_u32_e32 v149, vcc, 0, v145, vcc
	v_lshlrev_b32_e32 v207, 2, v135
	global_load_dwordx4 v[132:135], v[132:133], off offset:16
	s_nop 0
	global_load_dwordx4 v[136:139], v[136:137], off offset:16
	s_nop 0
	global_load_dwordx4 v[144:147], v[146:147], off
	s_nop 0
	global_load_dwordx4 v[148:151], v[148:149], off
	v_mov_b32_e32 v197, 0
	v_mov_b32_e32 v211, 0
	v_readlane_b32 s46, v243, 5
	v_readlane_b32 s47, v243, 6
	v_readlane_b32 s48, v243, 7
	v_readlane_b32 s49, v243, 8
	v_readlane_b32 s50, v243, 9
	v_readlane_b32 s51, v243, 10
	v_readlane_b32 s52, v243, 11
	v_readlane_b32 s53, v243, 12
	v_readlane_b32 s54, v243, 13
	v_readlane_b32 s55, v243, 14
	v_readlane_b32 s56, v243, 15
	v_readlane_b32 s57, v243, 16
	v_readlane_b32 s58, v243, 17
	v_readlane_b32 s59, v243, 18
	s_waitcnt vmcnt(0)
	v_mov_b32_e32 v208, v152
	v_mov_b32_e32 v209, v156
	v_mov_b32_e32 v156, v153
	v_mov_b32_e32 v152, v154
	v_mov_b32_e32 v153, v158
	v_mov_b32_e32 v158, v155
	v_pk_add_f32 v[154:155], v[208:209], v[156:157]
	v_pk_add_f32 v[152:153], v[152:153], v[158:159]
	v_mov_b32_e32 v156, v188
	v_mov_b32_e32 v157, v192
	v_mov_b32_e32 v192, v189
	v_mov_b32_e32 v158, v190
	v_mov_b32_e32 v159, v194
	v_mov_b32_e32 v194, v191
	v_pk_add_f32 v[152:153], v[154:155], v[152:153]
	v_pk_add_f32 v[154:155], v[156:157], v[192:193]
	v_pk_add_f32 v[156:157], v[158:159], v[194:195]
	v_mov_b32_e32 v188, v212
	v_pk_add_f32 v[154:155], v[154:155], v[156:157]
	v_mov_b32_e32 v157, v152
	v_mov_b32_e32 v156, v154
	v_mov_b32_e32 v152, v155
	v_pk_add_f32 v[152:153], v[156:157], v[152:153]
	ds_bpermute_b32 v155, v196, v153
	ds_bpermute_b32 v154, v196, v152
	v_mov_b32_e32 v189, v216
	v_mov_b32_e32 v216, v213
	v_mov_b32_e32 v190, v214
	v_mov_b32_e32 v191, v218
	s_waitcnt lgkmcnt(0)
	v_pk_add_f32 v[152:153], v[152:153], v[154:155]
	ds_bpermute_b32 v155, v207, v153
	ds_bpermute_b32 v154, v207, v152
	v_mov_b32_e32 v218, v215
	v_mov_b32_e32 v208, v220
	v_mov_b32_e32 v209, v224
	v_mov_b32_e32 v224, v221
	v_mov_b32_e32 v212, v222
	v_mov_b32_e32 v213, v226
	v_mov_b32_e32 v226, v223
	v_pk_add_f32 v[156:157], v[188:189], v[216:217]
	v_pk_add_f32 v[158:159], v[190:191], v[218:219]
	v_pk_add_f32 v[188:189], v[208:209], v[224:225]
	v_pk_add_f32 v[190:191], v[212:213], v[226:227]
	s_waitcnt lgkmcnt(0)
; DI unsigned pack2(float lo, float hi) { f32x2 v = {lo, hi}; bf16v2 r = __builtin_convertvector(v, bf16v2); return __builtin_bit_cast(unsigned, r); }
; DI float dpp_ror1(float v) { return __int_as_float(__builtin_amdgcn_update_dpp(0, __float_as_int(v), 0x121, 0xf, 0xf, false)); }
; DI float dpp_ror2(float v) { return __int_as_float(__builtin_amdgcn_update_dpp(0, __float_as_int(v), 0x122, 0xf, 0xf, false)); }
;   DI void operator()(const f32x4 (&acc)[2][2][4][2], const Unit& u, int wr, int wc, int fr, int fq) const {
;     ...
;       for (int m = 0; m < 4; ++m) rsv[m] = row_rstd(ssq, row0 + 16 * m + fr, fq);
;       float p1[8], p2[8];
; #pragma unroll
;       for (int e = 0; e < 8; ++e) { p1[e] = 0.f; p2[e] = 0.f; }
; #pragma unroll
;       for (int m = 0; m < 4; ++m) {
;         float g[8], a[8];
;         const float rs1 = rsv[m], rs2 = rs1 * rs1;
; #pragma unroll
;         for (int e = 0; e < 4; ++e) { g[e] = acc[ai][0][m][0][e] * acc[ai][1][m][0][e] * rs2; g[4 + e] = acc[ai][0][m][1][e] * acc[ai][1][m][1][e] * rs2; }
; #pragma unroll
;         for (int e = 0; e < 8; ++e) {
;           const float x1 = dpp_ror1(g[e]), x2 = dpp_ror2(g[e]);
;           const float pr1 = (fr == 0) ? p1[e] : x1, pr2 = (fr < 2) ? p2[e] : x2;
;           a[e] = w2[e] * g[e] + w1[e] * pr1 + w0[e] * pr2;
;           p1[e] = x1; p2[e] = x2;
;         }
;         if (m == 0 && fr < 2) {
;           float* hc = headC + (size_t)(span * 2 + fr) * 2048 + col;
;           *(f32x4*)hc = (f32x4){a[0], a[1], a[2], a[3]}; *(f32x4*)(hc + 4) = (f32x4){a[4], a[5], a[6], a[7]};
;         } else {
;           u32x4 w; w.x = pack2(a[0] * rs1, a[1] * rs1); w.y = pack2(a[2] * rs1, a[3] * rs1); w.z = pack2(a[4] * rs1, a[5] * rs1); w.w = pack2(a[6] * rs1, a[7] * rs1);
;           *(u32x4*)(C + (size_t)(row0 + 16 * m + fr) * 2048 + col) = w;
;         }
	v_pk_add_f32 v[152:153], v[152:153], v[154:155]
	v_pk_add_f32 v[156:157], v[156:157], v[158:159]
	v_pk_add_f32 v[158:159], v[188:189], v[190:191]
	v_pk_fma_f32 v[188:189], v[152:153], s[30:31], v[176:177] op_sel_hi:[1,0,0]
	v_mov_b32_e32 v153, v156
	v_mul_f32_e32 v152, 0x4b800000, v189
	v_cmp_gt_f32_e64 s[10:11], s84, v189
	v_mov_b32_e32 v156, v159
	v_mov_b32_e32 v194, v123
	v_cndmask_b32_e64 v152, v189, v152, s[10:11]
	v_rsq_f32_e32 v168, v152
	v_mov_b32_e32 v152, v158
	v_pk_add_f32 v[152:153], v[152:153], v[156:157]
	ds_bpermute_b32 v155, v196, v153
	ds_bpermute_b32 v154, v196, v152
	v_mul_f32_e32 v156, 0x45800000, v168
	v_cndmask_b32_e64 v195, v168, v156, s[10:11]
	v_mov_b32_e32 v217, 0
	v_mul_f32_e32 v156, v125, v113
	s_waitcnt lgkmcnt(0)
	v_pk_add_f32 v[190:191], v[152:153], v[154:155]
	v_mov_b32_e32 v152, v111
	v_mov_b32_e32 v153, v195
	v_mul_f32_e32 v154, v124, v112
	v_pk_mul_f32 v[152:153], v[194:195], v[152:153]
	v_mul_f32_e32 v155, v120, v108
	v_mul_f32_e32 v154, v154, v153
	v_pk_mul_f32 v[222:223], v[152:153], v[152:153] op_sel:[0,1] op_sel_hi:[1,0]
	v_mov_b32_e32 v213, 0
	v_mov_b32_dpp v217, v154 row_ror:1 row_mask:0xf bank_mask:0xf
	v_cndmask_b32_e64 v152, v217, 0, s[0:1]
	v_mul_f32_e32 v157, v121, v109
	v_mul_f32_e32 v158, v126, v114
	v_mul_f32_e32 v159, v122, v110
	v_mul_f32_e32 v168, v127, v115
	v_mul_f32_e32 v194, v155, v153
	v_mul_f32_e32 v155, v156, v153
	v_mov_b32_dpp v213, v154 row_ror:2 row_mask:0xf bank_mask:0xf
	v_mov_b32_e32 v221, 0
	v_mul_f32_e32 v152, v144, v152
	v_mul_f32_e32 v208, v157, v153
	v_mul_f32_e32 v156, v158, v153
	v_mul_f32_e32 v159, v159, v153
	v_mul_f32_e32 v157, v168, v153
	v_mov_b32_dpp v221, v155 row_ror:1 row_mask:0xf bank_mask:0xf
	v_cndmask_b32_e64 v153, v213, 0, s[8:9]
	v_fmac_f32_e32 v152, v148, v154
	v_mov_b32_e32 v219, 0
	v_fmac_f32_e32 v152, v140, v153
	v_cndmask_b32_e64 v153, v221, 0, s[0:1]
	v_mov_b32_dpp v219, v155 row_ror:2 row_mask:0xf bank_mask:0xf
	v_mul_f32_e32 v153, v145, v153
	v_mov_b32_e32 v216, 0
	v_cndmask_b32_e64 v154, v219, 0, s[8:9]
	v_fmac_f32_e32 v153, v149, v155
	v_mov_b32_dpp v216, v156 row_ror:1 row_mask:0xf bank_mask:0xf
	v_fmac_f32_e32 v153, v141, v154
	v_mov_b32_e32 v212, 0
	v_cndmask_b32_e64 v154, v216, 0, s[0:1]
	v_mov_b32_e32 v220, 0
	v_mov_b32_dpp v212, v156 row_ror:2 row_mask:0xf bank_mask:0xf
	v_mul_f32_e32 v154, v146, v154
	v_mov_b32_dpp v220, v157 row_ror:1 row_mask:0xf bank_mask:0xf
	v_cndmask_b32_e64 v155, v212, 0, s[8:9]
	v_fmac_f32_e32 v154, v150, v156
	v_mov_b32_e32 v218, 0
	v_fmac_f32_e32 v154, v142, v155
	v_cndmask_b32_e64 v155, v220, 0, s[0:1]
	v_mov_b32_dpp v218, v157 row_ror:2 row_mask:0xf bank_mask:0xf
	v_mul_f32_e32 v155, v147, v155
	v_cndmask_b32_e64 v156, v218, 0, s[8:9]
	v_fmac_f32_e32 v155, v151, v157
	v_mov_b32_dpp v197, v194 row_ror:1 row_mask:0xf bank_mask:0xf
	v_fmac_f32_e32 v155, v143, v156
	v_mov_b32_e32 v189, 0
	v_cndmask_b32_e64 v156, v197, 0, s[0:1]
	v_mov_b32_e32 v214, 0
	v_mov_b32_dpp v189, v194 row_ror:2 row_mask:0xf bank_mask:0xf
	v_mul_f32_e32 v156, v132, v156
	v_mov_b32_dpp v214, v208 row_ror:1 row_mask:0xf bank_mask:0xf
	v_cndmask_b32_e64 v157, v189, 0, s[8:9]
	v_fmac_f32_e32 v156, v136, v194
	v_fmac_f32_e32 v156, v128, v157
	v_cndmask_b32_e64 v157, v214, 0, s[0:1]
	v_mov_b32_e32 v209, 0
	v_mul_f32_e32 v157, v133, v157
	v_fmac_f32_e32 v157, v137, v208
	v_mov_b32_dpp v209, v208 row_ror:2 row_mask:0xf bank_mask:0xf
	v_mov_b32_e32 v208, 0
	v_cndmask_b32_e64 v158, v209, 0, s[8:9]
	v_fmac_f32_e32 v157, v129, v158
	v_mov_b32_dpp v208, v159 row_ror:1 row_mask:0xf bank_mask:0xf
	v_mov_b32_e32 v194, 0
	v_cndmask_b32_e64 v158, v208, 0, s[0:1]
	ds_bpermute_b32 v193, v207, v191
	ds_bpermute_b32 v192, v207, v190
	v_mov_b32_dpp v194, v159 row_ror:2 row_mask:0xf bank_mask:0xf
	v_mov_b32_e32 v215, 0
	v_mul_f32_e32 v158, v134, v158
	v_cndmask_b32_e64 v168, v194, 0, s[8:9]
	v_mov_b32_dpp v215, v222 row_ror:1 row_mask:0xf bank_mask:0xf
	v_fmac_f32_e32 v158, v138, v159
	v_mov_b32_dpp v211, v222 row_ror:2 row_mask:0xf bank_mask:0xf
	v_fmac_f32_e32 v158, v130, v168
	v_cndmask_b32_e64 v168, v215, 0, s[0:1]
	v_mul_f32_e32 v159, v139, v222
	v_cndmask_b32_e64 v223, v211, 0, s[8:9]
	v_fmac_f32_e32 v159, v135, v168
	v_cmp_gt_f32_e32 vcc, s84, v188
	v_fmac_f32_e32 v159, v131, v223
	s_and_saveexec_b64 s[10:11], s[4:5]
	s_xor_b64 s[10:11], exec, s[10:11]
	s_cbranch_execz .LBB0_1056
	v_mul_f32_e32 v152, v195, v152
	v_mul_f32_e32 v153, v195, v153
	v_cvt_pk_bf16_f32 v152, v152, v153
	v_mul_f32_e32 v153, v195, v154
	v_mul_f32_e32 v154, v195, v155
	v_cvt_pk_bf16_f32 v153, v153, v154
	v_mul_f32_e32 v154, v195, v156
	v_mul_f32_e32 v155, v195, v157
	v_cvt_pk_bf16_f32 v154, v154, v155
	v_mul_f32_e32 v155, v195, v158
	v_mul_f32_e32 v156, v195, v159
	v_cvt_pk_bf16_f32 v155, v155, v156
	v_lshlrev_b64 v[156:157], 12, v[186:187]
	v_lshl_add_u64 v[156:157], s[18:19], 0, v[156:157]
	v_lshl_add_u64 v[156:157], v[178:179], 1, v[156:157]
	global_store_dwordx4 v[156:157], v[152:155], off

; #define PG8_STAGE(bufoff, gbase, voff) do { _Pragma("unroll") for (int _i = 0; _i < 2; ++_i) \
;     __builtin_amdgcn_global_load_lds((const unsigned*)((const char*)(gbase) + (voff)[_i]), (LAS unsigned*)(lds + (bufoff) + ldsw + _i * 8192), 16, 0, 0); } while (0)
; #define PG8_LDA(dst, b, h) do { _Pragma("unroll") for (int m = 0; m < 4; ++m) _Pragma("unroll") for (int k = 0; k < 2; ++k) dst[m][k] = *(const LAS bf16x8*)(lds + PG8_SA(b, h) + aoff + m * 2048 + k * 1024); } while (0)
; #define PG8_LDB(dst, b, h) do { _Pragma("unroll") for (int n = 0; n < 2; ++n) _Pragma("unroll") for (int k = 0; k < 2; ++k) dst[n][k] = *(const LAS bf16x8*)(lds + PG8_SB(b, h) + boff + n * 2048 + k * 1024); } while (0)
; #define PG8_MMA(ai, bj, At, Bt) do { __builtin_amdgcn_s_setprio(1); _Pragma("unroll") for (int m = 0; m < 4; ++m) _Pragma("unroll") for (int n = 0; n < 2; ++n) _Pragma("unroll") for (int k = 0; k < 2; ++k) \
;     acc[ai][bj][m][n] = __builtin_amdgcn_mfma_f32_16x16x32_bf16(Bt[n][k], At[m][k], acc[ai][bj][m][n], 0, 0, 0); __builtin_amdgcn_s_setprio(0); } while (0)
; #define PG8_WAIT_V(n) asm volatile("s_waitcnt vmcnt(" #n ")" ::: "memory")
; #define PG8_WAIT_L(n) asm volatile("s_waitcnt lgkmcnt(" #n ")" ::: "memory")
; #define PG8_BAR __builtin_amdgcn_s_barrier()
; #define PG8_SCHED __builtin_amdgcn_sched_barrier(0)
; template <class Epi, class Sched = StaticOrder>
; DI void gemm_phase(LAS unsigned char* lds, const Gemm g, const Sched& S, const Epi& E) {
;     ...
;     for (int t = 0; t < nt; t += 2) {
;       const bool last = (t == nt - 2);
;       const char* a1 = cA + (size_t)(t + 1) * kstep;
;       const char* a2 = last ? nA : cA + (size_t)(t + 2) * kstep; const char* b2 = last ? nB : cB + (size_t)(t + 2) * kstep;
;       const char* a3 = a2 + kstep; const char* b3 = b2 + kstep;
;       PG8_LDB(B0, 0, 0); PG8_SCHED; PG8_LDA(At, 0, 0); PG8_STAGE(PG8_SA(1, 1), a1 + hstep, voffA);
;       PG8_WAIT_L(8); PG8_BAR; PG8_WAIT_L(0); PG8_MMA(0, 0, At, B0); PG8_BAR; PG8_SCHED;
;       PG8_LDB(B1, 0, 1); PG8_STAGE(PG8_SB(0, 0), b2, voffB);
;       PG8_BAR; PG8_WAIT_L(0); PG8_MMA(0, 1, At, B1); PG8_BAR;
;       PG8_LDA(At, 0, 1); PG8_STAGE(PG8_SA(0, 0), a2, voffA);
;       PG8_BAR; PG8_WAIT_L(0); PG8_MMA(1, 0, At, B0); PG8_BAR; PG8_SCHED;
;       PG8_STAGE(PG8_SB(0, 1), b2 + hstep, voffB);
;       PG8_WAIT_V(6); PG8_BAR; PG8_MMA(1, 1, At, B1); PG8_BAR;
.LBB0_1194:
	ds_read_b128 v[128:131], v214
	ds_read_b128 v[132:135], v214 offset:1024
	ds_read_b128 v[136:139], v214 offset:2048
	ds_read_b128 v[140:143], v214 offset:3072
	s_add_u32 s24, s22, 0xfff80080
	s_addc_u32 s25, s23, -1
	s_cmp_eq_u32 s54, 28
	s_cselect_b32 s27, s17, s25
	s_cselect_b32 s26, s43, s24
	s_cselect_b32 s25, s15, s53
	s_cselect_b32 s24, s51, s52
	ds_read_b128 v[144:147], v215
	ds_read_b128 v[148:151], v215 offset:1024
	ds_read_b128 v[152:155], v215 offset:2048
	ds_read_b128 v[156:159], v215 offset:3072
	ds_read_b128 v[160:163], v215 offset:4096
	ds_read_b128 v[164:167], v215 offset:5120
	ds_read_b128 v[168:171], v215 offset:6144
	ds_read_b128 v[172:175], v215 offset:7168
	ds_read_b128 v[192:195], v216
	ds_read_b128 v[196:199], v216 offset:1024
	ds_read_b128 v[200:203], v216 offset:2048
	ds_read_b128 v[204:207], v216 offset:3072
	s_waitcnt vmcnt(6)
	s_waitcnt lgkmcnt(4)
	s_setprio 1
	s_barrier
	v_mfma_f32_16x16x32_bf16 v[124:127], v[128:131], v[144:147], v[124:127]
	s_add_i32 m0, s37, 0xc000
	v_mfma_f32_16x16x32_bf16 v[120:123], v[136:139], v[144:147], v[120:123]
	global_load_lds_dwordx4 v184, s[22:23]
	v_mfma_f32_16x16x32_bf16 v[108:111], v[128:131], v[152:155], v[108:111]
	s_add_i32 m0, s37, 0xe000
	v_mfma_f32_16x16x32_bf16 v[104:107], v[136:139], v[152:155], v[104:107]
	global_load_lds_dwordx4 v186, s[22:23]
	v_mfma_f32_16x16x32_bf16 v[92:95], v[128:131], v[160:163], v[92:95]
	v_mfma_f32_16x16x32_bf16 v[88:91], v[136:139], v[160:163], v[88:91]
	v_mfma_f32_16x16x32_bf16 v[76:79], v[128:131], v[168:171], v[76:79]
	v_mfma_f32_16x16x32_bf16 v[72:75], v[136:139], v[168:171], v[72:75]
	v_mfma_f32_16x16x32_bf16 v[124:127], v[132:135], v[148:151], v[124:127]
	v_mfma_f32_16x16x32_bf16 v[120:123], v[140:143], v[148:151], v[120:123]
	v_mfma_f32_16x16x32_bf16 v[108:111], v[132:135], v[156:159], v[108:111]
	v_mfma_f32_16x16x32_bf16 v[104:107], v[140:143], v[156:159], v[104:107]
	v_mfma_f32_16x16x32_bf16 v[92:95], v[132:135], v[164:167], v[92:95]
	v_mfma_f32_16x16x32_bf16 v[88:91], v[140:143], v[164:167], v[88:91]
	v_mfma_f32_16x16x32_bf16 v[76:79], v[132:135], v[172:175], v[76:79]
	v_mfma_f32_16x16x32_bf16 v[72:75], v[140:143], v[172:175], v[72:75]
	s_waitcnt lgkmcnt(0)
	v_mfma_f32_16x16x32_bf16 v[116:119], v[192:195], v[144:147], v[116:119]
	v_mfma_f32_16x16x32_bf16 v[112:115], v[200:203], v[144:147], v[112:115]
	v_mfma_f32_16x16x32_bf16 v[100:103], v[192:195], v[152:155], v[100:103]
	v_mfma_f32_16x16x32_bf16 v[96:99], v[200:203], v[152:155], v[96:99]
	v_mfma_f32_16x16x32_bf16 v[84:87], v[192:195], v[160:163], v[84:87]
	v_mfma_f32_16x16x32_bf16 v[80:83], v[200:203], v[160:163], v[80:83]
	v_mfma_f32_16x16x32_bf16 v[68:71], v[192:195], v[168:171], v[68:71]
	v_mfma_f32_16x16x32_bf16 v[64:67], v[200:203], v[168:171], v[64:67]
	v_mfma_f32_16x16x32_bf16 v[116:119], v[196:199], v[148:151], v[116:119]
	v_mfma_f32_16x16x32_bf16 v[112:115], v[204:207], v[148:151], v[112:115]
	v_mfma_f32_16x16x32_bf16 v[100:103], v[196:199], v[156:159], v[100:103]
	v_mfma_f32_16x16x32_bf16 v[96:99], v[204:207], v[156:159], v[96:99]
	v_mfma_f32_16x16x32_bf16 v[84:87], v[196:199], v[164:167], v[84:87]
	v_mfma_f32_16x16x32_bf16 v[80:83], v[204:207], v[164:167], v[80:83]
	v_mfma_f32_16x16x32_bf16 v[68:71], v[196:199], v[172:175], v[68:71]
	v_mfma_f32_16x16x32_bf16 v[64:67], v[204:207], v[172:175], v[64:67]
	s_barrier
	s_setprio 0
	s_add_i32 s55, s48, s35
	s_add_u32 s98, s24, 0x80
	s_addc_u32 s99, s25, 0
	s_add_u32 s100, s26, 0x80
	s_addc_u32 s101, s27, 0
	s_mov_b32 m0, s55
	s_nop 0
	global_load_lds_dwordx4 v180, s[24:25]
	s_add_i32 m0, s55, 0x2000
	s_nop 0
	global_load_lds_dwordx4 v176, s[24:25]
	s_mov_b32 m0, s37
	ds_read_b128 v[144:147], v215 offset:16384
	ds_read_b128 v[148:151], v215 offset:17408
	ds_read_b128 v[152:155], v215 offset:18432
	ds_read_b128 v[156:159], v215 offset:19456
	ds_read_b128 v[160:163], v215 offset:20480
	ds_read_b128 v[164:167], v215 offset:21504
	ds_read_b128 v[168:171], v215 offset:22528
	ds_read_b128 v[172:175], v215 offset:23552
	global_load_lds_dwordx4 v182, s[26:27]
	s_mov_b32 m0, s38
	s_nop 0
	global_load_lds_dwordx4 v178, s[26:27]
	s_add_u32 s56, s24, 0x80000
	s_addc_u32 s57, s25, 0
	s_add_i32 s55, s49, s35
	s_waitcnt vmcnt(6)
	s_waitcnt lgkmcnt(0)
	s_setprio 1
	s_barrier
	v_mfma_f32_16x16x32_bf16 v[60:63], v[128:131], v[144:147], v[60:63]
	s_mov_b32 m0, s55
	v_mfma_f32_16x16x32_bf16 v[56:59], v[136:139], v[144:147], v[56:59]
	global_load_lds_dwordx4 v180, s[56:57]
	v_mfma_f32_16x16x32_bf16 v[44:47], v[128:131], v[152:155], v[44:47]
	s_bitset1_b32 m0, 13
	v_mfma_f32_16x16x32_bf16 v[40:43], v[136:139], v[152:155], v[40:43]
	global_load_lds_dwordx4 v176, s[56:57]
	v_mfma_f32_16x16x32_bf16 v[28:31], v[128:131], v[160:163], v[28:31]
	v_mfma_f32_16x16x32_bf16 v[24:27], v[136:139], v[160:163], v[24:27]
	v_mfma_f32_16x16x32_bf16 v[12:15], v[128:131], v[168:171], v[12:15]
	v_mfma_f32_16x16x32_bf16 v[8:11], v[136:139], v[168:171], v[8:11]
	v_mfma_f32_16x16x32_bf16 v[60:63], v[132:135], v[148:151], v[60:63]
	v_mfma_f32_16x16x32_bf16 v[56:59], v[140:143], v[148:151], v[56:59]
	v_mfma_f32_16x16x32_bf16 v[44:47], v[132:135], v[156:159], v[44:47]
	v_mfma_f32_16x16x32_bf16 v[40:43], v[140:143], v[156:159], v[40:43]
	v_mfma_f32_16x16x32_bf16 v[28:31], v[132:135], v[164:167], v[28:31]
	v_mfma_f32_16x16x32_bf16 v[24:27], v[140:143], v[164:167], v[24:27]
	v_mfma_f32_16x16x32_bf16 v[12:15], v[132:135], v[172:175], v[12:15]
	v_mfma_f32_16x16x32_bf16 v[8:11], v[140:143], v[172:175], v[8:11]
	v_mfma_f32_16x16x32_bf16 v[52:55], v[192:195], v[144:147], v[52:55]
	v_mfma_f32_16x16x32_bf16 v[48:51], v[200:203], v[144:147], v[48:51]
	v_mfma_f32_16x16x32_bf16 v[36:39], v[192:195], v[152:155], v[36:39]
	v_mfma_f32_16x16x32_bf16 v[32:35], v[200:203], v[152:155], v[32:35]
	v_mfma_f32_16x16x32_bf16 v[20:23], v[192:195], v[160:163], v[20:23]
	v_mfma_f32_16x16x32_bf16 v[16:19], v[200:203], v[160:163], v[16:19]
	v_mfma_f32_16x16x32_bf16 v[4:7], v[192:195], v[168:171], v[4:7]
	v_mfma_f32_16x16x32_bf16 v[0:3], v[200:203], v[168:171], v[0:3]
	v_mfma_f32_16x16x32_bf16 v[52:55], v[196:199], v[148:151], v[52:55]
	v_mfma_f32_16x16x32_bf16 v[48:51], v[204:207], v[148:151], v[48:51]
	v_mfma_f32_16x16x32_bf16 v[36:39], v[196:199], v[156:159], v[36:39]
	v_mfma_f32_16x16x32_bf16 v[32:35], v[204:207], v[156:159], v[32:35]
	v_mfma_f32_16x16x32_bf16 v[20:23], v[196:199], v[164:167], v[20:23]
	v_mfma_f32_16x16x32_bf16 v[16:19], v[204:207], v[164:167], v[16:19]
	v_mfma_f32_16x16x32_bf16 v[4:7], v[196:199], v[172:175], v[4:7]
	v_mfma_f32_16x16x32_bf16 v[0:3], v[204:207], v[172:175], v[0:3]
	s_barrier
; #define PG8_STAGE(bufoff, gbase, voff) do { _Pragma("unroll") for (int _i = 0; _i < 2; ++_i) \
;     __builtin_amdgcn_global_load_lds((const unsigned*)((const char*)(gbase) + (voff)[_i]), (LAS unsigned*)(lds + (bufoff) + ldsw + _i * 8192), 16, 0, 0); } while (0)
; #define PG8_LDA(dst, b, h) do { _Pragma("unroll") for (int m = 0; m < 4; ++m) _Pragma("unroll") for (int k = 0; k < 2; ++k) dst[m][k] = *(const LAS bf16x8*)(lds + PG8_SA(b, h) + aoff + m * 2048 + k * 1024); } while (0)
; #define PG8_LDB(dst, b, h) do { _Pragma("unroll") for (int n = 0; n < 2; ++n) _Pragma("unroll") for (int k = 0; k < 2; ++k) dst[n][k] = *(const LAS bf16x8*)(lds + PG8_SB(b, h) + boff + n * 2048 + k * 1024); } while (0)
; #define PG8_MMA(ai, bj, At, Bt) do { __builtin_amdgcn_s_setprio(1); _Pragma("unroll") for (int m = 0; m < 4; ++m) _Pragma("unroll") for (int n = 0; n < 2; ++n) _Pragma("unroll") for (int k = 0; k < 2; ++k) \
;     acc[ai][bj][m][n] = __builtin_amdgcn_mfma_f32_16x16x32_bf16(Bt[n][k], At[m][k], acc[ai][bj][m][n], 0, 0, 0); __builtin_amdgcn_s_setprio(0); } while (0)
; #define PG8_WAIT_V(n) asm volatile("s_waitcnt vmcnt(" #n ")" ::: "memory")
; #define PG8_WAIT_L(n) asm volatile("s_waitcnt lgkmcnt(" #n ")" ::: "memory")
; #define PG8_BAR __builtin_amdgcn_s_barrier()
; #define PG8_SCHED __builtin_amdgcn_sched_barrier(0)
; template <class Epi, class Sched = StaticOrder>
; DI void gemm_phase(LAS unsigned char* lds, const Gemm g, const Sched& S, const Epi& E) {
;     ...
;       PG8_LDB(B0, 1, 0); PG8_SCHED; PG8_LDA(At, 1, 0); PG8_STAGE(PG8_SA(0, 1), a2 + hstep, voffA);
;       PG8_WAIT_L(8); PG8_BAR; PG8_WAIT_L(0); PG8_MMA(0, 0, At, B0); PG8_BAR; PG8_SCHED;
;       PG8_LDB(B1, 1, 1); PG8_STAGE(PG8_SB(1, 0), b3, voffB);
;       PG8_BAR; PG8_WAIT_L(0); PG8_MMA(0, 1, At, B1); PG8_BAR;
;       PG8_LDA(At, 1, 1); PG8_STAGE(PG8_SA(1, 0), a3, voffA);
;       PG8_BAR; PG8_WAIT_L(0); PG8_MMA(1, 0, At, B0); PG8_BAR; PG8_SCHED;
;       PG8_STAGE(PG8_SB(1, 1), b3 + hstep, voffB);
;       PG8_WAIT_V(6); PG8_BAR; PG8_MMA(1, 1, At, B1); PG8_BAR;
;     }
	s_setprio 0
	s_add_i32 s55, 0, 0x18000
	v_add_u32_e32 v140, s55, v212
	ds_read_b128 v[128:131], v140
	ds_read_b128 v[132:135], v140 offset:1024
	ds_read_b128 v[136:139], v140 offset:2048
	ds_read_b128 v[140:143], v140 offset:3072
	s_add_u32 s26, s26, 0x80000
	s_addc_u32 s27, s27, 0
	s_mov_b32 m0, s39
	ds_read_b128 v[144:147], v215 offset:32768
	ds_read_b128 v[148:151], v215 offset:33792
	ds_read_b128 v[152:155], v215 offset:34816
	ds_read_b128 v[156:159], v215 offset:35840
	ds_read_b128 v[160:163], v215 offset:36864
	ds_read_b128 v[164:167], v215 offset:37888
	ds_read_b128 v[168:171], v215 offset:38912
	ds_read_b128 v[172:175], v215 offset:39936
	global_load_lds_dwordx4 v182, s[26:27]
	s_mov_b32 m0, s40
	s_nop 0
	global_load_lds_dwordx4 v178, s[26:27]
	s_add_i32 s26, 0, 0x1c000
	v_add_u32_e32 v204, s26, v212
	ds_read_b128 v[192:195], v204
	ds_read_b128 v[196:199], v204 offset:1024
	ds_read_b128 v[200:203], v204 offset:2048
	ds_read_b128 v[204:207], v204 offset:3072
	s_waitcnt vmcnt(8)
	s_waitcnt lgkmcnt(4)
	s_setprio 1
	s_barrier
	v_mfma_f32_16x16x32_bf16 v[124:127], v[128:131], v[144:147], v[124:127]
	v_mfma_f32_16x16x32_bf16 v[120:123], v[136:139], v[144:147], v[120:123]
	v_mfma_f32_16x16x32_bf16 v[108:111], v[128:131], v[152:155], v[108:111]
	v_mfma_f32_16x16x32_bf16 v[104:107], v[136:139], v[152:155], v[104:107]
	v_mfma_f32_16x16x32_bf16 v[92:95], v[128:131], v[160:163], v[92:95]
	v_mfma_f32_16x16x32_bf16 v[88:91], v[136:139], v[160:163], v[88:91]
	v_mfma_f32_16x16x32_bf16 v[76:79], v[128:131], v[168:171], v[76:79]
	v_mfma_f32_16x16x32_bf16 v[72:75], v[136:139], v[168:171], v[72:75]
	v_mfma_f32_16x16x32_bf16 v[124:127], v[132:135], v[148:151], v[124:127]
	v_mfma_f32_16x16x32_bf16 v[120:123], v[140:143], v[148:151], v[120:123]
	v_mfma_f32_16x16x32_bf16 v[108:111], v[132:135], v[156:159], v[108:111]
	v_mfma_f32_16x16x32_bf16 v[104:107], v[140:143], v[156:159], v[104:107]
	v_mfma_f32_16x16x32_bf16 v[92:95], v[132:135], v[164:167], v[92:95]
	v_mfma_f32_16x16x32_bf16 v[88:91], v[140:143], v[164:167], v[88:91]
	v_mfma_f32_16x16x32_bf16 v[76:79], v[132:135], v[172:175], v[76:79]
	v_mfma_f32_16x16x32_bf16 v[72:75], v[140:143], v[172:175], v[72:75]
	s_waitcnt lgkmcnt(0)
	v_mfma_f32_16x16x32_bf16 v[116:119], v[192:195], v[144:147], v[116:119]
	v_mfma_f32_16x16x32_bf16 v[112:115], v[200:203], v[144:147], v[112:115]
	v_mfma_f32_16x16x32_bf16 v[100:103], v[192:195], v[152:155], v[100:103]
	v_mfma_f32_16x16x32_bf16 v[96:99], v[200:203], v[152:155], v[96:99]
	v_mfma_f32_16x16x32_bf16 v[84:87], v[192:195], v[160:163], v[84:87]
	v_mfma_f32_16x16x32_bf16 v[80:83], v[200:203], v[160:163], v[80:83]
	v_mfma_f32_16x16x32_bf16 v[68:71], v[192:195], v[168:171], v[68:71]
	v_mfma_f32_16x16x32_bf16 v[64:67], v[200:203], v[168:171], v[64:67]
	v_mfma_f32_16x16x32_bf16 v[116:119], v[196:199], v[148:151], v[116:119]
	v_mfma_f32_16x16x32_bf16 v[112:115], v[204:207], v[148:151], v[112:115]
	v_mfma_f32_16x16x32_bf16 v[100:103], v[196:199], v[156:159], v[100:103]
	v_mfma_f32_16x16x32_bf16 v[96:99], v[204:207], v[156:159], v[96:99]
	v_mfma_f32_16x16x32_bf16 v[84:87], v[196:199], v[164:167], v[84:87]
	v_mfma_f32_16x16x32_bf16 v[80:83], v[204:207], v[164:167], v[80:83]
	v_mfma_f32_16x16x32_bf16 v[68:71], v[196:199], v[172:175], v[68:71]
	v_mfma_f32_16x16x32_bf16 v[64:67], v[204:207], v[172:175], v[64:67]
	s_barrier
	s_setprio 0
	s_add_i32 s27, s55, s35
	s_mov_b32 m0, s27
	s_nop 0
	global_load_lds_dwordx4 v180, s[98:99]
	s_add_i32 m0, s27, 0x2000
	s_nop 0
	global_load_lds_dwordx4 v176, s[98:99]
	s_mov_b32 m0, s44
	ds_read_b128 v[144:147], v215 offset:49152
	ds_read_b128 v[148:151], v215 offset:50176
	ds_read_b128 v[152:155], v215 offset:51200
	ds_read_b128 v[156:159], v215 offset:52224
	ds_read_b128 v[160:163], v215 offset:53248
	ds_read_b128 v[164:167], v215 offset:54272
	ds_read_b128 v[168:171], v215 offset:55296
	ds_read_b128 v[172:175], v215 offset:56320
	global_load_lds_dwordx4 v182, s[100:101]
	s_mov_b32 m0, s45
	s_nop 0
	global_load_lds_dwordx4 v178, s[100:101]
	s_add_u32 s24, s24, 0x80080
	s_addc_u32 s25, s25, 0
	s_add_i32 s26, s26, s35
	s_add_i32 s54, s54, 2
	s_add_u32 s22, s22, 0x100
	s_addc_u32 s23, s23, 0
	s_add_u32 s52, s52, 0x100
	s_addc_u32 s53, s53, 0
	s_cmp_gt_u32 s54, 29
	s_waitcnt vmcnt(6)
	s_waitcnt lgkmcnt(0)
	s_setprio 1
	s_barrier
	v_mfma_f32_16x16x32_bf16 v[60:63], v[128:131], v[144:147], v[60:63]
	s_mov_b32 m0, s26
	v_mfma_f32_16x16x32_bf16 v[56:59], v[136:139], v[144:147], v[56:59]
	global_load_lds_dwordx4 v180, s[24:25]
	v_mfma_f32_16x16x32_bf16 v[44:47], v[128:131], v[152:155], v[44:47]
	s_bitset1_b32 m0, 13
	v_mfma_f32_16x16x32_bf16 v[40:43], v[136:139], v[152:155], v[40:43]
	global_load_lds_dwordx4 v176, s[24:25]
	v_mfma_f32_16x16x32_bf16 v[28:31], v[128:131], v[160:163], v[28:31]
	v_mfma_f32_16x16x32_bf16 v[24:27], v[136:139], v[160:163], v[24:27]
	v_mfma_f32_16x16x32_bf16 v[12:15], v[128:131], v[168:171], v[12:15]
	v_mfma_f32_16x16x32_bf16 v[8:11], v[136:139], v[168:171], v[8:11]
	v_mfma_f32_16x16x32_bf16 v[60:63], v[132:135], v[148:151], v[60:63]
	v_mfma_f32_16x16x32_bf16 v[56:59], v[140:143], v[148:151], v[56:59]
	v_mfma_f32_16x16x32_bf16 v[44:47], v[132:135], v[156:159], v[44:47]
	v_mfma_f32_16x16x32_bf16 v[40:43], v[140:143], v[156:159], v[40:43]
	v_mfma_f32_16x16x32_bf16 v[28:31], v[132:135], v[164:167], v[28:31]
	v_mfma_f32_16x16x32_bf16 v[24:27], v[140:143], v[164:167], v[24:27]
	v_mfma_f32_16x16x32_bf16 v[12:15], v[132:135], v[172:175], v[12:15]
	v_mfma_f32_16x16x32_bf16 v[8:11], v[140:143], v[172:175], v[8:11]
	v_mfma_f32_16x16x32_bf16 v[52:55], v[192:195], v[144:147], v[52:55]
	v_mfma_f32_16x16x32_bf16 v[48:51], v[200:203], v[144:147], v[48:51]
	v_mfma_f32_16x16x32_bf16 v[36:39], v[192:195], v[152:155], v[36:39]
	v_mfma_f32_16x16x32_bf16 v[32:35], v[200:203], v[152:155], v[32:35]
	v_mfma_f32_16x16x32_bf16 v[20:23], v[192:195], v[160:163], v[20:23]
	v_mfma_f32_16x16x32_bf16 v[16:19], v[200:203], v[160:163], v[16:19]
	v_mfma_f32_16x16x32_bf16 v[4:7], v[192:195], v[168:171], v[4:7]
	v_mfma_f32_16x16x32_bf16 v[0:3], v[200:203], v[168:171], v[0:3]
	v_mfma_f32_16x16x32_bf16 v[52:55], v[196:199], v[148:151], v[52:55]
	v_mfma_f32_16x16x32_bf16 v[48:51], v[204:207], v[148:151], v[48:51]
	v_mfma_f32_16x16x32_bf16 v[36:39], v[196:199], v[156:159], v[36:39]
	v_mfma_f32_16x16x32_bf16 v[32:35], v[204:207], v[156:159], v[32:35]
	v_mfma_f32_16x16x32_bf16 v[20:23], v[196:199], v[164:167], v[20:23]
	v_mfma_f32_16x16x32_bf16 v[16:19], v[204:207], v[164:167], v[16:19]
	v_mfma_f32_16x16x32_bf16 v[4:7], v[196:199], v[172:175], v[4:7]
	v_mfma_f32_16x16x32_bf16 v[0:3], v[204:207], v[172:175], v[0:3]
	s_barrier
; DI unsigned pack2(float lo, float hi) { f32x2 v = {lo, hi}; bf16v2 r = __builtin_convertvector(v, bf16v2); return __builtin_bit_cast(unsigned, r); }
;   DI void operator()(const f32x4 (&acc)[2][2][4][2], const Unit& u, int wr, int wc, int fr, int fq) const {
;     const int row0 = u.pm * BM + wr * 64 + fr, col0 = u.pn * BM + wc * 32 + 8 * fq;
; #pragma unroll
;     for (int ai = 0; ai < 2; ++ai) {
;       f32x4 bv[4][2][2];
; #pragma unroll
;       for (int m = 0; m < 4; ++m)
; #pragma unroll
;         for (int bj = 0; bj < 2; ++bj) {
;           const float* bp = base + (size_t)(row0 + ai * HALF + m * 16) * 2048 + col0 + bj * HALF;
;           bv[m][bj][0] = *(const f32x4*)bp; bv[m][bj][1] = *(const f32x4*)(bp + 4);
;         }
; #pragma unroll
;       for (int m = 0; m < 4; ++m) {
;         const int row = row0 + ai * HALF + m * 16;
;         const size_t off = (size_t)row * 2048 + col0;
;         float ss = 0.f;
; #pragma unroll
;         for (int bj = 0; bj < 2; ++bj) {
;           const f32x4 v0 = acc[ai][bj][m][0] + bv[m][bj][0], v1 = acc[ai][bj][m][1] + bv[m][bj][1];
;           *(f32x4*)(C + off + bj * HALF) = v0; *(f32x4*)(C + off + bj * HALF + 4) = v1;
;           if (xb) {
;             u32x4 w; w.x = pack2(v0[0], v0[1]); w.y = pack2(v0[2], v0[3]); w.z = pack2(v1[0], v1[1]); w.w = pack2(v1[2], v1[3]);
;             *(u32x4*)(xb + off + bj * HALF) = w;
;             ss += v0[0] * v0[0] + v0[1] * v0[1] + v0[2] * v0[2] + v0[3] * v0[3] + v1[0] * v1[0] + v1[1] * v1[1] + v1[2] * v1[2] + v1[3] * v1[3];
;           }
;         }
;         if (xb) {
;           ss += __shfl_xor(ss, 16); ss += __shfl_xor(ss, 32);
;           if (fq == 0) ssq[(size_t)row * 32 + u.pn * 4 + wc] = ss;
;         }
	s_setprio 0
	s_cbranch_scc0 .LBB0_1194
	v_lshl_add_u32 v194, s12, 8, v211
	v_lshl_or_b32 v192, s42, 8, v213
	v_readlane_b32 s52, v243, 3
	v_ashrrev_i32_e32 v193, 31, v192
	v_readlane_b32 s66, v243, 17
	v_readlane_b32 s67, v243, 18
	v_ashrrev_i32_e32 v195, 31, v194
	v_lshlrev_b64 v[128:129], 13, v[194:195]
	v_lshl_add_u64 v[196:197], v[192:193], 2, s[66:67]
	v_lshl_add_u64 v[236:237], v[196:197], 0, v[128:129]
	global_load_dwordx4 v[220:223], v[236:237], off
	global_load_dwordx4 v[224:227], v[236:237], off offset:16
	global_load_dwordx4 v[228:231], v[236:237], off offset:512
	global_load_dwordx4 v[232:235], v[236:237], off offset:528
	v_or_b32_e32 v206, 16, v194
	v_or_b32_e32 v202, 32, v194
	v_or_b32_e32 v198, 48, v194
	v_ashrrev_i32_e32 v207, 31, v206
	v_ashrrev_i32_e32 v203, 31, v202
	v_ashrrev_i32_e32 v199, 31, v198
	v_lshlrev_b64 v[128:129], 13, v[206:207]
	v_lshlrev_b64 v[130:131], 13, v[202:203]
	v_lshlrev_b64 v[132:133], 13, v[198:199]
	v_lshl_add_u64 v[208:209], v[196:197], 0, v[128:129]
	v_lshl_add_u64 v[204:205], v[196:197], 0, v[130:131]
	v_lshl_add_u64 v[200:201], v[196:197], 0, v[132:133]
	global_load_dwordx4 v[168:171], v[208:209], off offset:16
	global_load_dwordx4 v[172:175], v[208:209], off
	global_load_dwordx4 v[160:163], v[208:209], off offset:528
	global_load_dwordx4 v[164:167], v[208:209], off offset:512
	global_load_dwordx4 v[152:155], v[204:205], off offset:16
	global_load_dwordx4 v[156:159], v[204:205], off
	global_load_dwordx4 v[144:147], v[204:205], off offset:528
	global_load_dwordx4 v[148:151], v[204:205], off offset:512
	global_load_dwordx4 v[136:139], v[200:201], off offset:16
	global_load_dwordx4 v[140:143], v[200:201], off
	global_load_dwordx4 v[128:131], v[200:201], off offset:528
	global_load_dwordx4 v[132:135], v[200:201], off offset:512
	v_and_b32_e32 v218, 64, v217
	v_xor_b32_e32 v238, 16, v217
	v_add_u32_e32 v240, 64, v218
	v_xor_b32_e32 v239, 32, v217
	v_cmp_lt_i32_e32 vcc, v238, v240
	v_lshlrev_b64 v[218:219], 11, v[194:195]
	s_lshl_b32 s22, s42, 2
	v_cndmask_b32_e32 v241, v217, v238, vcc
	v_cmp_lt_i32_e32 vcc, v239, v240
	s_ashr_i32 s23, s22, 31
	v_readlane_b32 s53, v243, 4
	v_cndmask_b32_e32 v240, v217, v239, vcc
	v_lshl_add_u64 v[238:239], v[218:219], 0, v[192:193]
	v_lshlrev_b32_e32 v218, 2, v241
	v_lshl_add_u64 v[238:239], v[238:239], 1, s[2:3]
	v_readlane_b32 s54, v243, 5
	v_readlane_b32 s55, v243, 6
	v_readlane_b32 s56, v243, 7
	v_readlane_b32 s57, v243, 8
	v_readlane_b32 s58, v243, 9
	v_readlane_b32 s59, v243, 10
	v_readlane_b32 s60, v243, 11
	v_readlane_b32 s61, v243, 12
	v_readlane_b32 s62, v243, 13
	v_readlane_b32 s63, v243, 14
	v_readlane_b32 s64, v243, 15
	v_readlane_b32 s65, v243, 16
	s_waitcnt vmcnt(0)
	v_pk_add_f32 v[126:127], v[126:127], v[222:223]
	v_pk_add_f32 v[124:125], v[124:125], v[220:221]
	v_pk_add_f32 v[116:117], v[116:117], v[228:229]
	v_pk_add_f32 v[122:123], v[122:123], v[226:227]
	v_pk_add_f32 v[120:121], v[120:121], v[224:225]
	v_pk_add_f32 v[220:221], v[112:113], v[232:233]
	global_store_dwordx4 v[236:237], v[124:127], off
	global_store_dwordx4 v[236:237], v[120:123], off offset:16
	v_cvt_pk_bf16_f32 v112, v124, v125
	v_mul_f32_e32 v125, v125, v125
	v_mul_f32_e32 v219, v117, v117
	v_pk_add_f32 v[118:119], v[118:119], v[230:231]
	v_fmac_f32_e32 v125, v124, v124
	v_fmac_f32_e32 v219, v116, v116
	v_fmac_f32_e32 v125, v126, v126
	v_fmac_f32_e32 v219, v118, v118
	v_fmac_f32_e32 v125, v127, v127
	v_fmac_f32_e32 v219, v119, v119
	v_fmac_f32_e32 v125, v120, v120
	v_fmac_f32_e32 v219, v220, v220
	v_pk_add_f32 v[222:223], v[114:115], v[234:235]
	v_fmac_f32_e32 v125, v121, v121
	v_fmac_f32_e32 v219, v221, v221
	v_fmac_f32_e32 v125, v122, v122
	v_fmac_f32_e32 v219, v222, v222
	v_fmac_f32_e32 v125, v123, v123
	v_fmac_f32_e32 v219, v223, v223
	v_cvt_pk_bf16_f32 v114, v120, v121
	v_add_f32_e32 v121, v125, v219
	v_cvt_pk_bf16_f32 v115, v122, v123
	ds_bpermute_b32 v122, v218, v121
	v_cvt_pk_bf16_f32 v113, v126, v127
	global_store_dwordx4 v[238:239], v[112:115], off
	global_store_dwordx4 v[236:237], v[116:119], off offset:512
	global_store_dwordx4 v[236:237], v[220:223], off offset:528
	v_lshlrev_b32_e32 v126, 2, v240
	v_cvt_pk_bf16_f32 v120, v116, v117
	s_waitcnt lgkmcnt(0)
	v_add_f32_e32 v112, v121, v122
	ds_bpermute_b32 v113, v126, v112
	v_cvt_pk_bf16_f32 v121, v118, v119
	v_cvt_pk_bf16_f32 v122, v220, v221
	v_cvt_pk_bf16_f32 v123, v222, v223
	global_store_dwordx4 v[238:239], v[120:123], off offset:256
	s_and_saveexec_b64 s[24:25], s[0:1]
	s_cbranch_execz .LBB0_1197
	s_waitcnt lgkmcnt(0)
	v_add_f32_e32 v114, v112, v113
	v_lshlrev_b64 v[112:113], 7, v[194:195]
	v_lshl_add_u64 v[112:113], s[8:9], 0, v[112:113]
	v_lshl_add_u64 v[112:113], s[22:23], 2, v[112:113]
	s_lshl_b32 s12, s41, 2
	v_lshl_add_u64 v[112:113], v[112:113], 0, s[12:13]
	global_store_dword v[112:113], v114, off

; #define PG8_STAGE(bufoff, gbase, voff) do { _Pragma("unroll") for (int _i = 0; _i < 2; ++_i) \
;     __builtin_amdgcn_global_load_lds((const unsigned*)((const char*)(gbase) + (voff)[_i]), (LAS unsigned*)(lds + (bufoff) + ldsw + _i * 8192), 16, 0, 0); } while (0)
; #define PG8_LDA(dst, b, h) do { _Pragma("unroll") for (int m = 0; m < 4; ++m) _Pragma("unroll") for (int k = 0; k < 2; ++k) dst[m][k] = *(const LAS bf16x8*)(lds + PG8_SA(b, h) + aoff + m * 2048 + k * 1024); } while (0)
; #define PG8_LDB(dst, b, h) do { _Pragma("unroll") for (int n = 0; n < 2; ++n) _Pragma("unroll") for (int k = 0; k < 2; ++k) dst[n][k] = *(const LAS bf16x8*)(lds + PG8_SB(b, h) + boff + n * 2048 + k * 1024); } while (0)
; #define PG8_MMA(ai, bj, At, Bt) do { __builtin_amdgcn_s_setprio(1); _Pragma("unroll") for (int m = 0; m < 4; ++m) _Pragma("unroll") for (int n = 0; n < 2; ++n) _Pragma("unroll") for (int k = 0; k < 2; ++k) \
;     acc[ai][bj][m][n] = __builtin_amdgcn_mfma_f32_16x16x32_bf16(Bt[n][k], At[m][k], acc[ai][bj][m][n], 0, 0, 0); __builtin_amdgcn_s_setprio(0); } while (0)
; #define PG8_WAIT_V(n) asm volatile("s_waitcnt vmcnt(" #n ")" ::: "memory")
; #define PG8_WAIT_L(n) asm volatile("s_waitcnt lgkmcnt(" #n ")" ::: "memory")
; #define PG8_BAR __builtin_amdgcn_s_barrier()
; #define PG8_SCHED __builtin_amdgcn_sched_barrier(0)
; template <class Epi, class Sched = StaticOrder>
; DI void gemm_phase(LAS unsigned char* lds, const Gemm g, const Sched& S, const Epi& E) {
;     ...
;     for (int t = 0; t < nt; t += 2) {
;       const bool last = (t == nt - 2);
;       const char* a1 = cA + (size_t)(t + 1) * kstep;
;       const char* a2 = last ? nA : cA + (size_t)(t + 2) * kstep; const char* b2 = last ? nB : cB + (size_t)(t + 2) * kstep;
;       const char* a3 = a2 + kstep; const char* b3 = b2 + kstep;
;       PG8_LDB(B0, 0, 0); PG8_SCHED; PG8_LDA(At, 0, 0); PG8_STAGE(PG8_SA(1, 1), a1 + hstep, voffA);
;       PG8_WAIT_L(8); PG8_BAR; PG8_WAIT_L(0); PG8_MMA(0, 0, At, B0); PG8_BAR; PG8_SCHED;
;       PG8_LDB(B1, 0, 1); PG8_STAGE(PG8_SB(0, 0), b2, voffB);
;       PG8_BAR; PG8_WAIT_L(0); PG8_MMA(0, 1, At, B1); PG8_BAR;
;       PG8_LDA(At, 0, 1); PG8_STAGE(PG8_SA(0, 0), a2, voffA);
;       PG8_BAR; PG8_WAIT_L(0); PG8_MMA(1, 0, At, B0); PG8_BAR; PG8_SCHED;
;       PG8_STAGE(PG8_SB(0, 1), b2 + hstep, voffB);
;       PG8_WAIT_V(6); PG8_BAR; PG8_MMA(1, 1, At, B1); PG8_BAR;
.LBB0_1277:
	ds_read_b128 v[64:67], v201
	ds_read_b128 v[68:71], v201 offset:1024
	ds_read_b128 v[72:75], v201 offset:2048
	ds_read_b128 v[76:79], v201 offset:3072
	s_add_u32 s48, s14, 0xfff80080
	s_addc_u32 s49, s15, -1
	s_cmp_eq_u32 s58, 28
	s_cselect_b32 s51, s41, s49
	s_cselect_b32 s50, s42, s48
	s_cselect_b32 s49, s39, s53
	s_cselect_b32 s48, s43, s52
	ds_read_b128 v[80:83], v202
	ds_read_b128 v[84:87], v202 offset:1024
	ds_read_b128 v[88:91], v202 offset:2048
	ds_read_b128 v[92:95], v202 offset:3072
	ds_read_b128 v[180:183], v202 offset:4096
	ds_read_b128 v[184:187], v202 offset:5120
	ds_read_b128 v[188:191], v202 offset:6144
	ds_read_b128 v[192:195], v202 offset:7168
	ds_read_b128 v[206:209], v203
	ds_read_b128 v[212:215], v203 offset:1024
	ds_read_b128 v[216:219], v203 offset:2048
	ds_read_b128 v[220:223], v203 offset:3072
	s_waitcnt vmcnt(6)
	s_waitcnt lgkmcnt(4)
	s_setprio 1
	s_barrier
	v_mfma_f32_16x16x32_bf16 v[156:159], v[64:67], v[80:83], v[156:159]
	s_add_i32 m0, s64, 0xc000
	v_mfma_f32_16x16x32_bf16 v[144:147], v[72:75], v[80:83], v[144:147]
	global_load_lds_dwordx4 v170, s[14:15]
	v_mfma_f32_16x16x32_bf16 v[140:143], v[64:67], v[88:91], v[140:143]
	s_add_i32 m0, s64, 0xe000
	v_mfma_f32_16x16x32_bf16 v[132:135], v[72:75], v[88:91], v[132:135]
	global_load_lds_dwordx4 v172, s[14:15]
	v_mfma_f32_16x16x32_bf16 v[124:127], v[64:67], v[180:183], v[124:127]
	v_mfma_f32_16x16x32_bf16 v[116:119], v[72:75], v[180:183], v[116:119]
	v_mfma_f32_16x16x32_bf16 v[112:115], v[64:67], v[188:191], v[112:115]
	v_mfma_f32_16x16x32_bf16 v[108:111], v[72:75], v[188:191], v[108:111]
	v_mfma_f32_16x16x32_bf16 v[156:159], v[68:71], v[84:87], v[156:159]
	v_mfma_f32_16x16x32_bf16 v[144:147], v[76:79], v[84:87], v[144:147]
	v_mfma_f32_16x16x32_bf16 v[140:143], v[68:71], v[92:95], v[140:143]
	v_mfma_f32_16x16x32_bf16 v[132:135], v[76:79], v[92:95], v[132:135]
	v_mfma_f32_16x16x32_bf16 v[124:127], v[68:71], v[184:187], v[124:127]
	v_mfma_f32_16x16x32_bf16 v[116:119], v[76:79], v[184:187], v[116:119]
	v_mfma_f32_16x16x32_bf16 v[112:115], v[68:71], v[192:195], v[112:115]
	v_mfma_f32_16x16x32_bf16 v[108:111], v[76:79], v[192:195], v[108:111]
	s_waitcnt lgkmcnt(0)
	v_mfma_f32_16x16x32_bf16 v[152:155], v[206:209], v[80:83], v[152:155]
	v_mfma_f32_16x16x32_bf16 v[80:83], v[216:219], v[80:83], v[148:151]
	v_mfma_f32_16x16x32_bf16 v[152:155], v[212:215], v[84:87], v[152:155]
	v_mfma_f32_16x16x32_bf16 v[80:83], v[220:223], v[84:87], v[80:83]
	v_mfma_f32_16x16x32_bf16 v[84:87], v[206:209], v[88:91], v[136:139]
	v_mfma_f32_16x16x32_bf16 v[88:91], v[216:219], v[88:91], v[128:131]
	v_mfma_f32_16x16x32_bf16 v[104:107], v[216:219], v[180:183], v[104:107]
	v_mfma_f32_16x16x32_bf16 v[100:103], v[206:209], v[188:191], v[100:103]
	v_mfma_f32_16x16x32_bf16 v[96:99], v[216:219], v[188:191], v[96:99]
	v_mfma_f32_16x16x32_bf16 v[84:87], v[212:215], v[92:95], v[84:87]
	v_mfma_f32_16x16x32_bf16 v[88:91], v[220:223], v[92:95], v[88:91]
	v_mfma_f32_16x16x32_bf16 v[92:95], v[206:209], v[180:183], v[120:123]
	v_mfma_f32_16x16x32_bf16 v[104:107], v[220:223], v[184:187], v[104:107]
	v_mfma_f32_16x16x32_bf16 v[100:103], v[212:215], v[192:195], v[100:103]
	v_mfma_f32_16x16x32_bf16 v[96:99], v[220:223], v[192:195], v[96:99]
	v_mfma_f32_16x16x32_bf16 v[92:95], v[212:215], v[184:187], v[92:95]
	s_barrier
	s_setprio 0
	s_add_i32 s59, s72, s62
	s_add_u32 s98, s48, 0x80
	s_addc_u32 s99, s49, 0
	s_add_u32 s100, s50, 0x80
	s_addc_u32 s101, s51, 0
	s_mov_b32 m0, s59
	s_nop 0
	global_load_lds_dwordx4 v164, s[48:49]
	s_add_i32 m0, s59, 0x2000
	s_nop 0
	global_load_lds_dwordx4 v160, s[48:49]
	s_mov_b32 m0, s64
	ds_read_b128 v[120:123], v202 offset:16384
	ds_read_b128 v[128:131], v202 offset:17408
	ds_read_b128 v[136:139], v202 offset:18432
	ds_read_b128 v[148:151], v202 offset:19456
	ds_read_b128 v[180:183], v202 offset:20480
	ds_read_b128 v[184:187], v202 offset:21504
	ds_read_b128 v[188:191], v202 offset:22528
	ds_read_b128 v[192:195], v202 offset:23552
	global_load_lds_dwordx4 v166, s[50:51]
	s_mov_b32 m0, s65
	s_nop 0
	global_load_lds_dwordx4 v162, s[50:51]
	s_add_u32 s78, s48, 0x80000
	s_addc_u32 s79, s49, 0
	s_add_i32 s59, s73, s62
	s_waitcnt vmcnt(6)
	s_waitcnt lgkmcnt(0)
	s_setprio 1
	s_barrier
	v_mfma_f32_16x16x32_bf16 v[60:63], v[64:67], v[120:123], v[60:63]
	s_mov_b32 m0, s59
	v_mfma_f32_16x16x32_bf16 v[48:51], v[72:75], v[120:123], v[48:51]
	global_load_lds_dwordx4 v164, s[78:79]
	v_mfma_f32_16x16x32_bf16 v[44:47], v[64:67], v[136:139], v[44:47]
	s_bitset1_b32 m0, 13
	v_mfma_f32_16x16x32_bf16 v[36:39], v[72:75], v[136:139], v[36:39]
	global_load_lds_dwordx4 v160, s[78:79]
	v_mfma_f32_16x16x32_bf16 v[28:31], v[64:67], v[180:183], v[28:31]
	v_mfma_f32_16x16x32_bf16 v[20:23], v[72:75], v[180:183], v[20:23]
	v_mfma_f32_16x16x32_bf16 v[16:19], v[64:67], v[188:191], v[16:19]
	v_mfma_f32_16x16x32_bf16 v[12:15], v[72:75], v[188:191], v[12:15]
	v_mfma_f32_16x16x32_bf16 v[60:63], v[68:71], v[128:131], v[60:63]
	v_mfma_f32_16x16x32_bf16 v[48:51], v[76:79], v[128:131], v[48:51]
	v_mfma_f32_16x16x32_bf16 v[44:47], v[68:71], v[148:151], v[44:47]
	v_mfma_f32_16x16x32_bf16 v[36:39], v[76:79], v[148:151], v[36:39]
	v_mfma_f32_16x16x32_bf16 v[28:31], v[68:71], v[184:187], v[28:31]
	v_mfma_f32_16x16x32_bf16 v[20:23], v[76:79], v[184:187], v[20:23]
	v_mfma_f32_16x16x32_bf16 v[16:19], v[68:71], v[192:195], v[16:19]
	v_mfma_f32_16x16x32_bf16 v[12:15], v[76:79], v[192:195], v[12:15]
	v_mfma_f32_16x16x32_bf16 v[56:59], v[206:209], v[120:123], v[56:59]
	v_mfma_f32_16x16x32_bf16 v[52:55], v[216:219], v[120:123], v[52:55]
	v_mfma_f32_16x16x32_bf16 v[40:43], v[206:209], v[136:139], v[40:43]
	v_mfma_f32_16x16x32_bf16 v[32:35], v[216:219], v[136:139], v[32:35]
	v_mfma_f32_16x16x32_bf16 v[24:27], v[206:209], v[180:183], v[24:27]
	v_mfma_f32_16x16x32_bf16 v[8:11], v[216:219], v[180:183], v[8:11]
	v_mfma_f32_16x16x32_bf16 v[4:7], v[206:209], v[188:191], v[4:7]
	v_mfma_f32_16x16x32_bf16 v[0:3], v[216:219], v[188:191], v[0:3]
	v_mfma_f32_16x16x32_bf16 v[56:59], v[212:215], v[128:131], v[56:59]
	v_mfma_f32_16x16x32_bf16 v[52:55], v[220:223], v[128:131], v[52:55]
	v_mfma_f32_16x16x32_bf16 v[40:43], v[212:215], v[148:151], v[40:43]
	v_mfma_f32_16x16x32_bf16 v[32:35], v[220:223], v[148:151], v[32:35]
	v_mfma_f32_16x16x32_bf16 v[24:27], v[212:215], v[184:187], v[24:27]
	v_mfma_f32_16x16x32_bf16 v[8:11], v[220:223], v[184:187], v[8:11]
	v_mfma_f32_16x16x32_bf16 v[4:7], v[212:215], v[192:195], v[4:7]
	v_mfma_f32_16x16x32_bf16 v[0:3], v[220:223], v[192:195], v[0:3]
	s_barrier
; #define PG8_STAGE(bufoff, gbase, voff) do { _Pragma("unroll") for (int _i = 0; _i < 2; ++_i) \
;     __builtin_amdgcn_global_load_lds((const unsigned*)((const char*)(gbase) + (voff)[_i]), (LAS unsigned*)(lds + (bufoff) + ldsw + _i * 8192), 16, 0, 0); } while (0)
; #define PG8_LDA(dst, b, h) do { _Pragma("unroll") for (int m = 0; m < 4; ++m) _Pragma("unroll") for (int k = 0; k < 2; ++k) dst[m][k] = *(const LAS bf16x8*)(lds + PG8_SA(b, h) + aoff + m * 2048 + k * 1024); } while (0)
; #define PG8_LDB(dst, b, h) do { _Pragma("unroll") for (int n = 0; n < 2; ++n) _Pragma("unroll") for (int k = 0; k < 2; ++k) dst[n][k] = *(const LAS bf16x8*)(lds + PG8_SB(b, h) + boff + n * 2048 + k * 1024); } while (0)
; #define PG8_MMA(ai, bj, At, Bt) do { __builtin_amdgcn_s_setprio(1); _Pragma("unroll") for (int m = 0; m < 4; ++m) _Pragma("unroll") for (int n = 0; n < 2; ++n) _Pragma("unroll") for (int k = 0; k < 2; ++k) \
;     acc[ai][bj][m][n] = __builtin_amdgcn_mfma_f32_16x16x32_bf16(Bt[n][k], At[m][k], acc[ai][bj][m][n], 0, 0, 0); __builtin_amdgcn_s_setprio(0); } while (0)
; #define PG8_WAIT_V(n) asm volatile("s_waitcnt vmcnt(" #n ")" ::: "memory")
; #define PG8_WAIT_L(n) asm volatile("s_waitcnt lgkmcnt(" #n ")" ::: "memory")
; #define PG8_BAR __builtin_amdgcn_s_barrier()
; #define PG8_SCHED __builtin_amdgcn_sched_barrier(0)
; template <class Epi, class Sched = StaticOrder>
; DI void gemm_phase(LAS unsigned char* lds, const Gemm g, const Sched& S, const Epi& E) {
;     ...
;       PG8_LDB(B0, 1, 0); PG8_SCHED; PG8_LDA(At, 1, 0); PG8_STAGE(PG8_SA(0, 1), a2 + hstep, voffA);
;       PG8_WAIT_L(8); PG8_BAR; PG8_WAIT_L(0); PG8_MMA(0, 0, At, B0); PG8_BAR; PG8_SCHED;
;       PG8_LDB(B1, 1, 1); PG8_STAGE(PG8_SB(1, 0), b3, voffB);
;       PG8_BAR; PG8_WAIT_L(0); PG8_MMA(0, 1, At, B1); PG8_BAR;
;       PG8_LDA(At, 1, 1); PG8_STAGE(PG8_SA(1, 0), a3, voffA);
;       PG8_BAR; PG8_WAIT_L(0); PG8_MMA(1, 0, At, B0); PG8_BAR; PG8_SCHED;
;       PG8_STAGE(PG8_SB(1, 1), b3 + hstep, voffB);
;       PG8_WAIT_V(6); PG8_BAR; PG8_MMA(1, 1, At, B1); PG8_BAR;
;     }
	s_setprio 0
	s_add_i32 s59, 0, 0x18000
	v_add_u32_e32 v76, s59, v198
	ds_read_b128 v[64:67], v76
	ds_read_b128 v[68:71], v76 offset:1024
	ds_read_b128 v[72:75], v76 offset:2048
	ds_read_b128 v[76:79], v76 offset:3072
	s_add_u32 s50, s50, 0x80000
	s_addc_u32 s51, s51, 0
	s_mov_b32 m0, s66
	ds_read_b128 v[120:123], v202 offset:32768
	ds_read_b128 v[128:131], v202 offset:33792
	ds_read_b128 v[180:183], v202 offset:34816
	ds_read_b128 v[184:187], v202 offset:35840
	ds_read_b128 v[188:191], v202 offset:36864
	ds_read_b128 v[192:195], v202 offset:37888
	ds_read_b128 v[206:209], v202 offset:38912
	ds_read_b128 v[212:215], v202 offset:39936
	global_load_lds_dwordx4 v166, s[50:51]
	s_mov_b32 m0, s67
	s_nop 0
	global_load_lds_dwordx4 v162, s[50:51]
	s_add_i32 s50, 0, 0x1c000
	v_add_u32_e32 v244, s50, v198
	ds_read_b128 v[216:219], v244
	ds_read_b128 v[220:223], v244 offset:1024
	ds_read_b128 v[224:227], v244 offset:2048
	ds_read_b128 v[228:231], v244 offset:3072
	s_waitcnt vmcnt(8)
	s_waitcnt lgkmcnt(4)
	s_setprio 1
	s_barrier
	v_mfma_f32_16x16x32_bf16 v[136:139], v[64:67], v[120:123], v[156:159]
	v_mfma_f32_16x16x32_bf16 v[156:159], v[68:71], v[128:131], v[136:139]
	v_mfma_f32_16x16x32_bf16 v[136:139], v[72:75], v[120:123], v[144:147]
	v_mfma_f32_16x16x32_bf16 v[144:147], v[76:79], v[128:131], v[136:139]
	v_mfma_f32_16x16x32_bf16 v[136:139], v[64:67], v[180:183], v[140:143]
	v_mfma_f32_16x16x32_bf16 v[132:135], v[72:75], v[180:183], v[132:135]
	v_mfma_f32_16x16x32_bf16 v[124:127], v[64:67], v[188:191], v[124:127]
	v_mfma_f32_16x16x32_bf16 v[116:119], v[72:75], v[188:191], v[116:119]
	v_mfma_f32_16x16x32_bf16 v[112:115], v[64:67], v[206:209], v[112:115]
	v_mfma_f32_16x16x32_bf16 v[108:111], v[72:75], v[206:209], v[108:111]
	v_mfma_f32_16x16x32_bf16 v[140:143], v[68:71], v[184:187], v[136:139]
	v_mfma_f32_16x16x32_bf16 v[132:135], v[76:79], v[184:187], v[132:135]
	v_mfma_f32_16x16x32_bf16 v[124:127], v[68:71], v[192:195], v[124:127]
	v_mfma_f32_16x16x32_bf16 v[116:119], v[76:79], v[192:195], v[116:119]
	v_mfma_f32_16x16x32_bf16 v[112:115], v[68:71], v[212:215], v[112:115]
	v_mfma_f32_16x16x32_bf16 v[108:111], v[76:79], v[212:215], v[108:111]
	s_waitcnt lgkmcnt(0)
	v_mfma_f32_16x16x32_bf16 v[80:83], v[224:227], v[120:123], v[80:83]
	v_mfma_f32_16x16x32_bf16 v[136:139], v[216:219], v[120:123], v[152:155]
	v_mfma_f32_16x16x32_bf16 v[148:151], v[228:231], v[128:131], v[80:83]
	v_mfma_f32_16x16x32_bf16 v[80:83], v[216:219], v[180:183], v[84:87]
	v_mfma_f32_16x16x32_bf16 v[152:155], v[220:223], v[128:131], v[136:139]
	v_mfma_f32_16x16x32_bf16 v[136:139], v[220:223], v[184:187], v[80:83]
	v_mfma_f32_16x16x32_bf16 v[80:83], v[224:227], v[180:183], v[88:91]
	v_mfma_f32_16x16x32_bf16 v[128:131], v[228:231], v[184:187], v[80:83]
	v_mfma_f32_16x16x32_bf16 v[80:83], v[216:219], v[188:191], v[92:95]
	v_mfma_f32_16x16x32_bf16 v[120:123], v[220:223], v[192:195], v[80:83]
	v_mfma_f32_16x16x32_bf16 v[80:83], v[224:227], v[188:191], v[104:107]
	v_mfma_f32_16x16x32_bf16 v[104:107], v[228:231], v[192:195], v[80:83]
	v_mfma_f32_16x16x32_bf16 v[80:83], v[216:219], v[206:209], v[100:103]
	v_mfma_f32_16x16x32_bf16 v[100:103], v[220:223], v[212:215], v[80:83]
	v_mfma_f32_16x16x32_bf16 v[80:83], v[224:227], v[206:209], v[96:99]
	v_mfma_f32_16x16x32_bf16 v[96:99], v[228:231], v[212:215], v[80:83]
	s_barrier
	s_setprio 0
	s_add_i32 s51, s59, s62
	s_mov_b32 m0, s51
	s_nop 0
	global_load_lds_dwordx4 v164, s[98:99]
	s_add_i32 m0, s51, 0x2000
	s_nop 0
	global_load_lds_dwordx4 v160, s[98:99]
	s_mov_b32 m0, s55
	s_nop 2
	ds_read_b128 v[80:83], v202 offset:49152
	ds_read_b128 v[84:87], v202 offset:50176
	ds_read_b128 v[88:91], v202 offset:51200
	ds_read_b128 v[92:95], v202 offset:52224
	ds_read_b128 v[180:183], v202 offset:53248
	ds_read_b128 v[184:187], v202 offset:54272
	ds_read_b128 v[188:191], v202 offset:55296
	ds_read_b128 v[192:195], v202 offset:56320
	global_load_lds_dwordx4 v166, s[100:101]
	s_mov_b32 m0, s68
	s_nop 0
	global_load_lds_dwordx4 v162, s[100:101]
	s_add_u32 s48, s48, 0x80080
	s_addc_u32 s49, s49, 0
	s_add_i32 s50, s50, s62
	s_add_i32 s58, s58, 2
	s_add_u32 s14, s14, 0x100
	s_addc_u32 s15, s15, 0
	s_add_u32 s52, s52, 0x100
	s_addc_u32 s53, s53, 0
	s_cmp_gt_u32 s58, 29
	s_waitcnt vmcnt(6)
	s_waitcnt lgkmcnt(0)
	s_setprio 1
	s_barrier
	v_mfma_f32_16x16x32_bf16 v[60:63], v[64:67], v[80:83], v[60:63]
	s_mov_b32 m0, s50
	v_mfma_f32_16x16x32_bf16 v[48:51], v[72:75], v[80:83], v[48:51]
	global_load_lds_dwordx4 v164, s[48:49]
	v_mfma_f32_16x16x32_bf16 v[44:47], v[64:67], v[88:91], v[44:47]
	s_bitset1_b32 m0, 13
	v_mfma_f32_16x16x32_bf16 v[36:39], v[72:75], v[88:91], v[36:39]
	global_load_lds_dwordx4 v160, s[48:49]
	v_mfma_f32_16x16x32_bf16 v[28:31], v[64:67], v[180:183], v[28:31]
	v_mfma_f32_16x16x32_bf16 v[20:23], v[72:75], v[180:183], v[20:23]
	v_mfma_f32_16x16x32_bf16 v[16:19], v[64:67], v[188:191], v[16:19]
	v_mfma_f32_16x16x32_bf16 v[12:15], v[72:75], v[188:191], v[12:15]
	v_mfma_f32_16x16x32_bf16 v[60:63], v[68:71], v[84:87], v[60:63]
	v_mfma_f32_16x16x32_bf16 v[48:51], v[76:79], v[84:87], v[48:51]
	v_mfma_f32_16x16x32_bf16 v[44:47], v[68:71], v[92:95], v[44:47]
	v_mfma_f32_16x16x32_bf16 v[36:39], v[76:79], v[92:95], v[36:39]
	v_mfma_f32_16x16x32_bf16 v[28:31], v[68:71], v[184:187], v[28:31]
	v_mfma_f32_16x16x32_bf16 v[20:23], v[76:79], v[184:187], v[20:23]
	v_mfma_f32_16x16x32_bf16 v[16:19], v[68:71], v[192:195], v[16:19]
	v_mfma_f32_16x16x32_bf16 v[12:15], v[76:79], v[192:195], v[12:15]
	v_mfma_f32_16x16x32_bf16 v[56:59], v[216:219], v[80:83], v[56:59]
	v_mfma_f32_16x16x32_bf16 v[52:55], v[224:227], v[80:83], v[52:55]
	v_mfma_f32_16x16x32_bf16 v[40:43], v[216:219], v[88:91], v[40:43]
	v_mfma_f32_16x16x32_bf16 v[32:35], v[224:227], v[88:91], v[32:35]
	v_mfma_f32_16x16x32_bf16 v[24:27], v[216:219], v[180:183], v[24:27]
	v_mfma_f32_16x16x32_bf16 v[8:11], v[224:227], v[180:183], v[8:11]
	v_mfma_f32_16x16x32_bf16 v[4:7], v[216:219], v[188:191], v[4:7]
	v_mfma_f32_16x16x32_bf16 v[0:3], v[224:227], v[188:191], v[0:3]
	v_mfma_f32_16x16x32_bf16 v[56:59], v[220:223], v[84:87], v[56:59]
	v_mfma_f32_16x16x32_bf16 v[52:55], v[228:231], v[84:87], v[52:55]
	v_mfma_f32_16x16x32_bf16 v[40:43], v[220:223], v[92:95], v[40:43]
	v_mfma_f32_16x16x32_bf16 v[32:35], v[228:231], v[92:95], v[32:35]
	v_mfma_f32_16x16x32_bf16 v[24:27], v[220:223], v[184:187], v[24:27]
	v_mfma_f32_16x16x32_bf16 v[8:11], v[228:231], v[184:187], v[8:11]
	v_mfma_f32_16x16x32_bf16 v[4:7], v[220:223], v[192:195], v[4:7]
	v_mfma_f32_16x16x32_bf16 v[0:3], v[228:231], v[192:195], v[0:3]
	s_barrier
; DI float dpp_ror1(float v) { return __int_as_float(__builtin_amdgcn_update_dpp(0, __float_as_int(v), 0x121, 0xf, 0xf, false)); }
; DI float dpp_ror2(float v) { return __int_as_float(__builtin_amdgcn_update_dpp(0, __float_as_int(v), 0x122, 0xf, 0xf, false)); }
;   DI void operator()(const f32x4 (&acc)[2][2][4][2], const Unit& u, int wr, int wc, int fr, int fq) const {
;     const int col = u.pn * 128 + wc * 32 + 8 * fq;
;     float w0[8], w1[8], w2[8], bb[8];
; #pragma unroll
;     for (int e = 0; e < 8; ++e) { w0[e] = cw[col + e]; w1[e] = cw[5632 + col + e]; w2[e] = cw[2 * 5632 + col + e]; bb[e] = cb[col + e]; }
; #pragma unroll
;     for (int ai = 0; ai < 2; ++ai) {
;       const int row0 = u.pm * BM + ai * HALF + wr * 64, span = row0 >> 6;
;       float rsv[4];
; #pragma unroll
;       for (int m = 0; m < 4; ++m) rsv[m] = row_rstd(ssq, row0 + 16 * m + fr, fq);
;       float p1[8], p2[8];
; #pragma unroll
;       for (int e = 0; e < 8; ++e) { p1[e] = 0.f; p2[e] = 0.f; }
; #pragma unroll
;       for (int m = 0; m < 4; ++m) {
;         float g[8], uu[8], a[8];
;         const float rs = rsv[m];
; #pragma unroll
;         for (int e = 0; e < 4; ++e) { g[e] = acc[ai][0][m][0][e] * rs; g[4 + e] = acc[ai][0][m][1][e] * rs; uu[e] = acc[ai][1][m][0][e] * rs; uu[4 + e] = acc[ai][1][m][1][e] * rs; }
; #pragma unroll
;         for (int e = 0; e < 8; ++e) {
;           const float x1 = dpp_ror1(g[e]), x2 = dpp_ror2(g[e]);
;           const float pr1 = (fr == 0) ? p1[e] : x1, pr2 = (fr < 2) ? p2[e] : x2;
;           a[e] = w2[e] * g[e] + w1[e] * pr1 + w0[e] * pr2 + bb[e];
;           p1[e] = x1; p2[e] = x2;
	s_setprio 0
	s_cbranch_scc0 .LBB0_1277
	s_lshl_b32 s39, s12, 8
	s_add_i32 s39, s39, s54
	v_or_b32_e32 v190, s39, v179
	v_ashrrev_i32_e32 v191, 31, v190
	v_lshlrev_b64 v[64:65], 7, v[190:191]
	v_or_b32_e32 v188, 16, v190
	v_lshl_add_u64 v[64:65], v[168:169], 0, v[64:65]
	v_ashrrev_i32_e32 v189, 31, v188
	global_load_dwordx4 v[192:195], v[64:65], off
	global_load_dwordx4 v[206:209], v[64:65], off offset:16
	v_lshlrev_b64 v[64:65], 7, v[188:189]
	v_lshl_add_u64 v[64:65], v[168:169], 0, v[64:65]
	global_load_dwordx4 v[212:215], v[64:65], off
	global_load_dwordx4 v[216:219], v[64:65], off offset:16
	v_or_b32_e32 v186, 32, v190
	v_ashrrev_i32_e32 v187, 31, v186
	v_lshlrev_b64 v[64:65], 7, v[186:187]
	v_or_b32_e32 v184, 48, v190
	v_lshl_add_u64 v[64:65], v[168:169], 0, v[64:65]
	v_ashrrev_i32_e32 v185, 31, v184
	global_load_dwordx4 v[220:223], v[64:65], off
	global_load_dwordx4 v[224:227], v[64:65], off offset:16
	v_lshlrev_b64 v[64:65], 7, v[184:185]
	v_lshl_add_u64 v[64:65], v[168:169], 0, v[64:65]
	global_load_dwordx4 v[228:231], v[64:65], off
	global_load_dwordx4 v[232:235], v[64:65], off offset:16
	v_lshl_or_b32 v180, s13, 7, v200
	v_and_b32_e32 v65, 64, v204
	v_xor_b32_e32 v64, 16, v204
	v_ashrrev_i32_e32 v181, 31, v180
	v_add_u32_e32 v65, 64, v65
	v_xor_b32_e32 v66, 32, v204
	v_lshlrev_b64 v[182:183], 2, v[180:181]
	v_cmp_lt_i32_e32 vcc, v64, v65
	v_lshl_add_u64 v[88:89], s[16:17], 0, v[182:183]
	v_lshl_add_u64 v[72:73], s[18:19], 0, v[182:183]
	v_cndmask_b32_e32 v64, v204, v64, vcc
	v_cmp_lt_i32_e32 vcc, v66, v65
	v_lshl_add_u64 v[74:75], v[88:89], 0, s[30:31]
	v_lshl_add_u64 v[76:77], v[88:89], 0, s[34:35]
	v_cndmask_b32_e32 v65, v204, v66, vcc
	v_add_co_u32_e32 v90, vcc, 0x5000, v88
	v_lshlrev_b32_e32 v187, 2, v64
	s_nop 0
	v_addc_co_u32_e32 v91, vcc, 0, v89, vcc
	v_add_co_u32_e32 v92, vcc, 0xb000, v88
	v_lshlrev_b32_e32 v185, 2, v65
	s_nop 0
	v_addc_co_u32_e32 v93, vcc, 0, v89, vcc
	global_load_dwordx4 v[64:67], v[88:89], off offset:16
	global_load_dwordx4 v[80:83], v[88:89], off
	global_load_dwordx4 v[68:71], v[72:73], off offset:16
	global_load_dwordx4 v[84:87], v[72:73], off
	s_nop 0
	global_load_dwordx4 v[72:75], v[74:75], off offset:16
	s_nop 0
	global_load_dwordx4 v[76:79], v[76:77], off offset:16
	s_nop 0
	global_load_dwordx4 v[88:91], v[90:91], off offset:2048
	s_nop 0
	global_load_dwordx4 v[92:95], v[92:93], off
	v_mov_b32_e32 v211, 0
	v_mov_b32_e32 v205, 0
	s_waitcnt vmcnt(0)
	v_mov_b32_e32 v196, v192
	v_mov_b32_e32 v197, v206
	v_mov_b32_e32 v206, v193
	v_mov_b32_e32 v192, v194
	v_mov_b32_e32 v193, v208
	v_mov_b32_e32 v208, v195
	v_pk_add_f32 v[194:195], v[196:197], v[206:207]
	v_pk_add_f32 v[192:193], v[192:193], v[208:209]
	v_mov_b32_e32 v196, v212
	v_mov_b32_e32 v197, v216
	v_mov_b32_e32 v216, v213
	v_mov_b32_e32 v206, v214
	v_mov_b32_e32 v207, v218
	v_mov_b32_e32 v218, v215
	v_pk_add_f32 v[192:193], v[194:195], v[192:193]
	v_pk_add_f32 v[194:195], v[196:197], v[216:217]
	v_pk_add_f32 v[196:197], v[206:207], v[218:219]
	v_mov_b32_e32 v208, v220
	v_pk_add_f32 v[194:195], v[194:195], v[196:197]
	v_mov_b32_e32 v197, v192
	v_mov_b32_e32 v196, v194
	v_mov_b32_e32 v192, v195
	v_pk_add_f32 v[192:193], v[196:197], v[192:193]
	ds_bpermute_b32 v195, v187, v193
	ds_bpermute_b32 v194, v187, v192
	v_mov_b32_e32 v209, v224
	v_mov_b32_e32 v224, v221
	v_mov_b32_e32 v212, v222
	v_mov_b32_e32 v213, v226
	s_waitcnt lgkmcnt(0)
	v_pk_add_f32 v[192:193], v[192:193], v[194:195]
	ds_bpermute_b32 v195, v185, v193
	ds_bpermute_b32 v194, v185, v192
	v_mov_b32_e32 v226, v223
	v_mov_b32_e32 v196, v228
	v_mov_b32_e32 v197, v232
	v_mov_b32_e32 v232, v229
	s_waitcnt lgkmcnt(0)
	v_pk_add_f32 v[192:193], v[192:193], v[194:195]
	v_mov_b32_e32 v206, v230
	v_pk_fma_f32 v[192:193], v[192:193], s[36:37], v[178:179] op_sel_hi:[1,0,0]
	v_mov_b32_e32 v207, v234
	v_mul_f32_e32 v189, 0x4b800000, v193
	v_cmp_gt_f32_e64 s[12:13], s74, v193
	v_mov_b32_e32 v234, v231
	v_pk_add_f32 v[208:209], v[208:209], v[224:225]
	v_cndmask_b32_e64 v189, v193, v189, s[12:13]
	v_rsq_f32_e32 v189, v189
	v_pk_add_f32 v[212:213], v[212:213], v[226:227]
	v_pk_add_f32 v[196:197], v[196:197], v[232:233]
	v_pk_add_f32 v[194:195], v[206:207], v[234:235]
	v_mul_f32_e32 v191, 0x45800000, v189
	v_cndmask_b32_e64 v220, v189, v191, s[12:13]
	v_pk_add_f32 v[208:209], v[208:209], v[212:213]
	v_pk_add_f32 v[194:195], v[196:197], v[194:195]
	v_pk_mul_f32 v[156:157], v[156:157], v[220:221] op_sel_hi:[1,0]
	v_mov_b32_e32 v216, 0
	v_mov_b32_e32 v218, 0
	v_mov_b32_e32 v196, v194
	v_mov_b32_e32 v197, v208
	v_mov_b32_e32 v208, v195
	v_mov_b32_dpp v216, v156 row_ror:1 row_mask:0xf bank_mask:0xf
	v_mov_b32_dpp v218, v157 row_ror:1 row_mask:0xf bank_mask:0xf
	v_pk_add_f32 v[194:195], v[196:197], v[208:209]
	v_cndmask_b32_e64 v207, v218, 0, s[0:1]
	v_cndmask_b32_e64 v206, v216, 0, s[0:1]
	v_pk_mul_f32 v[158:159], v[158:159], v[220:221] op_sel_hi:[1,0]
	v_mov_b32_e32 v212, 0
	v_mov_b32_e32 v214, 0
	ds_bpermute_b32 v197, v187, v195
	ds_bpermute_b32 v196, v187, v194
	v_mov_b32_e32 v215, 0
	v_mov_b32_e32 v217, 0
	v_pk_mul_f32 v[206:207], v[88:89], v[206:207]
	v_mov_b32_dpp v212, v158 row_ror:1 row_mask:0xf bank_mask:0xf
	v_mov_b32_dpp v214, v159 row_ror:1 row_mask:0xf bank_mask:0xf
	v_mov_b32_dpp v215, v156 row_ror:2 row_mask:0xf bank_mask:0xf
	v_mov_b32_dpp v217, v157 row_ror:2 row_mask:0xf bank_mask:0xf
	v_pk_fma_f32 v[156:157], v[92:93], v[156:157], v[206:207]
	v_mov_b32_e32 v213, 0
	v_cndmask_b32_e64 v207, v214, 0, s[0:1]
	v_cndmask_b32_e64 v206, v212, 0, s[0:1]
	v_cndmask_b32_e64 v209, v217, 0, s[4:5]
	v_cndmask_b32_e64 v208, v215, 0, s[4:5]
	v_mov_b32_dpp v211, v158 row_ror:2 row_mask:0xf bank_mask:0xf
	v_mov_b32_dpp v213, v159 row_ror:2 row_mask:0xf bank_mask:0xf
	v_pk_mul_f32 v[206:207], v[90:91], v[206:207]
	v_pk_fma_f32 v[156:157], v[80:81], v[208:209], v[156:157]
	v_cndmask_b32_e64 v209, v213, 0, s[4:5]
	v_cndmask_b32_e64 v208, v211, 0, s[4:5]
	v_pk_fma_f32 v[158:159], v[94:95], v[158:159], v[206:207]
	v_pk_mul_f32 v[144:145], v[144:145], v[220:221] op_sel_hi:[1,0]
	v_pk_fma_f32 v[158:159], v[82:83], v[208:209], v[158:159]
	v_mov_b32_e32 v207, 0
	v_mov_b32_e32 v209, 0
	v_pk_mul_f32 v[146:147], v[146:147], v[220:221] op_sel_hi:[1,0]
	v_mov_b32_e32 v191, 0
	s_waitcnt lgkmcnt(0)
; DI unsigned pack2(float lo, float hi) { f32x2 v = {lo, hi}; bf16v2 r = __builtin_convertvector(v, bf16v2); return __builtin_bit_cast(unsigned, r); }
; DI float silu_f(float x) { return x * sigmoid_f(x); }
; DI float dpp_ror1(float v) { return __int_as_float(__builtin_amdgcn_update_dpp(0, __float_as_int(v), 0x121, 0xf, 0xf, false)); }
; DI float dpp_ror2(float v) { return __int_as_float(__builtin_amdgcn_update_dpp(0, __float_as_int(v), 0x122, 0xf, 0xf, false)); }
;   DI void operator()(const f32x4 (&acc)[2][2][4][2], const Unit& u, int wr, int wc, int fr, int fq) const {
;     ...
; #pragma unroll
;         for (int e = 0; e < 8; ++e) {
;           const float x1 = dpp_ror1(g[e]), x2 = dpp_ror2(g[e]);
;           const float pr1 = (fr == 0) ? p1[e] : x1, pr2 = (fr < 2) ? p2[e] : x2;
;           a[e] = w2[e] * g[e] + w1[e] * pr1 + w0[e] * pr2 + bb[e];
;           p1[e] = x1; p2[e] = x2;
;         }
;         if (m == 0 && fr < 2) {
;           float* ha = headA + (size_t)(span * 2 + fr) * 5632 + col; float* hu = headU + (size_t)(span * 2 + fr) * 5632 + col;
;           *(f32x4*)ha = (f32x4){a[0], a[1], a[2], a[3]}; *(f32x4*)(ha + 4) = (f32x4){a[4], a[5], a[6], a[7]};
;           *(f32x4*)hu = (f32x4){uu[0], uu[1], uu[2], uu[3]}; *(f32x4*)(hu + 4) = (f32x4){uu[4], uu[5], uu[6], uu[7]};
;         } else {
;           u32x4 w;
;           w.x = pack2(silu_f(a[0]) * uu[0], silu_f(a[1]) * uu[1]);
;           w.y = pack2(silu_f(a[2]) * uu[2], silu_f(a[3]) * uu[3]);
;           w.z = pack2(silu_f(a[4]) * uu[4], silu_f(a[5]) * uu[5]);
;           w.w = pack2(silu_f(a[6]) * uu[6], silu_f(a[7]) * uu[7]);
;           *(u32x4*)(H + (size_t)(row0 + 16 * m + fr) * 5632 + col) = w;
	v_pk_add_f32 v[194:195], v[194:195], v[196:197]
	v_mov_b32_dpp v207, v144 row_ror:1 row_mask:0xf bank_mask:0xf
	v_mov_b32_dpp v209, v145 row_ror:1 row_mask:0xf bank_mask:0xf
	v_mov_b32_dpp v191, v146 row_ror:1 row_mask:0xf bank_mask:0xf
	v_mov_b32_dpp v205, v147 row_ror:1 row_mask:0xf bank_mask:0xf
	ds_bpermute_b32 v197, v185, v195
	ds_bpermute_b32 v196, v185, v194
	v_pk_mul_f32 v[152:153], v[152:153], v[220:221] op_sel_hi:[1,0]
	v_pk_mul_f32 v[148:149], v[148:149], v[220:221] op_sel_hi:[1,0]
	v_pk_mul_f32 v[154:155], v[154:155], v[220:221] op_sel_hi:[1,0]
	v_pk_mul_f32 v[150:151], v[150:151], v[220:221] op_sel_hi:[1,0]
	v_mov_b32_e32 v206, 0
	v_mov_b32_e32 v208, 0
	v_cndmask_b32_e64 v223, v209, 0, s[0:1]
	v_cndmask_b32_e64 v222, v207, 0, s[0:1]
	v_mov_b32_e32 v189, 0
	v_mov_b32_e32 v193, 0
	v_cndmask_b32_e64 v221, v205, 0, s[0:1]
	v_cndmask_b32_e64 v220, v191, 0, s[0:1]
	v_mov_b32_dpp v206, v144 row_ror:2 row_mask:0xf bank_mask:0xf
	v_mov_b32_dpp v208, v145 row_ror:2 row_mask:0xf bank_mask:0xf
	v_pk_mul_f32 v[222:223], v[72:73], v[222:223]
	v_mov_b32_dpp v189, v146 row_ror:2 row_mask:0xf bank_mask:0xf
	v_mov_b32_dpp v193, v147 row_ror:2 row_mask:0xf bank_mask:0xf
	v_pk_mul_f32 v[220:221], v[74:75], v[220:221]
	v_cndmask_b32_e64 v225, v208, 0, s[4:5]
	v_cndmask_b32_e64 v224, v206, 0, s[4:5]
	v_pk_fma_f32 v[144:145], v[76:77], v[144:145], v[222:223]
	v_cndmask_b32_e64 v223, v193, 0, s[4:5]
	v_cndmask_b32_e64 v222, v189, 0, s[4:5]
	v_pk_fma_f32 v[146:147], v[78:79], v[146:147], v[220:221]
	v_pk_fma_f32 v[144:145], v[64:65], v[224:225], v[144:145]
	v_pk_fma_f32 v[146:147], v[66:67], v[222:223], v[146:147]
	v_cmp_gt_f32_e32 vcc, s74, v192
	v_pk_add_f32 v[156:157], v[84:85], v[156:157]
	v_pk_add_f32 v[158:159], v[86:87], v[158:159]
	v_pk_add_f32 v[144:145], v[68:69], v[144:145]
	v_pk_add_f32 v[146:147], v[70:71], v[146:147]
	s_and_saveexec_b64 s[12:13], s[10:11]
	s_xor_b64 s[12:13], exec, s[12:13]
	s_cbranch_execz .LBB0_1280
	v_mul_f32_e32 v219, 0xbfb8aa3b, v156
	v_exp_f32_e32 v219, v219
	v_mul_f32_e32 v220, 0xbfb8aa3b, v157
	v_exp_f32_e32 v220, v220
	v_mul_f32_e32 v222, 0xbfb8aa3b, v159
	v_add_f32_e32 v219, 1.0, v219
	v_exp_f32_e32 v223, v222
	v_add_f32_e32 v221, 1.0, v220
	v_rcp_f32_e32 v220, v219
	v_mul_f32_e32 v219, 0xbfb8aa3b, v158
	v_exp_f32_e32 v219, v219
	v_rcp_f32_e32 v221, v221
	v_add_f32_e32 v219, 1.0, v219
	v_rcp_f32_e32 v222, v219
	v_add_f32_e32 v219, 1.0, v223
	v_rcp_f32_e32 v223, v219
	v_pk_mul_f32 v[156:157], v[156:157], v[220:221]
	s_nop 0
	v_pk_mul_f32 v[152:153], v[152:153], v[156:157]
	v_pk_mul_f32 v[156:157], v[158:159], v[222:223]
	v_cvt_pk_bf16_f32 v152, v152, v153
	v_mul_f32_e32 v153, 0xbfb8aa3b, v144
	v_pk_mul_f32 v[154:155], v[154:155], v[156:157]
	v_exp_f32_e32 v156, v153
	v_mul_f32_e32 v153, 0xbfb8aa3b, v145
	v_exp_f32_e32 v157, v153
	v_cvt_pk_bf16_f32 v153, v154, v155
	v_add_f32_e32 v154, 1.0, v156
	v_mul_f32_e32 v156, 0xbfb8aa3b, v146
	v_add_f32_e32 v155, 1.0, v157
	v_mul_f32_e32 v157, 0xbfb8aa3b, v147
	v_exp_f32_e32 v156, v156
	v_exp_f32_e32 v157, v157
	v_rcp_f32_e32 v154, v154
	v_rcp_f32_e32 v155, v155
	v_add_f32_e32 v156, 1.0, v156
	v_add_f32_e32 v157, 1.0, v157
	v_rcp_f32_e32 v156, v156
	v_rcp_f32_e32 v157, v157
	v_pk_mul_f32 v[144:145], v[144:145], v[154:155]
	s_nop 0
	v_pk_mul_f32 v[144:145], v[148:149], v[144:145]
	s_nop 0
	v_cvt_pk_bf16_f32 v154, v144, v145
	v_pk_mul_f32 v[144:145], v[146:147], v[156:157]
	s_nop 0
	v_pk_mul_f32 v[144:145], v[150:151], v[144:145]
	s_nop 0
	v_cvt_pk_bf16_f32 v155, v144, v145
	v_mov_b64_e32 v[144:145], s[20:21]
	v_mad_i64_i32 v[144:145], s[14:15], v190, s75, v[144:145]
	v_lshl_add_u64 v[144:145], v[180:181], 1, v[144:145]
	global_store_dwordx4 v[144:145], v[152:155], off

; #define PG8_STAGE(bufoff, gbase, voff) do { _Pragma("unroll") for (int _i = 0; _i < 2; ++_i) \
;     __builtin_amdgcn_global_load_lds((const unsigned*)((const char*)(gbase) + (voff)[_i]), (LAS unsigned*)(lds + (bufoff) + ldsw + _i * 8192), 16, 0, 0); } while (0)
; #define PG8_LDA(dst, b, h) do { _Pragma("unroll") for (int m = 0; m < 4; ++m) _Pragma("unroll") for (int k = 0; k < 2; ++k) dst[m][k] = *(const LAS bf16x8*)(lds + PG8_SA(b, h) + aoff + m * 2048 + k * 1024); } while (0)
; #define PG8_LDB(dst, b, h) do { _Pragma("unroll") for (int n = 0; n < 2; ++n) _Pragma("unroll") for (int k = 0; k < 2; ++k) dst[n][k] = *(const LAS bf16x8*)(lds + PG8_SB(b, h) + boff + n * 2048 + k * 1024); } while (0)
; #define PG8_MMA(ai, bj, At, Bt) do { __builtin_amdgcn_s_setprio(1); _Pragma("unroll") for (int m = 0; m < 4; ++m) _Pragma("unroll") for (int n = 0; n < 2; ++n) _Pragma("unroll") for (int k = 0; k < 2; ++k) \
;     acc[ai][bj][m][n] = __builtin_amdgcn_mfma_f32_16x16x32_bf16(Bt[n][k], At[m][k], acc[ai][bj][m][n], 0, 0, 0); __builtin_amdgcn_s_setprio(0); } while (0)
; #define PG8_WAIT_V(n) asm volatile("s_waitcnt vmcnt(" #n ")" ::: "memory")
; #define PG8_WAIT_L(n) asm volatile("s_waitcnt lgkmcnt(" #n ")" ::: "memory")
; #define PG8_BAR __builtin_amdgcn_s_barrier()
; #define PG8_SCHED __builtin_amdgcn_sched_barrier(0)
; template <class Epi, class Sched = StaticOrder>
; DI void gemm_phase(LAS unsigned char* lds, const Gemm g, const Sched& S, const Epi& E) {
;     ...
;     for (int t = 0; t < nt; t += 2) {
;       const bool last = (t == nt - 2);
;       const char* a1 = cA + (size_t)(t + 1) * kstep;
;       const char* a2 = last ? nA : cA + (size_t)(t + 2) * kstep; const char* b2 = last ? nB : cB + (size_t)(t + 2) * kstep;
;       const char* a3 = a2 + kstep; const char* b3 = b2 + kstep;
;       PG8_LDB(B0, 0, 0); PG8_SCHED; PG8_LDA(At, 0, 0); PG8_STAGE(PG8_SA(1, 1), a1 + hstep, voffA);
;       PG8_WAIT_L(8); PG8_BAR; PG8_WAIT_L(0); PG8_MMA(0, 0, At, B0); PG8_BAR; PG8_SCHED;
;       PG8_LDB(B1, 0, 1); PG8_STAGE(PG8_SB(0, 0), b2, voffB);
;       PG8_BAR; PG8_WAIT_L(0); PG8_MMA(0, 1, At, B1); PG8_BAR;
;       PG8_LDA(At, 0, 1); PG8_STAGE(PG8_SA(0, 0), a2, voffA);
;       PG8_BAR; PG8_WAIT_L(0); PG8_MMA(1, 0, At, B0); PG8_BAR; PG8_SCHED;
;       PG8_STAGE(PG8_SB(0, 1), b2 + hstep, voffB);
;       PG8_WAIT_V(6); PG8_BAR; PG8_MMA(1, 1, At, B1); PG8_BAR;
.LBB0_1424:
	ds_read_b128 v[144:147], v159
	ds_read_b128 v[148:151], v159 offset:1024
	ds_read_b128 v[152:155], v159 offset:2048
	ds_read_b128 v[162:165], v159 offset:3072
	s_add_u32 s18, s16, 0xffea0080
	s_addc_u32 s19, s17, -1
	s_cmpk_eq_i32 s47, 0x54
	s_cselect_b32 s21, s3, s19
	s_cselect_b32 s20, s2, s18
	s_cselect_b32 s19, s5, s46
	s_cselect_b32 s18, s4, s45
	ds_read_b128 v[166:169], v160
	ds_read_b128 v[170:173], v160 offset:1024
	ds_read_b128 v[174:177], v160 offset:2048
	ds_read_b128 v[178:181], v160 offset:3072
	ds_read_b128 v[182:185], v160 offset:4096
	ds_read_b128 v[186:189], v160 offset:5120
	ds_read_b128 v[190:193], v160 offset:6144
	ds_read_b128 v[194:197], v160 offset:7168
	ds_read_b128 v[198:201], v161
	ds_read_b128 v[202:205], v161 offset:1024
	ds_read_b128 v[206:209], v161 offset:2048
	ds_read_b128 v[210:213], v161 offset:3072
	s_waitcnt vmcnt(6)
	s_waitcnt lgkmcnt(4)
	s_setprio 1
	s_barrier
	v_mfma_f32_16x16x32_bf16 v[124:127], v[144:147], v[166:169], v[124:127]
	s_add_i32 m0, s30, 0xc000
	v_mfma_f32_16x16x32_bf16 v[120:123], v[152:155], v[166:169], v[120:123]
	global_load_lds_dwordx4 v136, s[16:17]
	v_mfma_f32_16x16x32_bf16 v[116:119], v[144:147], v[174:177], v[116:119]
	s_add_i32 m0, s30, 0xe000
	v_mfma_f32_16x16x32_bf16 v[112:115], v[152:155], v[174:177], v[112:115]
	global_load_lds_dwordx4 v138, s[16:17]
	v_mfma_f32_16x16x32_bf16 v[104:107], v[144:147], v[182:185], v[104:107]
	v_mfma_f32_16x16x32_bf16 v[96:99], v[152:155], v[182:185], v[96:99]
	v_mfma_f32_16x16x32_bf16 v[88:91], v[144:147], v[190:193], v[88:91]
	v_mfma_f32_16x16x32_bf16 v[80:83], v[152:155], v[190:193], v[80:83]
	v_mfma_f32_16x16x32_bf16 v[124:127], v[148:151], v[170:173], v[124:127]
	v_mfma_f32_16x16x32_bf16 v[120:123], v[162:165], v[170:173], v[120:123]
	v_mfma_f32_16x16x32_bf16 v[116:119], v[148:151], v[178:181], v[116:119]
	v_mfma_f32_16x16x32_bf16 v[112:115], v[162:165], v[178:181], v[112:115]
	v_mfma_f32_16x16x32_bf16 v[104:107], v[148:151], v[186:189], v[104:107]
	v_mfma_f32_16x16x32_bf16 v[96:99], v[162:165], v[186:189], v[96:99]
	v_mfma_f32_16x16x32_bf16 v[88:91], v[148:151], v[194:197], v[88:91]
	v_mfma_f32_16x16x32_bf16 v[80:83], v[162:165], v[194:197], v[80:83]
	s_waitcnt lgkmcnt(0)
	v_mfma_f32_16x16x32_bf16 v[108:111], v[198:201], v[166:169], v[108:111]
	v_mfma_f32_16x16x32_bf16 v[100:103], v[206:209], v[166:169], v[100:103]
	v_mfma_f32_16x16x32_bf16 v[92:95], v[198:201], v[174:177], v[92:95]
	v_mfma_f32_16x16x32_bf16 v[84:87], v[206:209], v[174:177], v[84:87]
	v_mfma_f32_16x16x32_bf16 v[76:79], v[198:201], v[182:185], v[76:79]
	v_mfma_f32_16x16x32_bf16 v[72:75], v[206:209], v[182:185], v[72:75]
	v_mfma_f32_16x16x32_bf16 v[68:71], v[198:201], v[190:193], v[68:71]
	v_mfma_f32_16x16x32_bf16 v[64:67], v[206:209], v[190:193], v[64:67]
	v_mfma_f32_16x16x32_bf16 v[108:111], v[202:205], v[170:173], v[108:111]
	v_mfma_f32_16x16x32_bf16 v[100:103], v[210:213], v[170:173], v[100:103]
	v_mfma_f32_16x16x32_bf16 v[92:95], v[202:205], v[178:181], v[92:95]
	v_mfma_f32_16x16x32_bf16 v[84:87], v[210:213], v[178:181], v[84:87]
	v_mfma_f32_16x16x32_bf16 v[76:79], v[202:205], v[186:189], v[76:79]
	v_mfma_f32_16x16x32_bf16 v[72:75], v[210:213], v[186:189], v[72:75]
	v_mfma_f32_16x16x32_bf16 v[68:71], v[202:205], v[194:197], v[68:71]
	v_mfma_f32_16x16x32_bf16 v[64:67], v[210:213], v[194:197], v[64:67]
	s_barrier
	s_setprio 0
	s_add_i32 s48, s39, s28
	s_add_u32 s98, s18, 0x80
	s_addc_u32 s99, s19, 0
	s_add_u32 s100, s20, 0x80
	s_addc_u32 s101, s21, 0
	s_mov_b32 m0, s48
	s_nop 0
	global_load_lds_dwordx4 v132, s[18:19]
	s_add_i32 m0, s48, 0x2000
	s_nop 0
	global_load_lds_dwordx4 v128, s[18:19]
	s_mov_b32 m0, s30
	ds_read_b128 v[166:169], v160 offset:16384
	ds_read_b128 v[170:173], v160 offset:17408
	ds_read_b128 v[174:177], v160 offset:18432
	ds_read_b128 v[178:181], v160 offset:19456
	ds_read_b128 v[182:185], v160 offset:20480
	ds_read_b128 v[186:189], v160 offset:21504
	ds_read_b128 v[190:193], v160 offset:22528
	ds_read_b128 v[194:197], v160 offset:23552
	global_load_lds_dwordx4 v134, s[20:21]
	s_mov_b32 m0, s31
	s_nop 0
	global_load_lds_dwordx4 v130, s[20:21]
	s_add_u32 s48, s18, 0x160000
	s_addc_u32 s49, s19, 0
	s_add_i32 s50, s40, s28
	s_waitcnt vmcnt(6)
	s_waitcnt lgkmcnt(0)
	s_setprio 1
	s_barrier
	v_mfma_f32_16x16x32_bf16 v[60:63], v[144:147], v[166:169], v[60:63]
	s_mov_b32 m0, s50
	v_mfma_f32_16x16x32_bf16 v[56:59], v[152:155], v[166:169], v[56:59]
	global_load_lds_dwordx4 v132, s[48:49]
	v_mfma_f32_16x16x32_bf16 v[52:55], v[144:147], v[174:177], v[52:55]
	s_bitset1_b32 m0, 13
	v_mfma_f32_16x16x32_bf16 v[44:47], v[152:155], v[174:177], v[44:47]
	global_load_lds_dwordx4 v128, s[48:49]
	v_mfma_f32_16x16x32_bf16 v[36:39], v[144:147], v[182:185], v[36:39]
	v_mfma_f32_16x16x32_bf16 v[28:31], v[152:155], v[182:185], v[28:31]
	v_mfma_f32_16x16x32_bf16 v[20:23], v[144:147], v[190:193], v[20:23]
	v_mfma_f32_16x16x32_bf16 v[12:15], v[152:155], v[190:193], v[12:15]
	v_mfma_f32_16x16x32_bf16 v[60:63], v[148:151], v[170:173], v[60:63]
	v_mfma_f32_16x16x32_bf16 v[56:59], v[162:165], v[170:173], v[56:59]
	v_mfma_f32_16x16x32_bf16 v[52:55], v[148:151], v[178:181], v[52:55]
	v_mfma_f32_16x16x32_bf16 v[44:47], v[162:165], v[178:181], v[44:47]
	v_mfma_f32_16x16x32_bf16 v[36:39], v[148:151], v[186:189], v[36:39]
	v_mfma_f32_16x16x32_bf16 v[28:31], v[162:165], v[186:189], v[28:31]
	v_mfma_f32_16x16x32_bf16 v[20:23], v[148:151], v[194:197], v[20:23]
	v_mfma_f32_16x16x32_bf16 v[12:15], v[162:165], v[194:197], v[12:15]
	v_mfma_f32_16x16x32_bf16 v[48:51], v[198:201], v[166:169], v[48:51]
	v_mfma_f32_16x16x32_bf16 v[40:43], v[206:209], v[166:169], v[40:43]
	v_mfma_f32_16x16x32_bf16 v[32:35], v[198:201], v[174:177], v[32:35]
	v_mfma_f32_16x16x32_bf16 v[24:27], v[206:209], v[174:177], v[24:27]
	v_mfma_f32_16x16x32_bf16 v[16:19], v[198:201], v[182:185], v[16:19]
	v_mfma_f32_16x16x32_bf16 v[8:11], v[206:209], v[182:185], v[8:11]
	v_mfma_f32_16x16x32_bf16 v[4:7], v[198:201], v[190:193], v[4:7]
	v_mfma_f32_16x16x32_bf16 v[0:3], v[206:209], v[190:193], v[0:3]
	v_mfma_f32_16x16x32_bf16 v[48:51], v[202:205], v[170:173], v[48:51]
	v_mfma_f32_16x16x32_bf16 v[40:43], v[210:213], v[170:173], v[40:43]
	v_mfma_f32_16x16x32_bf16 v[32:35], v[202:205], v[178:181], v[32:35]
	v_mfma_f32_16x16x32_bf16 v[24:27], v[210:213], v[178:181], v[24:27]
	v_mfma_f32_16x16x32_bf16 v[16:19], v[202:205], v[186:189], v[16:19]
	v_mfma_f32_16x16x32_bf16 v[8:11], v[210:213], v[186:189], v[8:11]
	v_mfma_f32_16x16x32_bf16 v[4:7], v[202:205], v[194:197], v[4:7]
	v_mfma_f32_16x16x32_bf16 v[0:3], v[210:213], v[194:197], v[0:3]
	s_barrier
; #define PG8_STAGE(bufoff, gbase, voff) do { _Pragma("unroll") for (int _i = 0; _i < 2; ++_i) \
;     __builtin_amdgcn_global_load_lds((const unsigned*)((const char*)(gbase) + (voff)[_i]), (LAS unsigned*)(lds + (bufoff) + ldsw + _i * 8192), 16, 0, 0); } while (0)
; #define PG8_LDA(dst, b, h) do { _Pragma("unroll") for (int m = 0; m < 4; ++m) _Pragma("unroll") for (int k = 0; k < 2; ++k) dst[m][k] = *(const LAS bf16x8*)(lds + PG8_SA(b, h) + aoff + m * 2048 + k * 1024); } while (0)
; #define PG8_LDB(dst, b, h) do { _Pragma("unroll") for (int n = 0; n < 2; ++n) _Pragma("unroll") for (int k = 0; k < 2; ++k) dst[n][k] = *(const LAS bf16x8*)(lds + PG8_SB(b, h) + boff + n * 2048 + k * 1024); } while (0)
; #define PG8_MMA(ai, bj, At, Bt) do { __builtin_amdgcn_s_setprio(1); _Pragma("unroll") for (int m = 0; m < 4; ++m) _Pragma("unroll") for (int n = 0; n < 2; ++n) _Pragma("unroll") for (int k = 0; k < 2; ++k) \
;     acc[ai][bj][m][n] = __builtin_amdgcn_mfma_f32_16x16x32_bf16(Bt[n][k], At[m][k], acc[ai][bj][m][n], 0, 0, 0); __builtin_amdgcn_s_setprio(0); } while (0)
; #define PG8_WAIT_V(n) asm volatile("s_waitcnt vmcnt(" #n ")" ::: "memory")
; #define PG8_WAIT_L(n) asm volatile("s_waitcnt lgkmcnt(" #n ")" ::: "memory")
; #define PG8_BAR __builtin_amdgcn_s_barrier()
; #define PG8_SCHED __builtin_amdgcn_sched_barrier(0)
; template <class Epi, class Sched = StaticOrder>
; DI void gemm_phase(LAS unsigned char* lds, const Gemm g, const Sched& S, const Epi& E) {
;     ...
;       PG8_LDB(B0, 1, 0); PG8_SCHED; PG8_LDA(At, 1, 0); PG8_STAGE(PG8_SA(0, 1), a2 + hstep, voffA);
;       PG8_WAIT_L(8); PG8_BAR; PG8_WAIT_L(0); PG8_MMA(0, 0, At, B0); PG8_BAR; PG8_SCHED;
;       PG8_LDB(B1, 1, 1); PG8_STAGE(PG8_SB(1, 0), b3, voffB);
;       PG8_BAR; PG8_WAIT_L(0); PG8_MMA(0, 1, At, B1); PG8_BAR;
;       PG8_LDA(At, 1, 1); PG8_STAGE(PG8_SA(1, 0), a3, voffA);
;       PG8_BAR; PG8_WAIT_L(0); PG8_MMA(1, 0, At, B0); PG8_BAR; PG8_SCHED;
;       PG8_STAGE(PG8_SB(1, 1), b3 + hstep, voffB);
;       PG8_WAIT_V(6); PG8_BAR; PG8_MMA(1, 1, At, B1); PG8_BAR;
;     }
	s_setprio 0
	s_add_i32 s48, 0, 0x18000
	v_add_u32_e32 v162, s48, v157
	ds_read_b128 v[144:147], v162
	ds_read_b128 v[148:151], v162 offset:1024
	ds_read_b128 v[152:155], v162 offset:2048
	ds_read_b128 v[162:165], v162 offset:3072
	s_add_u32 s20, s20, 0x160000
	s_addc_u32 s21, s21, 0
	s_mov_b32 m0, s33
	ds_read_b128 v[166:169], v160 offset:32768
	ds_read_b128 v[170:173], v160 offset:33792
	ds_read_b128 v[174:177], v160 offset:34816
	ds_read_b128 v[178:181], v160 offset:35840
	ds_read_b128 v[182:185], v160 offset:36864
	ds_read_b128 v[186:189], v160 offset:37888
	ds_read_b128 v[190:193], v160 offset:38912
	ds_read_b128 v[194:197], v160 offset:39936
	global_load_lds_dwordx4 v134, s[20:21]
	s_mov_b32 m0, s34
	s_nop 0
	global_load_lds_dwordx4 v130, s[20:21]
	s_add_i32 s20, 0, 0x1c000
	v_add_u32_e32 v210, s20, v157
	ds_read_b128 v[198:201], v210
	ds_read_b128 v[202:205], v210 offset:1024
	ds_read_b128 v[206:209], v210 offset:2048
	ds_read_b128 v[210:213], v210 offset:3072
	s_waitcnt vmcnt(8)
	s_waitcnt lgkmcnt(4)
	s_setprio 1
	s_barrier
	v_mfma_f32_16x16x32_bf16 v[124:127], v[144:147], v[166:169], v[124:127]
	v_mfma_f32_16x16x32_bf16 v[120:123], v[152:155], v[166:169], v[120:123]
	v_mfma_f32_16x16x32_bf16 v[116:119], v[144:147], v[174:177], v[116:119]
	v_mfma_f32_16x16x32_bf16 v[112:115], v[152:155], v[174:177], v[112:115]
	v_mfma_f32_16x16x32_bf16 v[104:107], v[144:147], v[182:185], v[104:107]
	v_mfma_f32_16x16x32_bf16 v[96:99], v[152:155], v[182:185], v[96:99]
	v_mfma_f32_16x16x32_bf16 v[88:91], v[144:147], v[190:193], v[88:91]
	v_mfma_f32_16x16x32_bf16 v[80:83], v[152:155], v[190:193], v[80:83]
	v_mfma_f32_16x16x32_bf16 v[124:127], v[148:151], v[170:173], v[124:127]
	v_mfma_f32_16x16x32_bf16 v[120:123], v[162:165], v[170:173], v[120:123]
	v_mfma_f32_16x16x32_bf16 v[116:119], v[148:151], v[178:181], v[116:119]
	v_mfma_f32_16x16x32_bf16 v[112:115], v[162:165], v[178:181], v[112:115]
	v_mfma_f32_16x16x32_bf16 v[104:107], v[148:151], v[186:189], v[104:107]
	v_mfma_f32_16x16x32_bf16 v[96:99], v[162:165], v[186:189], v[96:99]
	v_mfma_f32_16x16x32_bf16 v[88:91], v[148:151], v[194:197], v[88:91]
	v_mfma_f32_16x16x32_bf16 v[80:83], v[162:165], v[194:197], v[80:83]
	s_waitcnt lgkmcnt(0)
	v_mfma_f32_16x16x32_bf16 v[108:111], v[198:201], v[166:169], v[108:111]
	v_mfma_f32_16x16x32_bf16 v[100:103], v[206:209], v[166:169], v[100:103]
	v_mfma_f32_16x16x32_bf16 v[92:95], v[198:201], v[174:177], v[92:95]
	v_mfma_f32_16x16x32_bf16 v[84:87], v[206:209], v[174:177], v[84:87]
	v_mfma_f32_16x16x32_bf16 v[76:79], v[198:201], v[182:185], v[76:79]
	v_mfma_f32_16x16x32_bf16 v[72:75], v[206:209], v[182:185], v[72:75]
	v_mfma_f32_16x16x32_bf16 v[68:71], v[198:201], v[190:193], v[68:71]
	v_mfma_f32_16x16x32_bf16 v[64:67], v[206:209], v[190:193], v[64:67]
	v_mfma_f32_16x16x32_bf16 v[108:111], v[202:205], v[170:173], v[108:111]
	v_mfma_f32_16x16x32_bf16 v[100:103], v[210:213], v[170:173], v[100:103]
	v_mfma_f32_16x16x32_bf16 v[92:95], v[202:205], v[178:181], v[92:95]
	v_mfma_f32_16x16x32_bf16 v[84:87], v[210:213], v[178:181], v[84:87]
	v_mfma_f32_16x16x32_bf16 v[76:79], v[202:205], v[186:189], v[76:79]
	v_mfma_f32_16x16x32_bf16 v[72:75], v[210:213], v[186:189], v[72:75]
	v_mfma_f32_16x16x32_bf16 v[68:71], v[202:205], v[194:197], v[68:71]
	v_mfma_f32_16x16x32_bf16 v[64:67], v[210:213], v[194:197], v[64:67]
	s_barrier
	s_setprio 0
	s_add_i32 s21, s48, s28
	s_mov_b32 m0, s21
	s_nop 0
	global_load_lds_dwordx4 v132, s[98:99]
	s_add_i32 m0, s21, 0x2000
	s_nop 0
	global_load_lds_dwordx4 v128, s[98:99]
	s_mov_b32 m0, s35
	ds_read_b128 v[166:169], v160 offset:49152
	ds_read_b128 v[170:173], v160 offset:50176
	ds_read_b128 v[174:177], v160 offset:51200
	ds_read_b128 v[178:181], v160 offset:52224
	ds_read_b128 v[182:185], v160 offset:53248
	ds_read_b128 v[186:189], v160 offset:54272
	ds_read_b128 v[190:193], v160 offset:55296
	ds_read_b128 v[194:197], v160 offset:56320
	global_load_lds_dwordx4 v134, s[100:101]
	s_mov_b32 m0, s36
	s_nop 0
	global_load_lds_dwordx4 v130, s[100:101]
	s_add_u32 s18, s18, 0x160080
	s_addc_u32 s19, s19, 0
	s_add_i32 s20, s20, s28
	s_add_i32 s47, s47, 2
	s_add_u32 s16, s16, 0x100
	s_addc_u32 s17, s17, 0
	s_add_u32 s45, s45, 0x100
	s_addc_u32 s46, s46, 0
	s_cmpk_gt_u32 s47, 0x55
	s_waitcnt vmcnt(6)
	s_waitcnt lgkmcnt(0)
	s_setprio 1
	s_barrier
	v_mfma_f32_16x16x32_bf16 v[60:63], v[144:147], v[166:169], v[60:63]
	s_mov_b32 m0, s20
	v_mfma_f32_16x16x32_bf16 v[56:59], v[152:155], v[166:169], v[56:59]
	global_load_lds_dwordx4 v132, s[18:19]
	v_mfma_f32_16x16x32_bf16 v[52:55], v[144:147], v[174:177], v[52:55]
	s_bitset1_b32 m0, 13
	v_mfma_f32_16x16x32_bf16 v[44:47], v[152:155], v[174:177], v[44:47]
	global_load_lds_dwordx4 v128, s[18:19]
	v_mfma_f32_16x16x32_bf16 v[36:39], v[144:147], v[182:185], v[36:39]
	v_mfma_f32_16x16x32_bf16 v[28:31], v[152:155], v[182:185], v[28:31]
	v_mfma_f32_16x16x32_bf16 v[20:23], v[144:147], v[190:193], v[20:23]
	v_mfma_f32_16x16x32_bf16 v[12:15], v[152:155], v[190:193], v[12:15]
	v_mfma_f32_16x16x32_bf16 v[60:63], v[148:151], v[170:173], v[60:63]
	v_mfma_f32_16x16x32_bf16 v[56:59], v[162:165], v[170:173], v[56:59]
	v_mfma_f32_16x16x32_bf16 v[52:55], v[148:151], v[178:181], v[52:55]
	v_mfma_f32_16x16x32_bf16 v[44:47], v[162:165], v[178:181], v[44:47]
	v_mfma_f32_16x16x32_bf16 v[36:39], v[148:151], v[186:189], v[36:39]
	v_mfma_f32_16x16x32_bf16 v[28:31], v[162:165], v[186:189], v[28:31]
	v_mfma_f32_16x16x32_bf16 v[20:23], v[148:151], v[194:197], v[20:23]
	v_mfma_f32_16x16x32_bf16 v[12:15], v[162:165], v[194:197], v[12:15]
	v_mfma_f32_16x16x32_bf16 v[48:51], v[198:201], v[166:169], v[48:51]
	v_mfma_f32_16x16x32_bf16 v[40:43], v[206:209], v[166:169], v[40:43]
	v_mfma_f32_16x16x32_bf16 v[32:35], v[198:201], v[174:177], v[32:35]
	v_mfma_f32_16x16x32_bf16 v[24:27], v[206:209], v[174:177], v[24:27]
	v_mfma_f32_16x16x32_bf16 v[16:19], v[198:201], v[182:185], v[16:19]
	v_mfma_f32_16x16x32_bf16 v[8:11], v[206:209], v[182:185], v[8:11]
	v_mfma_f32_16x16x32_bf16 v[4:7], v[198:201], v[190:193], v[4:7]
	v_mfma_f32_16x16x32_bf16 v[0:3], v[206:209], v[190:193], v[0:3]
	v_mfma_f32_16x16x32_bf16 v[48:51], v[202:205], v[170:173], v[48:51]
	v_mfma_f32_16x16x32_bf16 v[40:43], v[210:213], v[170:173], v[40:43]
	v_mfma_f32_16x16x32_bf16 v[32:35], v[202:205], v[178:181], v[32:35]
	v_mfma_f32_16x16x32_bf16 v[24:27], v[210:213], v[178:181], v[24:27]
	v_mfma_f32_16x16x32_bf16 v[16:19], v[202:205], v[186:189], v[16:19]
	v_mfma_f32_16x16x32_bf16 v[8:11], v[210:213], v[186:189], v[8:11]
	v_mfma_f32_16x16x32_bf16 v[4:7], v[202:205], v[194:197], v[4:7]
	v_mfma_f32_16x16x32_bf16 v[0:3], v[210:213], v[194:197], v[0:3]
	s_barrier
;   DI void operator()(const f32x4 (&acc)[2][2][4][2], const Unit& u, int wr, int wc, int fr, int fq) const {
;     const int row0 = u.pm * BM + wr * 64 + fr, col0 = u.pn * BM + wc * 32 + 8 * fq;
; #pragma unroll
;     for (int ai = 0; ai < 2; ++ai) {
;       f32x4 bv[4][2][2];
; #pragma unroll
;       for (int m = 0; m < 4; ++m)
; #pragma unroll
;         for (int bj = 0; bj < 2; ++bj) {
;           const float* bp = base + (size_t)(row0 + ai * HALF + m * 16) * 2048 + col0 + bj * HALF;
;           bv[m][bj][0] = *(const f32x4*)bp; bv[m][bj][1] = *(const f32x4*)(bp + 4);
;         }
; #pragma unroll
;       for (int m = 0; m < 4; ++m) {
;         const int row = row0 + ai * HALF + m * 16;
;         const size_t off = (size_t)row * 2048 + col0;
;         float ss = 0.f;
; #pragma unroll
;         for (int bj = 0; bj < 2; ++bj) {
;           const f32x4 v0 = acc[ai][bj][m][0] + bv[m][bj][0], v1 = acc[ai][bj][m][1] + bv[m][bj][1];
;           *(f32x4*)(C + off + bj * HALF) = v0; *(f32x4*)(C + off + bj * HALF + 4) = v1;
; template <class Epi, class Sched = StaticOrder>
; DI void gemm_phase(LAS unsigned char* lds, const Gemm g, const Sched& S, const Epi& E) {
;     ...
;     E(acc, cur, wr, wc, fr, fq);
;     if (!has_next) break;
; #pragma unroll
;     for (int a = 0; a < 2; ++a)
; #pragma unroll
;       for (int b = 0; b < 2; ++b)
; #pragma unroll
;         for (int m = 0; m < 4; ++m)
; #pragma unroll
;           for (int n = 0; n < 2; ++n) acc[a][b][m][n] = (f32x4){0.f, 0.f, 0.f, 0.f};
;     cur = nxt; cA = nA; cB = nB; ++ui;
	s_setprio 0
	s_cbranch_scc0 .LBB0_1424
	v_lshl_or_b32 v144, s44, 8, v158
	v_lshl_add_u32 v154, s43, 8, v156
	v_ashrrev_i32_e32 v145, 31, v144
	v_lshlrev_b64 v[144:145], 2, v[144:145]
	v_ashrrev_i32_e32 v155, 31, v154
	v_lshl_add_u64 v[146:147], s[54:55], 0, v[144:145]
	v_lshlrev_b64 v[148:149], 13, v[154:155]
	v_or_b32_e32 v174, 16, v154
	v_lshl_add_u64 v[170:171], v[146:147], 0, v[148:149]
	v_ashrrev_i32_e32 v175, 31, v174
	global_load_dwordx4 v[150:153], v[170:171], off offset:16
	global_load_dwordx4 v[162:165], v[170:171], off
	global_load_dwordx4 v[166:169], v[170:171], off offset:528
	s_nop 0
	global_load_dwordx4 v[170:173], v[170:171], off offset:512
	v_lshlrev_b64 v[222:223], 13, v[174:175]
	v_or_b32_e32 v190, 32, v154
	v_lshl_add_u64 v[186:187], v[146:147], 0, v[222:223]
	v_ashrrev_i32_e32 v191, 31, v190
	global_load_dwordx4 v[174:177], v[186:187], off offset:16
	global_load_dwordx4 v[178:181], v[186:187], off
	global_load_dwordx4 v[182:185], v[186:187], off offset:528
	s_nop 0
	global_load_dwordx4 v[186:189], v[186:187], off offset:512
	v_lshlrev_b64 v[224:225], 13, v[190:191]
	v_or_b32_e32 v154, 48, v154
	v_lshl_add_u64 v[202:203], v[146:147], 0, v[224:225]
	v_ashrrev_i32_e32 v155, 31, v154
	global_load_dwordx4 v[190:193], v[202:203], off offset:16
	global_load_dwordx4 v[194:197], v[202:203], off
	global_load_dwordx4 v[198:201], v[202:203], off offset:528
	s_nop 0
	global_load_dwordx4 v[202:205], v[202:203], off offset:512
	v_lshlrev_b64 v[154:155], 13, v[154:155]
	v_lshl_add_u64 v[218:219], v[146:147], 0, v[154:155]
	global_load_dwordx4 v[206:209], v[218:219], off offset:16
	global_load_dwordx4 v[210:213], v[218:219], off
	global_load_dwordx4 v[214:217], v[218:219], off offset:528
	s_nop 0
	global_load_dwordx4 v[218:221], v[218:219], off offset:512
	s_and_b64 vcc, exec, s[0:1]
	s_mov_b32 s44, s41
	s_mov_b32 s43, s42
	s_mov_b64 s[18:19], s[4:5]
	s_mov_b64 s[16:17], s[2:3]
	s_waitcnt vmcnt(0)
	v_pk_add_f32 v[120:121], v[120:121], v[150:151]
	v_lshl_add_u64 v[150:151], s[54:55], 0, v[148:149]
	v_pk_add_f32 v[126:127], v[126:127], v[164:165]
	v_pk_add_f32 v[124:125], v[124:125], v[162:163]
	v_lshl_add_u64 v[150:151], v[150:151], 0, v[144:145]
	v_pk_add_f32 v[110:111], v[110:111], v[172:173]
	v_pk_add_f32 v[108:109], v[108:109], v[170:171]
	v_pk_add_f32 v[122:123], v[122:123], v[152:153]
	global_store_dwordx4 v[150:151], v[124:127], off
	global_store_dwordx4 v[150:151], v[120:123], off offset:16
	v_pk_add_f32 v[102:103], v[102:103], v[168:169]
	v_pk_add_f32 v[100:101], v[100:101], v[166:167]
	global_store_dwordx4 v[150:151], v[108:111], off offset:512
	global_store_dwordx4 v[150:151], v[100:103], off offset:528
	v_pk_add_f32 v[94:95], v[94:95], v[188:189]
	v_pk_add_f32 v[108:109], v[112:113], v[174:175]
	v_lshl_add_u64 v[112:113], s[54:55], 0, v[222:223]
	v_pk_add_f32 v[102:103], v[118:119], v[180:181]
	v_pk_add_f32 v[100:101], v[116:117], v[178:179]
	v_lshl_add_u64 v[112:113], v[112:113], 0, v[144:145]
	v_pk_add_f32 v[92:93], v[92:93], v[186:187]
	v_pk_add_f32 v[110:111], v[114:115], v[176:177]
	global_store_dwordx4 v[112:113], v[100:103], off
	global_store_dwordx4 v[112:113], v[108:111], off offset:16
	v_pk_add_f32 v[86:87], v[86:87], v[184:185]
	v_pk_add_f32 v[84:85], v[84:85], v[182:183]
	global_store_dwordx4 v[112:113], v[92:95], off offset:512
	global_store_dwordx4 v[112:113], v[84:87], off offset:528
	v_pk_add_f32 v[78:79], v[78:79], v[204:205]
	v_pk_add_f32 v[92:93], v[96:97], v[190:191]
	v_lshl_add_u64 v[96:97], s[54:55], 0, v[224:225]
	v_pk_add_f32 v[86:87], v[106:107], v[196:197]
	v_pk_add_f32 v[84:85], v[104:105], v[194:195]
	v_lshl_add_u64 v[96:97], v[96:97], 0, v[144:145]
	v_pk_add_f32 v[76:77], v[76:77], v[202:203]
	v_pk_add_f32 v[94:95], v[98:99], v[192:193]
	global_store_dwordx4 v[96:97], v[84:87], off
	global_store_dwordx4 v[96:97], v[92:95], off offset:16
	v_pk_add_f32 v[74:75], v[74:75], v[200:201]
	v_pk_add_f32 v[72:73], v[72:73], v[198:199]
	global_store_dwordx4 v[96:97], v[76:79], off offset:512
	global_store_dwordx4 v[96:97], v[72:75], off offset:528
	v_pk_add_f32 v[70:71], v[70:71], v[220:221]
	v_pk_add_f32 v[76:77], v[80:81], v[206:207]
	v_lshl_add_u64 v[80:81], s[54:55], 0, v[154:155]
	v_pk_add_f32 v[74:75], v[90:91], v[212:213]
	v_pk_add_f32 v[72:73], v[88:89], v[210:211]
	v_lshl_add_u64 v[80:81], v[80:81], 0, v[144:145]
	v_pk_add_f32 v[68:69], v[68:69], v[218:219]
	v_pk_add_f32 v[64:65], v[64:65], v[214:215]
	v_lshl_add_u64 v[154:155], v[148:149], 0, s[10:11]
	v_pk_add_f32 v[78:79], v[82:83], v[208:209]
	global_store_dwordx4 v[80:81], v[72:75], off
	global_store_dwordx4 v[80:81], v[76:79], off offset:16
	v_pk_add_f32 v[66:67], v[66:67], v[216:217]
	global_store_dwordx4 v[80:81], v[68:71], off offset:512
	global_store_dwordx4 v[80:81], v[64:67], off offset:528
	v_lshl_add_u64 v[152:153], v[148:149], 0, s[12:13]
	v_lshl_add_u64 v[150:151], v[148:149], 0, s[14:15]
	v_lshl_add_u64 v[64:65], v[146:147], 0, v[154:155]
	global_load_dwordx4 v[108:111], v[64:65], off offset:16
	global_load_dwordx4 v[120:123], v[64:65], off
	global_load_dwordx4 v[92:95], v[64:65], off offset:528
	global_load_dwordx4 v[100:103], v[64:65], off offset:512
	v_lshl_add_u64 v[64:65], v[146:147], 0, v[152:153]
	global_load_dwordx4 v[88:91], v[64:65], off offset:16
	global_load_dwordx4 v[96:99], v[64:65], off
	global_load_dwordx4 v[76:79], v[64:65], off offset:528
	global_load_dwordx4 v[84:87], v[64:65], off offset:512
	v_lshl_add_u64 v[68:69], v[146:147], 0, v[150:151]
	global_load_dwordx4 v[72:75], v[68:69], off offset:16
	global_load_dwordx4 v[80:83], v[68:69], off
	global_load_dwordx4 v[64:67], v[68:69], off offset:528
	s_nop 0
	global_load_dwordx4 v[68:71], v[68:69], off offset:512
	v_lshl_add_u64 v[148:149], v[148:149], 0, s[6:7]
	v_lshl_add_u64 v[112:113], v[146:147], 0, v[148:149]
	global_load_dwordx4 v[116:119], v[112:113], off offset:16
	global_load_dwordx4 v[124:127], v[112:113], off
	global_load_dwordx4 v[104:107], v[112:113], off offset:528
	s_nop 0
	global_load_dwordx4 v[112:115], v[112:113], off offset:512
	s_waitcnt vmcnt(0)
; #define PG8_WAIT_V(n) asm volatile("s_waitcnt vmcnt(" #n ")" ::: "memory")
; #define PG8_BAR __builtin_amdgcn_s_barrier()
;   DI void operator()(const f32x4 (&acc)[2][2][4][2], const Unit& u, int wr, int wc, int fr, int fq) const {
;     ...
;           const float* bp = base + (size_t)(row0 + ai * HALF + m * 16) * 2048 + col0 + bj * HALF;
;           bv[m][bj][0] = *(const f32x4*)bp; bv[m][bj][1] = *(const f32x4*)(bp + 4);
;         }
; #pragma unroll
;       for (int m = 0; m < 4; ++m) {
;         const int row = row0 + ai * HALF + m * 16;
;         const size_t off = (size_t)row * 2048 + col0;
;         float ss = 0.f;
; #pragma unroll
;         for (int bj = 0; bj < 2; ++bj) {
;           const f32x4 v0 = acc[ai][bj][m][0] + bv[m][bj][0], v1 = acc[ai][bj][m][1] + bv[m][bj][1];
;           *(f32x4*)(C + off + bj * HALF) = v0; *(f32x4*)(C + off + bj * HALF + 4) = v1;
; template <class Epi, class Sched = StaticOrder>
; DI void gemm_phase(LAS unsigned char* lds, const Gemm g, const Sched& S, const Epi& E) {
;     ...
;     if (!has_next) break;
; #pragma unroll
;     for (int a = 0; a < 2; ++a)
; #pragma unroll
;       for (int b = 0; b < 2; ++b)
; #pragma unroll
;         for (int m = 0; m < 4; ++m)
; #pragma unroll
;           for (int n = 0; n < 2; ++n) acc[a][b][m][n] = (f32x4){0.f, 0.f, 0.f, 0.f};
;     cur = nxt; cA = nA; cB = nB; ++ui;
;   }
;   PG8_WAIT_V(0);
;   if (wr == 0) PG8_BAR;
;   PG8_BAR;
	v_pk_add_f32 v[56:57], v[56:57], v[108:109]
	v_lshl_add_u64 v[108:109], s[54:55], 0, v[154:155]
	v_pk_add_f32 v[62:63], v[62:63], v[122:123]
	v_pk_add_f32 v[60:61], v[60:61], v[120:121]
	v_lshl_add_u64 v[108:109], v[108:109], 0, v[144:145]
	v_pk_add_f32 v[50:51], v[50:51], v[102:103]
	v_pk_add_f32 v[48:49], v[48:49], v[100:101]
	v_pk_add_f32 v[58:59], v[58:59], v[110:111]
	global_store_dwordx4 v[108:109], v[60:63], off
	global_store_dwordx4 v[108:109], v[56:59], off offset:16
	v_pk_add_f32 v[42:43], v[42:43], v[94:95]
	v_pk_add_f32 v[40:41], v[40:41], v[92:93]
	global_store_dwordx4 v[108:109], v[48:51], off offset:512
	global_store_dwordx4 v[108:109], v[40:43], off offset:528
	v_pk_add_f32 v[34:35], v[34:35], v[86:87]
	v_lshl_add_u64 v[48:49], s[54:55], 0, v[152:153]
	v_pk_add_f32 v[42:43], v[54:55], v[98:99]
	v_pk_add_f32 v[40:41], v[52:53], v[96:97]
	v_lshl_add_u64 v[48:49], v[48:49], 0, v[144:145]
	v_pk_add_f32 v[32:33], v[32:33], v[84:85]
	v_pk_add_f32 v[46:47], v[46:47], v[90:91]
	v_pk_add_f32 v[44:45], v[44:45], v[88:89]
	global_store_dwordx4 v[48:49], v[40:43], off
	global_store_dwordx4 v[48:49], v[44:47], off offset:16
	v_pk_add_f32 v[26:27], v[26:27], v[78:79]
	v_pk_add_f32 v[24:25], v[24:25], v[76:77]
	global_store_dwordx4 v[48:49], v[32:35], off offset:512
	global_store_dwordx4 v[48:49], v[24:27], off offset:528
	v_pk_add_f32 v[18:19], v[18:19], v[70:71]
	v_lshl_add_u64 v[32:33], s[54:55], 0, v[150:151]
	v_pk_add_f32 v[26:27], v[38:39], v[82:83]
	v_pk_add_f32 v[24:25], v[36:37], v[80:81]
	v_lshl_add_u64 v[32:33], v[32:33], 0, v[144:145]
	v_pk_add_f32 v[16:17], v[16:17], v[68:69]
	v_pk_add_f32 v[30:31], v[30:31], v[74:75]
	v_pk_add_f32 v[28:29], v[28:29], v[72:73]
	global_store_dwordx4 v[32:33], v[24:27], off
	global_store_dwordx4 v[32:33], v[28:31], off offset:16
	v_pk_add_f32 v[10:11], v[10:11], v[66:67]
	v_pk_add_f32 v[8:9], v[8:9], v[64:65]
	global_store_dwordx4 v[32:33], v[16:19], off offset:512
	global_store_dwordx4 v[32:33], v[8:11], off offset:528
	v_pk_add_f32 v[6:7], v[6:7], v[114:115]
	v_lshl_add_u64 v[16:17], s[54:55], 0, v[148:149]
	v_pk_add_f32 v[10:11], v[22:23], v[126:127]
	v_pk_add_f32 v[8:9], v[20:21], v[124:125]
	v_lshl_add_u64 v[16:17], v[16:17], 0, v[144:145]
	v_pk_add_f32 v[4:5], v[4:5], v[112:113]
	v_pk_add_f32 v[14:15], v[14:15], v[118:119]
	v_pk_add_f32 v[12:13], v[12:13], v[116:117]
	global_store_dwordx4 v[16:17], v[8:11], off
	global_store_dwordx4 v[16:17], v[12:15], off offset:16
	v_pk_add_f32 v[2:3], v[2:3], v[106:107]
	v_pk_add_f32 v[0:1], v[0:1], v[104:105]
	global_store_dwordx4 v[16:17], v[4:7], off offset:512
	global_store_dwordx4 v[16:17], v[0:3], off offset:528
	s_cbranch_vccz .LBB0_1417
	s_waitcnt vmcnt(0)
	s_cmpk_gt_u32 s23, 0xff
	s_cbranch_scc1 .LBB0_1428
	s_barrier
